# one static s_setprio 1 for waves 0-3 at kernel entry, all per-cluster s_setprio flips deleted (timing-only, bit-identical)
# speedup vs baseline: 1.0045x; 1.0045x over previous
; #define LAS __attribute__((address_space(3)))
; __device__ __forceinline__ unsigned xb_add(unsigned* p, unsigned v) { return __hip_atomic_fetch_add(p, v, __ATOMIC_RELAXED, __HIP_MEMORY_SCOPE_AGENT); }
; __device__ __forceinline__ unsigned xb_xcc_id() { return (unsigned)__builtin_amdgcn_s_getreg((3 << 11) | 20) & 0xFu; }
; __device__ __forceinline__ XcdBarrier xcd_barrier_post(unsigned* bar, volatile LAS unsigned* st) {
;     XcdBarrier b; b.bar = bar; b.x = xb_xcc_id(); b.st = st;
;     if (threadIdx.x == 0) (void)xb_add(&bar[XB_XCNT(b.x)], 1u);
;     return b;
; __global__ void __launch_bounds__(NWAVES * 64, 2) fwd_megakernel(Args args) {
;     ...
;     F.lds = (LAS unsigned char*)lds_raw; F.tid = threadIdx.x; F.lane = F.tid & 63; F.wave = __builtin_amdgcn_readfirstlane(F.tid >> 6); F.G = gridDim.x;
;     const __attribute__((address_space(4))) Args* KA = (const __attribute__((address_space(4))) Args*)__builtin_amdgcn_kernarg_segment_ptr();
;     F.a = KA; F.out = KA->out;
;     unsigned char* ws = KA->ws;
;     F.Z = (bf16*)(ws + WS_Z); F.MIX = (bf16*)(ws + WS_MIX); F.rope = (const f32x2*)(ws + WS_ROPE);
;     bf16* XG = (bf16*)(ws + WS_XB); bf16* ACT = (bf16*)(ws + WS_ACT); bf16* PRJ = (bf16*)(ws + WS_PRJ); float* SS = (float*)(ws + WS_SS);
;     const int lo = KA->ph_lo, hi = KA->ph_hi;
;     const bool spread = (F.G == 256);
;     ...
;     if (F.tid < 64) ((LAS unsigned*)(F.lds + OFF_MISC))[F.tid] = 0u;
;     __syncthreads();
;     const XcdBarrier bar = xcd_barrier_post((unsigned*)(ws + WS_CTL), (volatile LAS unsigned*)(F.lds + OFF_MISC));
_Z14fwd_megakernel4Args:
	s_load_dwordx8 s[24:31], s[0:1], 0xe8
	v_readfirstlane_b32 s97, v0
	s_nop 3
	s_and_b32 s97, s97, 0x3ff
	s_lshr_b32 s97, s97, 6
	s_cmp_lt_u32 s97, 4
	s_cbranch_scc0 .Lprio_done
	s_setprio 1
.Lprio_done:
	s_add_u32 s8, s0, 0x100
	v_and_b32_e32 v192, 0x3ff, v0
	s_addc_u32 s9, s1, 0
	v_readfirstlane_b32 s14, v192
	v_cmp_gt_u32_e32 vcc, 64, v192
	s_and_saveexec_b64 s[4:5], vcc
	v_lshl_add_u32 v1, v192, 2, 0
	v_add_u32_e32 v1, 0x25f00, v1
	v_mov_b32_e32 v2, 0
	ds_write_b32 v1, v2
	s_or_b64 exec, exec, s[4:5]
	s_load_dword s3, s[0:1], 0x108
	s_waitcnt lgkmcnt(0)
	s_add_u32 s4, s26, 0xd490800
	s_addc_u32 s5, s27, 0
	s_barrier
	v_writelane_b32 v254, s3, 0
	v_writelane_b32 v254, s4, 1
	s_getreg_b32 s3, hwreg(HW_REG_XCC_ID, 0, 4)
	s_and_b32 s3, s3, 15
	v_writelane_b32 v254, s5, 2
	v_writelane_b32 v254, s3, 3
	v_cmp_eq_u32_e64 s[4:5], 0, v192
	s_mov_b64 s[6:7], exec
	s_nop 0
	v_writelane_b32 v254, s4, 4
	s_nop 1
	v_writelane_b32 v254, s5, 5
	s_and_b64 s[4:5], s[6:7], s[4:5]
	s_mov_b64 exec, s[4:5]
	s_cbranch_execz .LBB0_5
	s_mov_b64 s[10:11], exec
	v_mbcnt_lo_u32_b32 v1, s10, 0
	v_mbcnt_hi_u32_b32 v1, s11, v1
	v_cmp_eq_u32_e32 vcc, 0, v1
	s_and_b64 s[4:5], exec, vcc
	s_mov_b64 exec, s[4:5]
	s_cbranch_execz .LBB0_5
	v_readlane_b32 s3, v254, 3
	s_bcnt1_i32_b64 s4, s[10:11]
	s_lshl_b32 s3, s3, 8
	v_mov_b32_e32 v2, s4
	v_readlane_b32 s4, v254, 1
	v_mov_b32_e32 v1, s3
	v_readlane_b32 s5, v254, 2
	s_nop 4
	global_atomic_add v1, v2, s[4:5] offset:1024

; #define PG8_STAGE(bufoff, gbase, voff) do { _Pragma("unroll") for (int _i = 0; _i < 2; ++_i) \
;         __builtin_amdgcn_global_load_lds((const unsigned*)((const char*)(gbase) + (voff)[_i]), (PG8_LAS unsigned*)(lds + (bufoff) + ldsw + _i * 8192), 16, 0, 0); } while (0)
; #define PG8_LDA(dst, b, h) do { _Pragma("unroll") for (int m = 0; m < 4; ++m) _Pragma("unroll") for (int k = 0; k < 2; ++k) dst[m][k] = *(const PG8_LAS bf16x8*)(lds + PG8_SA(b, h) + aoff + m * 2048 + k * 1024); } while (0)
; #define PG8_LDB(dst, b, h) do { _Pragma("unroll") for (int n = 0; n < 2; ++n) _Pragma("unroll") for (int k = 0; k < 2; ++k) dst[n][k] = *(const PG8_LAS bf16x8*)(lds + PG8_SB(b, h) + boff + n * 2048 + k * 1024); } while (0)
; #define PG8_MMA(ai, bj, At, Bt) do { __builtin_amdgcn_s_setprio(1); _Pragma("unroll") for (int m = 0; m < 4; ++m) _Pragma("unroll") for (int n = 0; n < 2; ++n) _Pragma("unroll") for (int k = 0; k < 2; ++k) \
;         acc[ai][bj][m][n] = __builtin_amdgcn_mfma_f32_16x16x32_bf16(Bt[n][k], At[m][k], acc[ai][bj][m][n], 0, 0, 0); __builtin_amdgcn_s_setprio(0); } while (0)
; #define PG8_WAIT_V(n) asm volatile("s_waitcnt vmcnt(" #n ")" ::: "memory")
; #define PG8_WAIT_L(n) asm volatile("s_waitcnt lgkmcnt(" #n ")" ::: "memory")
; #define PG8_BAR __builtin_amdgcn_s_barrier()
; #define PG8_SCHED __builtin_amdgcn_sched_barrier(0)
; template <class Epi, class Sched, bool ALIGN_EPI = false, bool SP2 = false>
; __device__ __forceinline__ void gemm_phase(PG8_LAS unsigned char* lds, const Gemm g, const Sched& S, const Epi& E) {
;     ...
;             PG8_LDB(B0, 0, 0); PG8_LDB(B1, 0, 1); PG8_SCHED; PG8_LDA(At, 0, 0); PG8_STAGE(PG8_SA(1, 1), a1 + hstep, voffA);
;             PG8_WAIT_V(8); PG8_WAIT_L(0); PG8_BAR; PG8_MMA(0, 0, At, B0); PG8_MMA(0, 1, At, B1); PG8_BAR; PG8_SCHED;
;             PG8_LDA(At, 0, 1); PG8_STAGE(PG8_SB(0, 0), b2, voffB); PG8_STAGE(PG8_SB(0, 1), b2 + hstep, voffB); PG8_STAGE(PG8_SA(0, 0), a2, voffA);
;             PG8_WAIT_V(8); PG8_WAIT_L(0); PG8_BAR; PG8_MMA(1, 0, At, B0); PG8_MMA(1, 1, At, B1); PG8_BAR; PG8_SCHED;
;             PG8_LDB(B0, 1, 0); PG8_LDB(B1, 1, 1); PG8_SCHED; PG8_LDA(At, 1, 0); PG8_STAGE(PG8_SA(0, 1), a2 + hstep, voffA);
.LBB0_264:
	ds_read_b128 v[148:151], v168
	ds_read_b128 v[152:155], v168 offset:1024
	ds_read_b128 v[156:159], v168 offset:2048
	ds_read_b128 v[160:163], v168 offset:3072
	ds_read_b128 v[174:177], v169
	ds_read_b128 v[178:181], v169 offset:1024
	ds_read_b128 v[182:185], v169 offset:2048
	ds_read_b128 v[186:189], v169 offset:3072
	s_add_i32 s71, s42, 2
	s_add_u32 s72, s40, 0x80
	s_addc_u32 s43, s41, 0
	s_cmp_eq_u32 s63, s42
	s_cselect_b32 s42, s8, s72
	s_cselect_b32 s43, s9, s43
	s_cselect_b32 s73, s37, s38
	s_cselect_b32 s72, s36, s33
	v_lshl_add_u64 v[164:165], s[40:41], 0, v[140:141]
	s_add_i32 m0, s56, 0xc000
	ds_read_b128 v[194:197], v170
	ds_read_b128 v[198:201], v170 offset:1024
	ds_read_b128 v[202:205], v170 offset:2048
	ds_read_b128 v[206:209], v170 offset:3072
	ds_read_b128 v[210:213], v170 offset:4096
	ds_read_b128 v[214:217], v170 offset:5120
	ds_read_b128 v[218:221], v170 offset:6144
	ds_read_b128 v[222:225], v170 offset:7168
	global_load_lds_dwordx4 v[164:165], off
	v_lshl_add_u64 v[164:165], s[40:41], 0, v[142:143]
	s_add_i32 m0, s56, 0xe000
	s_nop 0
	global_load_lds_dwordx4 v[164:165], off
	s_waitcnt vmcnt(8)
	s_waitcnt lgkmcnt(0)
	s_barrier
	s_waitcnt lgkmcnt(0)
	v_mfma_f32_16x16x32_bf16 v[120:123], v[148:151], v[194:197], v[120:123]
	v_mfma_f32_16x16x32_bf16 v[116:119], v[156:159], v[194:197], v[116:119]
	v_mfma_f32_16x16x32_bf16 v[108:111], v[148:151], v[202:205], v[108:111]
	v_mfma_f32_16x16x32_bf16 v[100:103], v[156:159], v[202:205], v[100:103]
	v_mfma_f32_16x16x32_bf16 v[92:95], v[148:151], v[210:213], v[92:95]
	v_mfma_f32_16x16x32_bf16 v[84:87], v[156:159], v[210:213], v[84:87]
	v_mfma_f32_16x16x32_bf16 v[76:79], v[148:151], v[218:221], v[76:79]
	v_mfma_f32_16x16x32_bf16 v[68:71], v[156:159], v[218:221], v[68:71]
	v_mfma_f32_16x16x32_bf16 v[120:123], v[152:155], v[198:201], v[120:123]
	v_mfma_f32_16x16x32_bf16 v[116:119], v[160:163], v[198:201], v[116:119]
	v_mfma_f32_16x16x32_bf16 v[108:111], v[152:155], v[206:209], v[108:111]
	v_mfma_f32_16x16x32_bf16 v[100:103], v[160:163], v[206:209], v[100:103]
	v_mfma_f32_16x16x32_bf16 v[92:95], v[152:155], v[214:217], v[92:95]
	v_mfma_f32_16x16x32_bf16 v[84:87], v[160:163], v[214:217], v[84:87]
	v_mfma_f32_16x16x32_bf16 v[76:79], v[152:155], v[222:225], v[76:79]
	v_mfma_f32_16x16x32_bf16 v[68:71], v[160:163], v[222:225], v[68:71]
	v_mfma_f32_16x16x32_bf16 v[124:127], v[174:177], v[194:197], v[124:127]
	v_mfma_f32_16x16x32_bf16 v[112:115], v[182:185], v[194:197], v[112:115]
	v_mfma_f32_16x16x32_bf16 v[104:107], v[174:177], v[202:205], v[104:107]
	v_mfma_f32_16x16x32_bf16 v[96:99], v[182:185], v[202:205], v[96:99]
	v_mfma_f32_16x16x32_bf16 v[88:91], v[174:177], v[210:213], v[88:91]
	v_mfma_f32_16x16x32_bf16 v[80:83], v[182:185], v[210:213], v[80:83]
	v_mfma_f32_16x16x32_bf16 v[72:75], v[174:177], v[218:221], v[72:75]
	v_mfma_f32_16x16x32_bf16 v[64:67], v[182:185], v[218:221], v[64:67]
	v_mfma_f32_16x16x32_bf16 v[124:127], v[178:181], v[198:201], v[124:127]
	v_mfma_f32_16x16x32_bf16 v[112:115], v[186:189], v[198:201], v[112:115]
	v_mfma_f32_16x16x32_bf16 v[104:107], v[178:181], v[206:209], v[104:107]
	v_mfma_f32_16x16x32_bf16 v[96:99], v[186:189], v[206:209], v[96:99]
	v_mfma_f32_16x16x32_bf16 v[88:91], v[178:181], v[214:217], v[88:91]
	v_mfma_f32_16x16x32_bf16 v[80:83], v[186:189], v[214:217], v[80:83]
	v_mfma_f32_16x16x32_bf16 v[72:75], v[178:181], v[222:225], v[72:75]
	v_mfma_f32_16x16x32_bf16 v[64:67], v[186:189], v[222:225], v[64:67]
	s_barrier
	s_add_i32 s74, s66, s3
	v_lshl_add_u64 v[164:165], s[72:73], 0, v[134:135]
	s_mov_b32 m0, s74
	ds_read_b128 v[194:197], v170 offset:16384
	ds_read_b128 v[198:201], v170 offset:17408
	ds_read_b128 v[202:205], v170 offset:18432
	ds_read_b128 v[206:209], v170 offset:19456
	ds_read_b128 v[210:213], v170 offset:20480
	ds_read_b128 v[214:217], v170 offset:21504
	ds_read_b128 v[218:221], v170 offset:22528
	ds_read_b128 v[222:225], v170 offset:23552
	global_load_lds_dwordx4 v[164:165], off
	s_add_i32 m0, s74, 0x2000
	v_lshl_add_u64 v[190:191], s[72:73], 0, v[130:131]
	s_add_u32 s72, s72, s12
	s_addc_u32 s73, s73, s13
	s_add_i32 s74, s67, s3
	global_load_lds_dwordx4 v[190:191], off
	v_lshl_add_u64 v[226:227], s[72:73], 0, v[134:135]
	s_mov_b32 m0, s74
	v_lshl_add_u64 v[228:229], s[72:73], 0, v[130:131]
	global_load_lds_dwordx4 v[226:227], off
	s_add_i32 m0, s74, 0x2000
	v_lshl_add_u64 v[230:231], s[42:43], 0, v[136:137]
	global_load_lds_dwordx4 v[228:229], off
	s_mov_b32 m0, s56
	v_lshl_add_u64 v[232:233], s[42:43], 0, v[132:133]
	global_load_lds_dwordx4 v[230:231], off
	s_mov_b32 m0, s57
	s_nop 0
	global_load_lds_dwordx4 v[232:233], off
	s_cmp_lg_u32 s71, 2
	s_cbranch_scc1 .Lss_p1_skip
	s_lshl_b32 s84, s4, 14
	s_mov_b32 s85, 0
	s_add_i32 m0, s56, 0x20000
	v_lshl_add_u64 v[238:239], v[236:237], 0, s[84:85]
	s_add_u32 s84, s84, 0x2000
	global_load_lds_dwordx4 v[238:239], off
	s_add_i32 m0, s56, 0x22000
	v_lshl_add_u64 v[238:239], v[236:237], 0, s[84:85]
	global_load_lds_dwordx4 v[238:239], off
; #define PG8_STAGE(bufoff, gbase, voff) do { _Pragma("unroll") for (int _i = 0; _i < 2; ++_i) \
;         __builtin_amdgcn_global_load_lds((const unsigned*)((const char*)(gbase) + (voff)[_i]), (PG8_LAS unsigned*)(lds + (bufoff) + ldsw + _i * 8192), 16, 0, 0); } while (0)
; #define PG8_LDA(dst, b, h) do { _Pragma("unroll") for (int m = 0; m < 4; ++m) _Pragma("unroll") for (int k = 0; k < 2; ++k) dst[m][k] = *(const PG8_LAS bf16x8*)(lds + PG8_SA(b, h) + aoff + m * 2048 + k * 1024); } while (0)
; #define PG8_LDB(dst, b, h) do { _Pragma("unroll") for (int n = 0; n < 2; ++n) _Pragma("unroll") for (int k = 0; k < 2; ++k) dst[n][k] = *(const PG8_LAS bf16x8*)(lds + PG8_SB(b, h) + boff + n * 2048 + k * 1024); } while (0)
; #define PG8_MMA(ai, bj, At, Bt) do { __builtin_amdgcn_s_setprio(1); _Pragma("unroll") for (int m = 0; m < 4; ++m) _Pragma("unroll") for (int n = 0; n < 2; ++n) _Pragma("unroll") for (int k = 0; k < 2; ++k) \
;         acc[ai][bj][m][n] = __builtin_amdgcn_mfma_f32_16x16x32_bf16(Bt[n][k], At[m][k], acc[ai][bj][m][n], 0, 0, 0); __builtin_amdgcn_s_setprio(0); } while (0)
; #define PG8_WAIT_V(n) asm volatile("s_waitcnt vmcnt(" #n ")" ::: "memory")
; #define PG8_WAIT_L(n) asm volatile("s_waitcnt lgkmcnt(" #n ")" ::: "memory")
; #define PG8_BAR __builtin_amdgcn_s_barrier()
; #define PG8_SCHED __builtin_amdgcn_sched_barrier(0)
; template <class Epi, class Sched, bool ALIGN_EPI = false, bool SP2 = false>
; __device__ __forceinline__ void gemm_phase(PG8_LAS unsigned char* lds, const Gemm g, const Sched& S, const Epi& E) {
;     ...
;             PG8_WAIT_V(8); PG8_WAIT_L(0); PG8_BAR; PG8_MMA(1, 0, At, B0); PG8_MMA(1, 1, At, B1); PG8_BAR; PG8_SCHED;
;             PG8_LDB(B0, 1, 0); PG8_LDB(B1, 1, 1); PG8_SCHED; PG8_LDA(At, 1, 0); PG8_STAGE(PG8_SA(0, 1), a2 + hstep, voffA);
;             PG8_WAIT_V(8); PG8_WAIT_L(0); PG8_BAR; PG8_MMA(0, 0, At, B0); PG8_MMA(0, 1, At, B1); PG8_BAR; PG8_SCHED;
.Lss_p1_skip:
	s_waitcnt vmcnt(8)
	s_waitcnt lgkmcnt(0)
	s_barrier
	s_waitcnt lgkmcnt(0)
	v_mfma_f32_16x16x32_bf16 v[60:63], v[148:151], v[194:197], v[60:63]
	v_mfma_f32_16x16x32_bf16 v[52:55], v[156:159], v[194:197], v[52:55]
	v_mfma_f32_16x16x32_bf16 v[44:47], v[148:151], v[202:205], v[44:47]
	v_mfma_f32_16x16x32_bf16 v[36:39], v[156:159], v[202:205], v[36:39]
	v_mfma_f32_16x16x32_bf16 v[28:31], v[148:151], v[210:213], v[28:31]
	v_mfma_f32_16x16x32_bf16 v[20:23], v[156:159], v[210:213], v[20:23]
	v_mfma_f32_16x16x32_bf16 v[12:15], v[148:151], v[218:221], v[12:15]
	v_mfma_f32_16x16x32_bf16 v[4:7], v[156:159], v[218:221], v[4:7]
	v_mfma_f32_16x16x32_bf16 v[60:63], v[152:155], v[198:201], v[60:63]
	v_mfma_f32_16x16x32_bf16 v[52:55], v[160:163], v[198:201], v[52:55]
	v_mfma_f32_16x16x32_bf16 v[44:47], v[152:155], v[206:209], v[44:47]
	v_mfma_f32_16x16x32_bf16 v[36:39], v[160:163], v[206:209], v[36:39]
	v_mfma_f32_16x16x32_bf16 v[28:31], v[152:155], v[214:217], v[28:31]
	v_mfma_f32_16x16x32_bf16 v[20:23], v[160:163], v[214:217], v[20:23]
	v_mfma_f32_16x16x32_bf16 v[12:15], v[152:155], v[222:225], v[12:15]
	v_mfma_f32_16x16x32_bf16 v[4:7], v[160:163], v[222:225], v[4:7]
	v_mfma_f32_16x16x32_bf16 v[56:59], v[174:177], v[194:197], v[56:59]
	v_mfma_f32_16x16x32_bf16 v[48:51], v[182:185], v[194:197], v[48:51]
	v_mfma_f32_16x16x32_bf16 v[40:43], v[174:177], v[202:205], v[40:43]
	v_mfma_f32_16x16x32_bf16 v[32:35], v[182:185], v[202:205], v[32:35]
	v_mfma_f32_16x16x32_bf16 v[24:27], v[174:177], v[210:213], v[24:27]
	v_mfma_f32_16x16x32_bf16 v[16:19], v[182:185], v[210:213], v[16:19]
	v_mfma_f32_16x16x32_bf16 v[8:11], v[174:177], v[218:221], v[8:11]
	v_mfma_f32_16x16x32_bf16 v[0:3], v[182:185], v[218:221], v[0:3]
	v_mfma_f32_16x16x32_bf16 v[56:59], v[178:181], v[198:201], v[56:59]
	v_mfma_f32_16x16x32_bf16 v[48:51], v[186:189], v[198:201], v[48:51]
	v_mfma_f32_16x16x32_bf16 v[40:43], v[178:181], v[206:209], v[40:43]
	v_mfma_f32_16x16x32_bf16 v[32:35], v[186:189], v[206:209], v[32:35]
	v_mfma_f32_16x16x32_bf16 v[24:27], v[178:181], v[214:217], v[24:27]
	v_mfma_f32_16x16x32_bf16 v[16:19], v[186:189], v[214:217], v[16:19]
	v_mfma_f32_16x16x32_bf16 v[8:11], v[178:181], v[222:225], v[8:11]
	v_mfma_f32_16x16x32_bf16 v[0:3], v[186:189], v[222:225], v[0:3]
	s_barrier
	s_add_i32 s72, 0, 0x18000
	v_add_u32_e32 v128, s72, v166
	s_add_i32 s73, 0, 0x1c000
	ds_read_b128 v[148:151], v128
	ds_read_b128 v[152:155], v128 offset:1024
	ds_read_b128 v[156:159], v128 offset:2048
	ds_read_b128 v[160:163], v128 offset:3072
	v_add_u32_e32 v128, s73, v166
	ds_read_b128 v[174:177], v128
	ds_read_b128 v[178:181], v128 offset:1024
	ds_read_b128 v[182:185], v128 offset:2048
	ds_read_b128 v[186:189], v128 offset:3072
	s_add_u32 s42, s42, s12
	s_addc_u32 s43, s43, s13
	s_mov_b32 m0, s58
	v_lshl_add_u64 v[234:235], s[42:43], 0, v[136:137]
	ds_read_b128 v[194:197], v170 offset:32768
	ds_read_b128 v[198:201], v170 offset:33792
	ds_read_b128 v[202:205], v170 offset:34816
	ds_read_b128 v[206:209], v170 offset:35840
	ds_read_b128 v[210:213], v170 offset:36864
	ds_read_b128 v[214:217], v170 offset:37888
	ds_read_b128 v[218:221], v170 offset:38912
	ds_read_b128 v[222:225], v170 offset:39936
	global_load_lds_dwordx4 v[234:235], off
	v_lshl_add_u64 v[234:235], s[42:43], 0, v[132:133]
	s_mov_b32 m0, s59
	s_nop 0
	global_load_lds_dwordx4 v[234:235], off
	s_waitcnt vmcnt(8)
	s_waitcnt lgkmcnt(0)
	s_barrier
	s_waitcnt lgkmcnt(0)
	v_mfma_f32_16x16x32_bf16 v[120:123], v[148:151], v[194:197], v[120:123]
	v_mfma_f32_16x16x32_bf16 v[116:119], v[156:159], v[194:197], v[116:119]
	v_mfma_f32_16x16x32_bf16 v[108:111], v[148:151], v[202:205], v[108:111]
	v_mfma_f32_16x16x32_bf16 v[100:103], v[156:159], v[202:205], v[100:103]
	v_mfma_f32_16x16x32_bf16 v[92:95], v[148:151], v[210:213], v[92:95]
	v_mfma_f32_16x16x32_bf16 v[84:87], v[156:159], v[210:213], v[84:87]
	v_mfma_f32_16x16x32_bf16 v[76:79], v[148:151], v[218:221], v[76:79]
	v_mfma_f32_16x16x32_bf16 v[68:71], v[156:159], v[218:221], v[68:71]
	v_mfma_f32_16x16x32_bf16 v[120:123], v[152:155], v[198:201], v[120:123]
	v_mfma_f32_16x16x32_bf16 v[116:119], v[160:163], v[198:201], v[116:119]
	v_mfma_f32_16x16x32_bf16 v[108:111], v[152:155], v[206:209], v[108:111]
	v_mfma_f32_16x16x32_bf16 v[100:103], v[160:163], v[206:209], v[100:103]
	v_mfma_f32_16x16x32_bf16 v[92:95], v[152:155], v[214:217], v[92:95]
	v_mfma_f32_16x16x32_bf16 v[84:87], v[160:163], v[214:217], v[84:87]
	v_mfma_f32_16x16x32_bf16 v[76:79], v[152:155], v[222:225], v[76:79]
	v_mfma_f32_16x16x32_bf16 v[68:71], v[160:163], v[222:225], v[68:71]
	v_mfma_f32_16x16x32_bf16 v[124:127], v[174:177], v[194:197], v[124:127]
	v_mfma_f32_16x16x32_bf16 v[112:115], v[182:185], v[194:197], v[112:115]
	v_mfma_f32_16x16x32_bf16 v[104:107], v[174:177], v[202:205], v[104:107]
	v_mfma_f32_16x16x32_bf16 v[96:99], v[182:185], v[202:205], v[96:99]
	v_mfma_f32_16x16x32_bf16 v[88:91], v[174:177], v[210:213], v[88:91]
	v_mfma_f32_16x16x32_bf16 v[80:83], v[182:185], v[210:213], v[80:83]
	v_mfma_f32_16x16x32_bf16 v[72:75], v[174:177], v[218:221], v[72:75]
	v_mfma_f32_16x16x32_bf16 v[64:67], v[182:185], v[218:221], v[64:67]
	v_mfma_f32_16x16x32_bf16 v[124:127], v[178:181], v[198:201], v[124:127]
	v_mfma_f32_16x16x32_bf16 v[112:115], v[186:189], v[198:201], v[112:115]
	v_mfma_f32_16x16x32_bf16 v[104:107], v[178:181], v[206:209], v[104:107]
	v_mfma_f32_16x16x32_bf16 v[96:99], v[186:189], v[206:209], v[96:99]
	v_mfma_f32_16x16x32_bf16 v[88:91], v[178:181], v[214:217], v[88:91]
	v_mfma_f32_16x16x32_bf16 v[80:83], v[186:189], v[214:217], v[80:83]
	v_mfma_f32_16x16x32_bf16 v[72:75], v[178:181], v[222:225], v[72:75]
	v_mfma_f32_16x16x32_bf16 v[64:67], v[186:189], v[222:225], v[64:67]
	s_barrier
; #define PG8_STAGE(bufoff, gbase, voff) do { _Pragma("unroll") for (int _i = 0; _i < 2; ++_i) \
;         __builtin_amdgcn_global_load_lds((const unsigned*)((const char*)(gbase) + (voff)[_i]), (PG8_LAS unsigned*)(lds + (bufoff) + ldsw + _i * 8192), 16, 0, 0); } while (0)
; #define PG8_LDA(dst, b, h) do { _Pragma("unroll") for (int m = 0; m < 4; ++m) _Pragma("unroll") for (int k = 0; k < 2; ++k) dst[m][k] = *(const PG8_LAS bf16x8*)(lds + PG8_SA(b, h) + aoff + m * 2048 + k * 1024); } while (0)
; #define PG8_MMA(ai, bj, At, Bt) do { __builtin_amdgcn_s_setprio(1); _Pragma("unroll") for (int m = 0; m < 4; ++m) _Pragma("unroll") for (int n = 0; n < 2; ++n) _Pragma("unroll") for (int k = 0; k < 2; ++k) \
;         acc[ai][bj][m][n] = __builtin_amdgcn_mfma_f32_16x16x32_bf16(Bt[n][k], At[m][k], acc[ai][bj][m][n], 0, 0, 0); __builtin_amdgcn_s_setprio(0); } while (0)
; #define PG8_WAIT_V(n) asm volatile("s_waitcnt vmcnt(" #n ")" ::: "memory")
; #define PG8_WAIT_L(n) asm volatile("s_waitcnt lgkmcnt(" #n ")" ::: "memory")
; #define PG8_BAR __builtin_amdgcn_s_barrier()
; #define PG8_SCHED __builtin_amdgcn_sched_barrier(0)
; template <class Epi, class Sched, bool ALIGN_EPI = false, bool SP2 = false>
; __device__ __forceinline__ void gemm_phase(PG8_LAS unsigned char* lds, const Gemm g, const Sched& S, const Epi& E) {
;     ...
;             const char* a1 = cA + (size_t)(t + 1) * kstep;
;             const char* a2 = last ? nA : cA + (size_t)(t + 2) * kstep; const char* b2 = last ? nB : cB + (size_t)(t + 2) * kstep;
;             const char* a3 = a2 + kstep; const char* b3 = b2 + kstep;
;     ...
;             PG8_LDA(At, 1, 1); PG8_STAGE(PG8_SB(1, 0), b3, voffB); PG8_STAGE(PG8_SB(1, 1), b3 + hstep, voffB); PG8_STAGE(PG8_SA(1, 0), a3, voffA);
;             PG8_WAIT_V(8); PG8_WAIT_L(0); PG8_BAR; PG8_MMA(1, 0, At, B0); PG8_MMA(1, 1, At, B1); PG8_BAR; PG8_SCHED;
	s_add_i32 s42, s72, s3
	v_lshl_add_u64 v[164:165], v[164:165], 0, s[18:19]
	s_mov_b32 m0, s42
	ds_read_b128 v[194:197], v170 offset:49152
	ds_read_b128 v[198:201], v170 offset:50176
	ds_read_b128 v[202:205], v170 offset:51200
	ds_read_b128 v[206:209], v170 offset:52224
	ds_read_b128 v[210:213], v170 offset:53248
	ds_read_b128 v[214:217], v170 offset:54272
	ds_read_b128 v[218:221], v170 offset:55296
	ds_read_b128 v[222:225], v170 offset:56320
	global_load_lds_dwordx4 v[164:165], off
	v_lshl_add_u64 v[164:165], v[190:191], 0, s[18:19]
	s_add_i32 m0, s42, 0x2000
	s_add_i32 s42, s73, s3
	global_load_lds_dwordx4 v[164:165], off
	v_lshl_add_u64 v[164:165], v[226:227], 0, s[18:19]
	s_mov_b32 m0, s42
	s_nop 0
	global_load_lds_dwordx4 v[164:165], off
	v_lshl_add_u64 v[164:165], v[228:229], 0, s[18:19]
	s_add_i32 m0, s42, 0x2000
	s_nop 0
	global_load_lds_dwordx4 v[164:165], off
	v_lshl_add_u64 v[164:165], v[230:231], 0, s[18:19]
	s_mov_b32 m0, s48
	s_nop 0
	global_load_lds_dwordx4 v[164:165], off
	v_lshl_add_u64 v[164:165], v[232:233], 0, s[18:19]
	s_mov_b32 m0, s61
	s_nop 0
	global_load_lds_dwordx4 v[164:165], off
	s_waitcnt vmcnt(8)
	s_waitcnt lgkmcnt(0)
	s_barrier
	s_waitcnt lgkmcnt(0)
	v_mfma_f32_16x16x32_bf16 v[60:63], v[148:151], v[194:197], v[60:63]
	v_mfma_f32_16x16x32_bf16 v[52:55], v[156:159], v[194:197], v[52:55]
	v_mfma_f32_16x16x32_bf16 v[44:47], v[148:151], v[202:205], v[44:47]
	v_mfma_f32_16x16x32_bf16 v[36:39], v[156:159], v[202:205], v[36:39]
	v_mfma_f32_16x16x32_bf16 v[28:31], v[148:151], v[210:213], v[28:31]
	v_mfma_f32_16x16x32_bf16 v[20:23], v[156:159], v[210:213], v[20:23]
	v_mfma_f32_16x16x32_bf16 v[12:15], v[148:151], v[218:221], v[12:15]
	v_mfma_f32_16x16x32_bf16 v[4:7], v[156:159], v[218:221], v[4:7]
	v_mfma_f32_16x16x32_bf16 v[60:63], v[152:155], v[198:201], v[60:63]
	v_mfma_f32_16x16x32_bf16 v[52:55], v[160:163], v[198:201], v[52:55]
	v_mfma_f32_16x16x32_bf16 v[44:47], v[152:155], v[206:209], v[44:47]
	v_mfma_f32_16x16x32_bf16 v[36:39], v[160:163], v[206:209], v[36:39]
	v_mfma_f32_16x16x32_bf16 v[28:31], v[152:155], v[214:217], v[28:31]
	v_mfma_f32_16x16x32_bf16 v[20:23], v[160:163], v[214:217], v[20:23]
	v_mfma_f32_16x16x32_bf16 v[12:15], v[152:155], v[222:225], v[12:15]
	v_mfma_f32_16x16x32_bf16 v[4:7], v[160:163], v[222:225], v[4:7]
	v_mfma_f32_16x16x32_bf16 v[56:59], v[174:177], v[194:197], v[56:59]
	v_mfma_f32_16x16x32_bf16 v[48:51], v[182:185], v[194:197], v[48:51]
	v_mfma_f32_16x16x32_bf16 v[40:43], v[174:177], v[202:205], v[40:43]
	v_mfma_f32_16x16x32_bf16 v[32:35], v[182:185], v[202:205], v[32:35]
	v_mfma_f32_16x16x32_bf16 v[24:27], v[174:177], v[210:213], v[24:27]
	v_mfma_f32_16x16x32_bf16 v[16:19], v[182:185], v[210:213], v[16:19]
	v_mfma_f32_16x16x32_bf16 v[8:11], v[174:177], v[218:221], v[8:11]
	v_mfma_f32_16x16x32_bf16 v[0:3], v[182:185], v[218:221], v[0:3]
	v_mfma_f32_16x16x32_bf16 v[56:59], v[178:181], v[198:201], v[56:59]
	v_mfma_f32_16x16x32_bf16 v[48:51], v[186:189], v[198:201], v[48:51]
	v_mfma_f32_16x16x32_bf16 v[40:43], v[178:181], v[206:209], v[40:43]
	v_mfma_f32_16x16x32_bf16 v[32:35], v[186:189], v[206:209], v[32:35]
	v_mfma_f32_16x16x32_bf16 v[24:27], v[178:181], v[214:217], v[24:27]
	v_mfma_f32_16x16x32_bf16 v[16:19], v[186:189], v[214:217], v[16:19]
	v_mfma_f32_16x16x32_bf16 v[8:11], v[178:181], v[222:225], v[8:11]
	v_mfma_f32_16x16x32_bf16 v[0:3], v[186:189], v[222:225], v[0:3]
	s_barrier
	s_add_u32 s40, s40, 0x100
	s_addc_u32 s41, s41, 0
	s_add_u32 s33, s33, 0x100
	s_addc_u32 s38, s38, 0
	s_cmp_ge_i32 s71, s62
	s_mov_b32 s42, s71
	s_cbranch_scc0 .LBB0_264

; #define PG8_STAGE(bufoff, gbase, voff) do { _Pragma("unroll") for (int _i = 0; _i < 2; ++_i) \
;         __builtin_amdgcn_global_load_lds((const unsigned*)((const char*)(gbase) + (voff)[_i]), (PG8_LAS unsigned*)(lds + (bufoff) + ldsw + _i * 8192), 16, 0, 0); } while (0)
; #define PG8_LDA(dst, b, h) do { _Pragma("unroll") for (int m = 0; m < 4; ++m) _Pragma("unroll") for (int k = 0; k < 2; ++k) dst[m][k] = *(const PG8_LAS bf16x8*)(lds + PG8_SA(b, h) + aoff + m * 2048 + k * 1024); } while (0)
; #define PG8_LDB(dst, b, h) do { _Pragma("unroll") for (int n = 0; n < 2; ++n) _Pragma("unroll") for (int k = 0; k < 2; ++k) dst[n][k] = *(const PG8_LAS bf16x8*)(lds + PG8_SB(b, h) + boff + n * 2048 + k * 1024); } while (0)
; #define PG8_MMA(ai, bj, At, Bt) do { __builtin_amdgcn_s_setprio(1); _Pragma("unroll") for (int m = 0; m < 4; ++m) _Pragma("unroll") for (int n = 0; n < 2; ++n) _Pragma("unroll") for (int k = 0; k < 2; ++k) \
;         acc[ai][bj][m][n] = __builtin_amdgcn_mfma_f32_16x16x32_bf16(Bt[n][k], At[m][k], acc[ai][bj][m][n], 0, 0, 0); __builtin_amdgcn_s_setprio(0); } while (0)
; #define PG8_WAIT_V(n) asm volatile("s_waitcnt vmcnt(" #n ")" ::: "memory")
; #define PG8_WAIT_L(n) asm volatile("s_waitcnt lgkmcnt(" #n ")" ::: "memory")
; #define PG8_BAR __builtin_amdgcn_s_barrier()
; #define PG8_SCHED __builtin_amdgcn_sched_barrier(0)
; template <class Epi, class Sched, bool ALIGN_EPI = false, bool SP2 = false>
; __device__ __forceinline__ void gemm_phase(PG8_LAS unsigned char* lds, const Gemm g, const Sched& S, const Epi& E) {
;     ...
;             PG8_LDB(B0, 0, 0); PG8_LDB(B1, 0, 1); PG8_SCHED; PG8_LDA(At, 0, 0); PG8_STAGE(PG8_SA(1, 1), a1 + hstep, voffA);
;             PG8_WAIT_V(8); PG8_WAIT_L(0); PG8_BAR; PG8_MMA(0, 0, At, B0); PG8_MMA(0, 1, At, B1); PG8_BAR; PG8_SCHED;
;             PG8_LDA(At, 0, 1); PG8_STAGE(PG8_SB(0, 0), b2, voffB); PG8_STAGE(PG8_SB(0, 1), b2 + hstep, voffB); PG8_STAGE(PG8_SA(0, 0), a2, voffA);
;             PG8_WAIT_V(8); PG8_WAIT_L(0); PG8_BAR; PG8_MMA(1, 0, At, B0); PG8_MMA(1, 1, At, B1); PG8_BAR; PG8_SCHED;
;             PG8_LDB(B0, 1, 0); PG8_LDB(B1, 1, 1); PG8_SCHED; PG8_LDA(At, 1, 0); PG8_STAGE(PG8_SA(0, 1), a2 + hstep, voffA);
.LBB0_284:
	ds_read_b128 v[150:153], v144
	ds_read_b128 v[154:157], v144 offset:1024
	ds_read_b128 v[158:161], v144 offset:2048
	ds_read_b128 v[162:165], v144 offset:3072
	ds_read_b128 v[166:169], v145
	ds_read_b128 v[170:173], v145 offset:1024
	ds_read_b128 v[174:177], v145 offset:2048
	ds_read_b128 v[178:181], v145 offset:3072
	s_add_i32 s90, s62, 2
	s_add_u32 s91, s60, 0x80
	s_addc_u32 s63, s61, 0
	s_cmp_eq_u32 s74, s62
	s_cselect_b32 s62, s56, s91
	s_cselect_b32 s63, s57, s63
	s_cselect_b32 s93, s59, s89
	s_cselect_b32 s92, s58, s33
	s_mov_b32 m0, s75
	v_lshl_add_u64 v[190:191], s[60:61], 0, v[140:141]
	ds_read_b128 v[182:185], v146
	ds_read_b128 v[186:189], v146 offset:1024
	ds_read_b128 v[194:197], v146 offset:2048
	ds_read_b128 v[198:201], v146 offset:3072
	ds_read_b128 v[202:205], v146 offset:4096
	ds_read_b128 v[206:209], v146 offset:5120
	ds_read_b128 v[210:213], v146 offset:6144
	ds_read_b128 v[214:217], v146 offset:7168
	global_load_lds_dwordx4 v[190:191], off
	v_lshl_add_u64 v[190:191], s[60:61], 0, v[142:143]
	s_mov_b32 m0, s76
	s_nop 0
	global_load_lds_dwordx4 v[190:191], off
	s_waitcnt vmcnt(8)
	s_waitcnt lgkmcnt(0)
	s_barrier
	s_waitcnt lgkmcnt(0)
	v_mfma_f32_16x16x32_bf16 v[124:127], v[150:153], v[182:185], v[124:127]
	v_mfma_f32_16x16x32_bf16 v[120:123], v[158:161], v[182:185], v[120:123]
	v_mfma_f32_16x16x32_bf16 v[108:111], v[150:153], v[194:197], v[108:111]
	v_mfma_f32_16x16x32_bf16 v[104:107], v[158:161], v[194:197], v[104:107]
	v_mfma_f32_16x16x32_bf16 v[92:95], v[150:153], v[202:205], v[92:95]
	v_mfma_f32_16x16x32_bf16 v[88:91], v[158:161], v[202:205], v[88:91]
	v_mfma_f32_16x16x32_bf16 v[76:79], v[150:153], v[210:213], v[76:79]
	v_mfma_f32_16x16x32_bf16 v[72:75], v[158:161], v[210:213], v[72:75]
	v_mfma_f32_16x16x32_bf16 v[124:127], v[154:157], v[186:189], v[124:127]
	v_mfma_f32_16x16x32_bf16 v[120:123], v[162:165], v[186:189], v[120:123]
	v_mfma_f32_16x16x32_bf16 v[108:111], v[154:157], v[198:201], v[108:111]
	v_mfma_f32_16x16x32_bf16 v[104:107], v[162:165], v[198:201], v[104:107]
	v_mfma_f32_16x16x32_bf16 v[92:95], v[154:157], v[206:209], v[92:95]
	v_mfma_f32_16x16x32_bf16 v[88:91], v[162:165], v[206:209], v[88:91]
	v_mfma_f32_16x16x32_bf16 v[76:79], v[154:157], v[214:217], v[76:79]
	v_mfma_f32_16x16x32_bf16 v[72:75], v[162:165], v[214:217], v[72:75]
	v_mfma_f32_16x16x32_bf16 v[116:119], v[166:169], v[182:185], v[116:119]
	v_mfma_f32_16x16x32_bf16 v[112:115], v[174:177], v[182:185], v[112:115]
	v_mfma_f32_16x16x32_bf16 v[100:103], v[166:169], v[194:197], v[100:103]
	v_mfma_f32_16x16x32_bf16 v[96:99], v[174:177], v[194:197], v[96:99]
	v_mfma_f32_16x16x32_bf16 v[84:87], v[166:169], v[202:205], v[84:87]
	v_mfma_f32_16x16x32_bf16 v[80:83], v[174:177], v[202:205], v[80:83]
	v_mfma_f32_16x16x32_bf16 v[68:71], v[166:169], v[210:213], v[68:71]
	v_mfma_f32_16x16x32_bf16 v[64:67], v[174:177], v[210:213], v[64:67]
	v_mfma_f32_16x16x32_bf16 v[116:119], v[170:173], v[186:189], v[116:119]
	v_mfma_f32_16x16x32_bf16 v[112:115], v[178:181], v[186:189], v[112:115]
	v_mfma_f32_16x16x32_bf16 v[100:103], v[170:173], v[198:201], v[100:103]
	v_mfma_f32_16x16x32_bf16 v[96:99], v[178:181], v[198:201], v[96:99]
	v_mfma_f32_16x16x32_bf16 v[84:87], v[170:173], v[206:209], v[84:87]
	v_mfma_f32_16x16x32_bf16 v[80:83], v[178:181], v[206:209], v[80:83]
	v_mfma_f32_16x16x32_bf16 v[68:71], v[170:173], v[214:217], v[68:71]
	v_mfma_f32_16x16x32_bf16 v[64:67], v[178:181], v[214:217], v[64:67]
	s_barrier
	s_mov_b32 m0, s77
	v_lshl_add_u64 v[190:191], s[92:93], 0, v[134:135]
	v_lshl_add_u64 v[218:219], s[92:93], 0, v[130:131]
	s_add_u32 s92, s92, s12
	ds_read_b128 v[182:185], v146 offset:16384
	ds_read_b128 v[186:189], v146 offset:17408
	ds_read_b128 v[194:197], v146 offset:18432
	ds_read_b128 v[198:201], v146 offset:19456
	ds_read_b128 v[202:205], v146 offset:20480
	ds_read_b128 v[206:209], v146 offset:21504
	ds_read_b128 v[210:213], v146 offset:22528
	ds_read_b128 v[214:217], v146 offset:23552
	global_load_lds_dwordx4 v[190:191], off
	s_mov_b32 m0, s78
	s_addc_u32 s93, s93, s13
	global_load_lds_dwordx4 v[218:219], off
	v_lshl_add_u64 v[220:221], s[92:93], 0, v[134:135]
	s_mov_b32 m0, s79
	v_lshl_add_u64 v[222:223], s[92:93], 0, v[130:131]
	global_load_lds_dwordx4 v[220:221], off
	s_mov_b32 m0, s80
	v_lshl_add_u64 v[224:225], s[62:63], 0, v[136:137]
	global_load_lds_dwordx4 v[222:223], off
	s_mov_b32 m0, s4
	v_lshl_add_u64 v[226:227], s[62:63], 0, v[132:133]
	global_load_lds_dwordx4 v[224:225], off
	s_mov_b32 m0, s5
	s_nop 0
	global_load_lds_dwordx4 v[226:227], off
	s_waitcnt vmcnt(8)
	s_waitcnt lgkmcnt(0)
	s_barrier
; #define PG8_STAGE(bufoff, gbase, voff) do { _Pragma("unroll") for (int _i = 0; _i < 2; ++_i) \
;         __builtin_amdgcn_global_load_lds((const unsigned*)((const char*)(gbase) + (voff)[_i]), (PG8_LAS unsigned*)(lds + (bufoff) + ldsw + _i * 8192), 16, 0, 0); } while (0)
; #define PG8_LDA(dst, b, h) do { _Pragma("unroll") for (int m = 0; m < 4; ++m) _Pragma("unroll") for (int k = 0; k < 2; ++k) dst[m][k] = *(const PG8_LAS bf16x8*)(lds + PG8_SA(b, h) + aoff + m * 2048 + k * 1024); } while (0)
; #define PG8_LDB(dst, b, h) do { _Pragma("unroll") for (int n = 0; n < 2; ++n) _Pragma("unroll") for (int k = 0; k < 2; ++k) dst[n][k] = *(const PG8_LAS bf16x8*)(lds + PG8_SB(b, h) + boff + n * 2048 + k * 1024); } while (0)
; #define PG8_MMA(ai, bj, At, Bt) do { __builtin_amdgcn_s_setprio(1); _Pragma("unroll") for (int m = 0; m < 4; ++m) _Pragma("unroll") for (int n = 0; n < 2; ++n) _Pragma("unroll") for (int k = 0; k < 2; ++k) \
;         acc[ai][bj][m][n] = __builtin_amdgcn_mfma_f32_16x16x32_bf16(Bt[n][k], At[m][k], acc[ai][bj][m][n], 0, 0, 0); __builtin_amdgcn_s_setprio(0); } while (0)
; #define PG8_WAIT_V(n) asm volatile("s_waitcnt vmcnt(" #n ")" ::: "memory")
; #define PG8_WAIT_L(n) asm volatile("s_waitcnt lgkmcnt(" #n ")" ::: "memory")
; #define PG8_BAR __builtin_amdgcn_s_barrier()
; #define PG8_SCHED __builtin_amdgcn_sched_barrier(0)
; template <class Epi, class Sched, bool ALIGN_EPI = false, bool SP2 = false>
; __device__ __forceinline__ void gemm_phase(PG8_LAS unsigned char* lds, const Gemm g, const Sched& S, const Epi& E) {
;     ...
;             PG8_WAIT_V(8); PG8_WAIT_L(0); PG8_BAR; PG8_MMA(1, 0, At, B0); PG8_MMA(1, 1, At, B1); PG8_BAR; PG8_SCHED;
;             PG8_LDB(B0, 1, 0); PG8_LDB(B1, 1, 1); PG8_SCHED; PG8_LDA(At, 1, 0); PG8_STAGE(PG8_SA(0, 1), a2 + hstep, voffA);
;             PG8_WAIT_V(8); PG8_WAIT_L(0); PG8_BAR; PG8_MMA(0, 0, At, B0); PG8_MMA(0, 1, At, B1); PG8_BAR; PG8_SCHED;
	s_waitcnt lgkmcnt(0)
	v_mfma_f32_16x16x32_bf16 v[60:63], v[150:153], v[182:185], v[60:63]
	v_mfma_f32_16x16x32_bf16 v[56:59], v[158:161], v[182:185], v[56:59]
	v_mfma_f32_16x16x32_bf16 v[44:47], v[150:153], v[194:197], v[44:47]
	v_mfma_f32_16x16x32_bf16 v[40:43], v[158:161], v[194:197], v[40:43]
	v_mfma_f32_16x16x32_bf16 v[28:31], v[150:153], v[202:205], v[28:31]
	v_mfma_f32_16x16x32_bf16 v[24:27], v[158:161], v[202:205], v[24:27]
	v_mfma_f32_16x16x32_bf16 v[12:15], v[150:153], v[210:213], v[12:15]
	v_mfma_f32_16x16x32_bf16 v[8:11], v[158:161], v[210:213], v[8:11]
	v_mfma_f32_16x16x32_bf16 v[60:63], v[154:157], v[186:189], v[60:63]
	v_mfma_f32_16x16x32_bf16 v[56:59], v[162:165], v[186:189], v[56:59]
	v_mfma_f32_16x16x32_bf16 v[44:47], v[154:157], v[198:201], v[44:47]
	v_mfma_f32_16x16x32_bf16 v[40:43], v[162:165], v[198:201], v[40:43]
	v_mfma_f32_16x16x32_bf16 v[28:31], v[154:157], v[206:209], v[28:31]
	v_mfma_f32_16x16x32_bf16 v[24:27], v[162:165], v[206:209], v[24:27]
	v_mfma_f32_16x16x32_bf16 v[12:15], v[154:157], v[214:217], v[12:15]
	v_mfma_f32_16x16x32_bf16 v[8:11], v[162:165], v[214:217], v[8:11]
	v_mfma_f32_16x16x32_bf16 v[52:55], v[166:169], v[182:185], v[52:55]
	v_mfma_f32_16x16x32_bf16 v[48:51], v[174:177], v[182:185], v[48:51]
	v_mfma_f32_16x16x32_bf16 v[36:39], v[166:169], v[194:197], v[36:39]
	v_mfma_f32_16x16x32_bf16 v[32:35], v[174:177], v[194:197], v[32:35]
	v_mfma_f32_16x16x32_bf16 v[20:23], v[166:169], v[202:205], v[20:23]
	v_mfma_f32_16x16x32_bf16 v[16:19], v[174:177], v[202:205], v[16:19]
	v_mfma_f32_16x16x32_bf16 v[4:7], v[166:169], v[210:213], v[4:7]
	v_mfma_f32_16x16x32_bf16 v[0:3], v[174:177], v[210:213], v[0:3]
	v_mfma_f32_16x16x32_bf16 v[52:55], v[170:173], v[186:189], v[52:55]
	v_mfma_f32_16x16x32_bf16 v[48:51], v[178:181], v[186:189], v[48:51]
	v_mfma_f32_16x16x32_bf16 v[36:39], v[170:173], v[198:201], v[36:39]
	v_mfma_f32_16x16x32_bf16 v[32:35], v[178:181], v[198:201], v[32:35]
	v_mfma_f32_16x16x32_bf16 v[20:23], v[170:173], v[206:209], v[20:23]
	v_mfma_f32_16x16x32_bf16 v[16:19], v[178:181], v[206:209], v[16:19]
	v_mfma_f32_16x16x32_bf16 v[4:7], v[170:173], v[214:217], v[4:7]
	v_mfma_f32_16x16x32_bf16 v[0:3], v[178:181], v[214:217], v[0:3]
	s_barrier
	ds_read_b128 v[150:153], v147
	ds_read_b128 v[154:157], v147 offset:1024
	ds_read_b128 v[158:161], v147 offset:2048
	ds_read_b128 v[162:165], v147 offset:3072
	ds_read_b128 v[166:169], v148
	ds_read_b128 v[170:173], v148 offset:1024
	ds_read_b128 v[174:177], v148 offset:2048
	ds_read_b128 v[178:181], v148 offset:3072
	s_add_u32 s62, s62, s12
	s_addc_u32 s63, s63, s13
	s_mov_b32 m0, s65
	v_lshl_add_u64 v[228:229], s[62:63], 0, v[136:137]
	ds_read_b128 v[182:185], v146 offset:32768
	ds_read_b128 v[186:189], v146 offset:33792
	ds_read_b128 v[194:197], v146 offset:34816
	ds_read_b128 v[198:201], v146 offset:35840
	ds_read_b128 v[202:205], v146 offset:36864
	ds_read_b128 v[206:209], v146 offset:37888
	ds_read_b128 v[210:213], v146 offset:38912
	ds_read_b128 v[214:217], v146 offset:39936
	global_load_lds_dwordx4 v[228:229], off
	v_lshl_add_u64 v[228:229], s[62:63], 0, v[132:133]
	s_mov_b32 m0, s66
	s_nop 0
	global_load_lds_dwordx4 v[228:229], off
	s_waitcnt vmcnt(8)
	s_waitcnt lgkmcnt(0)
	s_barrier
	s_waitcnt lgkmcnt(0)
	v_mfma_f32_16x16x32_bf16 v[124:127], v[150:153], v[182:185], v[124:127]
	v_mfma_f32_16x16x32_bf16 v[120:123], v[158:161], v[182:185], v[120:123]
	v_mfma_f32_16x16x32_bf16 v[108:111], v[150:153], v[194:197], v[108:111]
	v_mfma_f32_16x16x32_bf16 v[104:107], v[158:161], v[194:197], v[104:107]
	v_mfma_f32_16x16x32_bf16 v[92:95], v[150:153], v[202:205], v[92:95]
	v_mfma_f32_16x16x32_bf16 v[88:91], v[158:161], v[202:205], v[88:91]
	v_mfma_f32_16x16x32_bf16 v[76:79], v[150:153], v[210:213], v[76:79]
	v_mfma_f32_16x16x32_bf16 v[72:75], v[158:161], v[210:213], v[72:75]
	v_mfma_f32_16x16x32_bf16 v[124:127], v[154:157], v[186:189], v[124:127]
	v_mfma_f32_16x16x32_bf16 v[120:123], v[162:165], v[186:189], v[120:123]
	v_mfma_f32_16x16x32_bf16 v[108:111], v[154:157], v[198:201], v[108:111]
	v_mfma_f32_16x16x32_bf16 v[104:107], v[162:165], v[198:201], v[104:107]
	v_mfma_f32_16x16x32_bf16 v[92:95], v[154:157], v[206:209], v[92:95]
	v_mfma_f32_16x16x32_bf16 v[88:91], v[162:165], v[206:209], v[88:91]
	v_mfma_f32_16x16x32_bf16 v[76:79], v[154:157], v[214:217], v[76:79]
	v_mfma_f32_16x16x32_bf16 v[72:75], v[162:165], v[214:217], v[72:75]
	v_mfma_f32_16x16x32_bf16 v[116:119], v[166:169], v[182:185], v[116:119]
	v_mfma_f32_16x16x32_bf16 v[112:115], v[174:177], v[182:185], v[112:115]
	v_mfma_f32_16x16x32_bf16 v[100:103], v[166:169], v[194:197], v[100:103]
	v_mfma_f32_16x16x32_bf16 v[96:99], v[174:177], v[194:197], v[96:99]
	v_mfma_f32_16x16x32_bf16 v[84:87], v[166:169], v[202:205], v[84:87]
	v_mfma_f32_16x16x32_bf16 v[80:83], v[174:177], v[202:205], v[80:83]
	v_mfma_f32_16x16x32_bf16 v[68:71], v[166:169], v[210:213], v[68:71]
	v_mfma_f32_16x16x32_bf16 v[64:67], v[174:177], v[210:213], v[64:67]
	v_mfma_f32_16x16x32_bf16 v[116:119], v[170:173], v[186:189], v[116:119]
	v_mfma_f32_16x16x32_bf16 v[112:115], v[178:181], v[186:189], v[112:115]
	v_mfma_f32_16x16x32_bf16 v[100:103], v[170:173], v[198:201], v[100:103]
	v_mfma_f32_16x16x32_bf16 v[96:99], v[178:181], v[198:201], v[96:99]
	v_mfma_f32_16x16x32_bf16 v[84:87], v[170:173], v[206:209], v[84:87]
	v_mfma_f32_16x16x32_bf16 v[80:83], v[178:181], v[206:209], v[80:83]
	v_mfma_f32_16x16x32_bf16 v[68:71], v[170:173], v[214:217], v[68:71]
	v_mfma_f32_16x16x32_bf16 v[64:67], v[178:181], v[214:217], v[64:67]
	s_barrier
; #define PG8_STAGE(bufoff, gbase, voff) do { _Pragma("unroll") for (int _i = 0; _i < 2; ++_i) \
;         __builtin_amdgcn_global_load_lds((const unsigned*)((const char*)(gbase) + (voff)[_i]), (PG8_LAS unsigned*)(lds + (bufoff) + ldsw + _i * 8192), 16, 0, 0); } while (0)
; #define PG8_LDA(dst, b, h) do { _Pragma("unroll") for (int m = 0; m < 4; ++m) _Pragma("unroll") for (int k = 0; k < 2; ++k) dst[m][k] = *(const PG8_LAS bf16x8*)(lds + PG8_SA(b, h) + aoff + m * 2048 + k * 1024); } while (0)
; #define PG8_MMA(ai, bj, At, Bt) do { __builtin_amdgcn_s_setprio(1); _Pragma("unroll") for (int m = 0; m < 4; ++m) _Pragma("unroll") for (int n = 0; n < 2; ++n) _Pragma("unroll") for (int k = 0; k < 2; ++k) \
;         acc[ai][bj][m][n] = __builtin_amdgcn_mfma_f32_16x16x32_bf16(Bt[n][k], At[m][k], acc[ai][bj][m][n], 0, 0, 0); __builtin_amdgcn_s_setprio(0); } while (0)
; #define PG8_WAIT_V(n) asm volatile("s_waitcnt vmcnt(" #n ")" ::: "memory")
; #define PG8_WAIT_L(n) asm volatile("s_waitcnt lgkmcnt(" #n ")" ::: "memory")
; #define PG8_BAR __builtin_amdgcn_s_barrier()
; #define PG8_SCHED __builtin_amdgcn_sched_barrier(0)
; template <class Epi, class Sched, bool ALIGN_EPI = false, bool SP2 = false>
; __device__ __forceinline__ void gemm_phase(PG8_LAS unsigned char* lds, const Gemm g, const Sched& S, const Epi& E) {
;     ...
;             PG8_LDA(At, 1, 1); PG8_STAGE(PG8_SB(1, 0), b3, voffB); PG8_STAGE(PG8_SB(1, 1), b3 + hstep, voffB); PG8_STAGE(PG8_SA(1, 0), a3, voffA);
;             PG8_WAIT_V(8); PG8_WAIT_L(0); PG8_BAR; PG8_MMA(1, 0, At, B0); PG8_MMA(1, 1, At, B1); PG8_BAR; PG8_SCHED;
	s_mov_b32 m0, s84
	v_lshl_add_u64 v[190:191], v[190:191], 0, s[18:19]
	ds_read_b128 v[182:185], v146 offset:49152
	ds_read_b128 v[186:189], v146 offset:50176
	ds_read_b128 v[194:197], v146 offset:51200
	ds_read_b128 v[198:201], v146 offset:52224
	ds_read_b128 v[202:205], v146 offset:53248
	ds_read_b128 v[206:209], v146 offset:54272
	ds_read_b128 v[210:213], v146 offset:55296
	ds_read_b128 v[214:217], v146 offset:56320
	global_load_lds_dwordx4 v[190:191], off
	v_lshl_add_u64 v[190:191], v[218:219], 0, s[18:19]
	s_mov_b32 m0, s85
	s_nop 0
	global_load_lds_dwordx4 v[190:191], off
	v_lshl_add_u64 v[190:191], v[220:221], 0, s[18:19]
	s_mov_b32 m0, s86
	s_nop 0
	global_load_lds_dwordx4 v[190:191], off
	v_lshl_add_u64 v[190:191], v[222:223], 0, s[18:19]
	s_mov_b32 m0, s87
	s_nop 0
	global_load_lds_dwordx4 v[190:191], off
	v_lshl_add_u64 v[190:191], v[224:225], 0, s[18:19]
	s_mov_b32 m0, s69
	s_nop 0
	global_load_lds_dwordx4 v[190:191], off
	v_lshl_add_u64 v[190:191], v[226:227], 0, s[18:19]
	s_mov_b32 m0, s70
	s_nop 0
	global_load_lds_dwordx4 v[190:191], off
	s_waitcnt vmcnt(8)
	s_waitcnt lgkmcnt(0)
	s_barrier
	s_waitcnt lgkmcnt(0)
	v_mfma_f32_16x16x32_bf16 v[60:63], v[150:153], v[182:185], v[60:63]
	v_mfma_f32_16x16x32_bf16 v[56:59], v[158:161], v[182:185], v[56:59]
	v_mfma_f32_16x16x32_bf16 v[44:47], v[150:153], v[194:197], v[44:47]
	v_mfma_f32_16x16x32_bf16 v[40:43], v[158:161], v[194:197], v[40:43]
	v_mfma_f32_16x16x32_bf16 v[28:31], v[150:153], v[202:205], v[28:31]
	v_mfma_f32_16x16x32_bf16 v[24:27], v[158:161], v[202:205], v[24:27]
	v_mfma_f32_16x16x32_bf16 v[12:15], v[150:153], v[210:213], v[12:15]
	v_mfma_f32_16x16x32_bf16 v[8:11], v[158:161], v[210:213], v[8:11]
	v_mfma_f32_16x16x32_bf16 v[60:63], v[154:157], v[186:189], v[60:63]
	v_mfma_f32_16x16x32_bf16 v[56:59], v[162:165], v[186:189], v[56:59]
	v_mfma_f32_16x16x32_bf16 v[44:47], v[154:157], v[198:201], v[44:47]
	v_mfma_f32_16x16x32_bf16 v[40:43], v[162:165], v[198:201], v[40:43]
	v_mfma_f32_16x16x32_bf16 v[28:31], v[154:157], v[206:209], v[28:31]
	v_mfma_f32_16x16x32_bf16 v[24:27], v[162:165], v[206:209], v[24:27]
	v_mfma_f32_16x16x32_bf16 v[12:15], v[154:157], v[214:217], v[12:15]
	v_mfma_f32_16x16x32_bf16 v[8:11], v[162:165], v[214:217], v[8:11]
	v_mfma_f32_16x16x32_bf16 v[52:55], v[166:169], v[182:185], v[52:55]
	v_mfma_f32_16x16x32_bf16 v[48:51], v[174:177], v[182:185], v[48:51]
	v_mfma_f32_16x16x32_bf16 v[36:39], v[166:169], v[194:197], v[36:39]
	v_mfma_f32_16x16x32_bf16 v[32:35], v[174:177], v[194:197], v[32:35]
	v_mfma_f32_16x16x32_bf16 v[20:23], v[166:169], v[202:205], v[20:23]
	v_mfma_f32_16x16x32_bf16 v[16:19], v[174:177], v[202:205], v[16:19]
	v_mfma_f32_16x16x32_bf16 v[4:7], v[166:169], v[210:213], v[4:7]
	v_mfma_f32_16x16x32_bf16 v[0:3], v[174:177], v[210:213], v[0:3]
	v_mfma_f32_16x16x32_bf16 v[52:55], v[170:173], v[186:189], v[52:55]
	v_mfma_f32_16x16x32_bf16 v[48:51], v[178:181], v[186:189], v[48:51]
	v_mfma_f32_16x16x32_bf16 v[36:39], v[170:173], v[198:201], v[36:39]
	v_mfma_f32_16x16x32_bf16 v[32:35], v[178:181], v[198:201], v[32:35]
	v_mfma_f32_16x16x32_bf16 v[20:23], v[170:173], v[206:209], v[20:23]
	v_mfma_f32_16x16x32_bf16 v[16:19], v[178:181], v[206:209], v[16:19]
	v_mfma_f32_16x16x32_bf16 v[4:7], v[170:173], v[214:217], v[4:7]
	v_mfma_f32_16x16x32_bf16 v[0:3], v[178:181], v[214:217], v[0:3]
	s_barrier
	s_add_u32 s60, s60, 0x100
	s_addc_u32 s61, s61, 0
	s_add_u32 s33, s33, 0x100
	s_addc_u32 s89, s89, 0
	s_cmp_ge_i32 s90, s72
	s_mov_b32 s62, s90
	s_cbranch_scc0 .LBB0_284

; #define PG8_STAGE(bufoff, gbase, voff) do { _Pragma("unroll") for (int _i = 0; _i < 2; ++_i) \
;         __builtin_amdgcn_global_load_lds((const unsigned*)((const char*)(gbase) + (voff)[_i]), (PG8_LAS unsigned*)(lds + (bufoff) + ldsw + _i * 8192), 16, 0, 0); } while (0)
; #define PG8_LDA(dst, b, h) do { _Pragma("unroll") for (int m = 0; m < 4; ++m) _Pragma("unroll") for (int k = 0; k < 2; ++k) dst[m][k] = *(const PG8_LAS bf16x8*)(lds + PG8_SA(b, h) + aoff + m * 2048 + k * 1024); } while (0)
; #define PG8_LDB(dst, b, h) do { _Pragma("unroll") for (int n = 0; n < 2; ++n) _Pragma("unroll") for (int k = 0; k < 2; ++k) dst[n][k] = *(const PG8_LAS bf16x8*)(lds + PG8_SB(b, h) + boff + n * 2048 + k * 1024); } while (0)
; #define PG8_MMA(ai, bj, At, Bt) do { __builtin_amdgcn_s_setprio(1); _Pragma("unroll") for (int m = 0; m < 4; ++m) _Pragma("unroll") for (int n = 0; n < 2; ++n) _Pragma("unroll") for (int k = 0; k < 2; ++k) \
;         acc[ai][bj][m][n] = __builtin_amdgcn_mfma_f32_16x16x32_bf16(Bt[n][k], At[m][k], acc[ai][bj][m][n], 0, 0, 0); __builtin_amdgcn_s_setprio(0); } while (0)
; #define PG8_WAIT_V(n) asm volatile("s_waitcnt vmcnt(" #n ")" ::: "memory")
; #define PG8_WAIT_L(n) asm volatile("s_waitcnt lgkmcnt(" #n ")" ::: "memory")
; #define PG8_BAR __builtin_amdgcn_s_barrier()
; #define PG8_SCHED __builtin_amdgcn_sched_barrier(0)
; template <class Epi, class Sched, bool ALIGN_EPI = false, bool SP2 = false>
; __device__ __forceinline__ void gemm_phase(PG8_LAS unsigned char* lds, const Gemm g, const Sched& S, const Epi& E) {
;     ...
;             PG8_LDB(B0, 0, 0); PG8_LDB(B1, 0, 1); PG8_SCHED; PG8_LDA(At, 0, 0); PG8_STAGE(PG8_SA(1, 1), a1 + hstep, voffA);
;             PG8_WAIT_V(8); PG8_WAIT_L(0); PG8_BAR; PG8_MMA(0, 0, At, B0); PG8_MMA(0, 1, At, B1); PG8_BAR; PG8_SCHED;
;             PG8_LDA(At, 0, 1); PG8_STAGE(PG8_SB(0, 0), b2, voffB); PG8_STAGE(PG8_SB(0, 1), b2 + hstep, voffB); PG8_STAGE(PG8_SA(0, 0), a2, voffA);
;             PG8_WAIT_V(8); PG8_WAIT_L(0); PG8_BAR; PG8_MMA(1, 0, At, B0); PG8_MMA(1, 1, At, B1); PG8_BAR; PG8_SCHED;
;             PG8_LDB(B0, 1, 0); PG8_LDB(B1, 1, 1); PG8_SCHED; PG8_LDA(At, 1, 0); PG8_STAGE(PG8_SA(0, 1), a2 + hstep, voffA);
.LBB0_368:
	ds_read_b128 v[144:147], v248
	ds_read_b128 v[148:151], v248 offset:1024
	ds_read_b128 v[152:155], v248 offset:2048
	ds_read_b128 v[156:159], v248 offset:3072
	ds_read_b128 v[160:163], v249
	ds_read_b128 v[164:167], v249 offset:1024
	ds_read_b128 v[168:171], v249 offset:2048
	ds_read_b128 v[172:175], v249 offset:3072
	s_add_i32 s38, s33, 2
	s_add_u32 s60, s58, 0x80
	s_addc_u32 s61, s59, 0
	s_cmp_eq_u32 s68, s33
	s_cselect_b32 s61, s11, s61
	s_cselect_b32 s60, s10, s60
	s_cselect_b32 s79, s57, s5
	s_cselect_b32 s78, s56, s4
	v_lshl_add_u64 v[210:211], s[58:59], 0, v[138:139]
	s_add_i32 m0, s39, 0xc000
	ds_read_b128 v[176:179], v250
	ds_read_b128 v[180:183], v250 offset:1024
	ds_read_b128 v[184:187], v250 offset:2048
	ds_read_b128 v[188:191], v250 offset:3072
	ds_read_b128 v[194:197], v250 offset:4096
	ds_read_b128 v[198:201], v250 offset:5120
	ds_read_b128 v[202:205], v250 offset:6144
	ds_read_b128 v[206:209], v250 offset:7168
	global_load_lds_dwordx4 v[210:211], off
	v_lshl_add_u64 v[210:211], s[58:59], 0, v[140:141]
	s_add_i32 m0, s39, 0xe000
	s_nop 0
	global_load_lds_dwordx4 v[210:211], off
	s_waitcnt vmcnt(8)
	s_waitcnt lgkmcnt(0)
	s_barrier
	s_waitcnt lgkmcnt(0)
	v_mfma_f32_16x16x32_bf16 v[124:127], v[144:147], v[176:179], v[124:127]
	v_mfma_f32_16x16x32_bf16 v[120:123], v[152:155], v[176:179], v[120:123]
	v_mfma_f32_16x16x32_bf16 v[116:119], v[144:147], v[184:187], v[116:119]
	v_mfma_f32_16x16x32_bf16 v[112:115], v[152:155], v[184:187], v[112:115]
	v_mfma_f32_16x16x32_bf16 v[104:107], v[144:147], v[194:197], v[104:107]
	v_mfma_f32_16x16x32_bf16 v[96:99], v[152:155], v[194:197], v[96:99]
	v_mfma_f32_16x16x32_bf16 v[88:91], v[144:147], v[202:205], v[88:91]
	v_mfma_f32_16x16x32_bf16 v[80:83], v[152:155], v[202:205], v[80:83]
	v_mfma_f32_16x16x32_bf16 v[124:127], v[148:151], v[180:183], v[124:127]
	v_mfma_f32_16x16x32_bf16 v[120:123], v[156:159], v[180:183], v[120:123]
	v_mfma_f32_16x16x32_bf16 v[116:119], v[148:151], v[188:191], v[116:119]
	v_mfma_f32_16x16x32_bf16 v[112:115], v[156:159], v[188:191], v[112:115]
	v_mfma_f32_16x16x32_bf16 v[104:107], v[148:151], v[198:201], v[104:107]
	v_mfma_f32_16x16x32_bf16 v[96:99], v[156:159], v[198:201], v[96:99]
	v_mfma_f32_16x16x32_bf16 v[88:91], v[148:151], v[206:209], v[88:91]
	v_mfma_f32_16x16x32_bf16 v[80:83], v[156:159], v[206:209], v[80:83]
	v_mfma_f32_16x16x32_bf16 v[108:111], v[160:163], v[176:179], v[108:111]
	v_mfma_f32_16x16x32_bf16 v[100:103], v[168:171], v[176:179], v[100:103]
	v_mfma_f32_16x16x32_bf16 v[92:95], v[160:163], v[184:187], v[92:95]
	v_mfma_f32_16x16x32_bf16 v[84:87], v[168:171], v[184:187], v[84:87]
	v_mfma_f32_16x16x32_bf16 v[76:79], v[160:163], v[194:197], v[76:79]
	v_mfma_f32_16x16x32_bf16 v[72:75], v[168:171], v[194:197], v[72:75]
	v_mfma_f32_16x16x32_bf16 v[68:71], v[160:163], v[202:205], v[68:71]
	v_mfma_f32_16x16x32_bf16 v[64:67], v[168:171], v[202:205], v[64:67]
	v_mfma_f32_16x16x32_bf16 v[108:111], v[164:167], v[180:183], v[108:111]
	v_mfma_f32_16x16x32_bf16 v[100:103], v[172:175], v[180:183], v[100:103]
	v_mfma_f32_16x16x32_bf16 v[92:95], v[164:167], v[188:191], v[92:95]
	v_mfma_f32_16x16x32_bf16 v[84:87], v[172:175], v[188:191], v[84:87]
	v_mfma_f32_16x16x32_bf16 v[76:79], v[164:167], v[198:201], v[76:79]
	v_mfma_f32_16x16x32_bf16 v[72:75], v[172:175], v[198:201], v[72:75]
	v_mfma_f32_16x16x32_bf16 v[68:71], v[164:167], v[206:209], v[68:71]
	v_mfma_f32_16x16x32_bf16 v[64:67], v[172:175], v[206:209], v[64:67]
	s_barrier
	s_add_i32 s33, s72, s3
	v_lshl_add_u64 v[210:211], s[78:79], 0, v[132:133]
	s_mov_b32 m0, s33
	ds_read_b128 v[176:179], v250 offset:16384
	ds_read_b128 v[180:183], v250 offset:17408
	ds_read_b128 v[184:187], v250 offset:18432
	ds_read_b128 v[188:191], v250 offset:19456
	ds_read_b128 v[194:197], v250 offset:20480
	ds_read_b128 v[198:201], v250 offset:21504
	ds_read_b128 v[202:205], v250 offset:22528
	ds_read_b128 v[206:209], v250 offset:23552
	global_load_lds_dwordx4 v[210:211], off
	s_add_i32 m0, s33, 0x2000
	v_lshl_add_u64 v[212:213], s[78:79], 0, v[136:137]
	s_add_u32 s78, s78, s16
	s_addc_u32 s79, s79, s17
	s_add_i32 s33, s73, s3
	global_load_lds_dwordx4 v[212:213], off
	v_lshl_add_u64 v[214:215], s[78:79], 0, v[132:133]
	s_mov_b32 m0, s33
	v_lshl_add_u64 v[216:217], s[78:79], 0, v[136:137]
	global_load_lds_dwordx4 v[214:215], off
	s_add_i32 m0, s33, 0x2000
	v_lshl_add_u64 v[218:219], s[60:61], 0, v[130:131]
	global_load_lds_dwordx4 v[216:217], off
	s_mov_b32 m0, s39
	v_lshl_add_u64 v[220:221], s[60:61], 0, v[134:135]
	global_load_lds_dwordx4 v[218:219], off
	s_mov_b32 m0, s49
	s_nop 0
	global_load_lds_dwordx4 v[220:221], off
	s_waitcnt vmcnt(8)
	s_waitcnt lgkmcnt(0)
	s_barrier
; #define PG8_STAGE(bufoff, gbase, voff) do { _Pragma("unroll") for (int _i = 0; _i < 2; ++_i) \
;         __builtin_amdgcn_global_load_lds((const unsigned*)((const char*)(gbase) + (voff)[_i]), (PG8_LAS unsigned*)(lds + (bufoff) + ldsw + _i * 8192), 16, 0, 0); } while (0)
; #define PG8_LDA(dst, b, h) do { _Pragma("unroll") for (int m = 0; m < 4; ++m) _Pragma("unroll") for (int k = 0; k < 2; ++k) dst[m][k] = *(const PG8_LAS bf16x8*)(lds + PG8_SA(b, h) + aoff + m * 2048 + k * 1024); } while (0)
; #define PG8_LDB(dst, b, h) do { _Pragma("unroll") for (int n = 0; n < 2; ++n) _Pragma("unroll") for (int k = 0; k < 2; ++k) dst[n][k] = *(const PG8_LAS bf16x8*)(lds + PG8_SB(b, h) + boff + n * 2048 + k * 1024); } while (0)
; #define PG8_MMA(ai, bj, At, Bt) do { __builtin_amdgcn_s_setprio(1); _Pragma("unroll") for (int m = 0; m < 4; ++m) _Pragma("unroll") for (int n = 0; n < 2; ++n) _Pragma("unroll") for (int k = 0; k < 2; ++k) \
;         acc[ai][bj][m][n] = __builtin_amdgcn_mfma_f32_16x16x32_bf16(Bt[n][k], At[m][k], acc[ai][bj][m][n], 0, 0, 0); __builtin_amdgcn_s_setprio(0); } while (0)
; #define PG8_WAIT_V(n) asm volatile("s_waitcnt vmcnt(" #n ")" ::: "memory")
; #define PG8_WAIT_L(n) asm volatile("s_waitcnt lgkmcnt(" #n ")" ::: "memory")
; #define PG8_BAR __builtin_amdgcn_s_barrier()
; #define PG8_SCHED __builtin_amdgcn_sched_barrier(0)
; template <class Epi, class Sched, bool ALIGN_EPI = false, bool SP2 = false>
; __device__ __forceinline__ void gemm_phase(PG8_LAS unsigned char* lds, const Gemm g, const Sched& S, const Epi& E) {
;     ...
;             PG8_WAIT_V(8); PG8_WAIT_L(0); PG8_BAR; PG8_MMA(1, 0, At, B0); PG8_MMA(1, 1, At, B1); PG8_BAR; PG8_SCHED;
;             PG8_LDB(B0, 1, 0); PG8_LDB(B1, 1, 1); PG8_SCHED; PG8_LDA(At, 1, 0); PG8_STAGE(PG8_SA(0, 1), a2 + hstep, voffA);
;             PG8_WAIT_V(8); PG8_WAIT_L(0); PG8_BAR; PG8_MMA(0, 0, At, B0); PG8_MMA(0, 1, At, B1); PG8_BAR; PG8_SCHED;
	s_waitcnt lgkmcnt(0)
	v_mfma_f32_16x16x32_bf16 v[60:63], v[144:147], v[176:179], v[60:63]
	v_mfma_f32_16x16x32_bf16 v[56:59], v[152:155], v[176:179], v[56:59]
	v_mfma_f32_16x16x32_bf16 v[52:55], v[144:147], v[184:187], v[52:55]
	v_mfma_f32_16x16x32_bf16 v[48:51], v[152:155], v[184:187], v[48:51]
	v_mfma_f32_16x16x32_bf16 v[40:43], v[144:147], v[194:197], v[40:43]
	v_mfma_f32_16x16x32_bf16 v[32:35], v[152:155], v[194:197], v[32:35]
	v_mfma_f32_16x16x32_bf16 v[24:27], v[144:147], v[202:205], v[24:27]
	v_mfma_f32_16x16x32_bf16 v[16:19], v[152:155], v[202:205], v[16:19]
	v_mfma_f32_16x16x32_bf16 v[60:63], v[148:151], v[180:183], v[60:63]
	v_mfma_f32_16x16x32_bf16 v[56:59], v[156:159], v[180:183], v[56:59]
	v_mfma_f32_16x16x32_bf16 v[52:55], v[148:151], v[188:191], v[52:55]
	v_mfma_f32_16x16x32_bf16 v[48:51], v[156:159], v[188:191], v[48:51]
	v_mfma_f32_16x16x32_bf16 v[40:43], v[148:151], v[198:201], v[40:43]
	v_mfma_f32_16x16x32_bf16 v[32:35], v[156:159], v[198:201], v[32:35]
	v_mfma_f32_16x16x32_bf16 v[24:27], v[148:151], v[206:209], v[24:27]
	v_mfma_f32_16x16x32_bf16 v[16:19], v[156:159], v[206:209], v[16:19]
	v_mfma_f32_16x16x32_bf16 v[44:47], v[160:163], v[176:179], v[44:47]
	v_mfma_f32_16x16x32_bf16 v[36:39], v[168:171], v[176:179], v[36:39]
	v_mfma_f32_16x16x32_bf16 v[28:31], v[160:163], v[184:187], v[28:31]
	v_mfma_f32_16x16x32_bf16 v[20:23], v[168:171], v[184:187], v[20:23]
	v_mfma_f32_16x16x32_bf16 v[12:15], v[160:163], v[194:197], v[12:15]
	v_mfma_f32_16x16x32_bf16 v[8:11], v[168:171], v[194:197], v[8:11]
	v_mfma_f32_16x16x32_bf16 v[4:7], v[160:163], v[202:205], v[4:7]
	v_mfma_f32_16x16x32_bf16 v[0:3], v[168:171], v[202:205], v[0:3]
	v_mfma_f32_16x16x32_bf16 v[44:47], v[164:167], v[180:183], v[44:47]
	v_mfma_f32_16x16x32_bf16 v[36:39], v[172:175], v[180:183], v[36:39]
	v_mfma_f32_16x16x32_bf16 v[28:31], v[164:167], v[188:191], v[28:31]
	v_mfma_f32_16x16x32_bf16 v[20:23], v[172:175], v[188:191], v[20:23]
	v_mfma_f32_16x16x32_bf16 v[12:15], v[164:167], v[198:201], v[12:15]
	v_mfma_f32_16x16x32_bf16 v[8:11], v[172:175], v[198:201], v[8:11]
	v_mfma_f32_16x16x32_bf16 v[4:7], v[164:167], v[206:209], v[4:7]
	v_mfma_f32_16x16x32_bf16 v[0:3], v[172:175], v[206:209], v[0:3]
	s_barrier
	s_add_i32 s33, 0, 0x18000
	v_add_u32_e32 v128, s33, v193
	s_add_i32 s77, 0, 0x1c000
	ds_read_b128 v[144:147], v128
	ds_read_b128 v[148:151], v128 offset:1024
	ds_read_b128 v[152:155], v128 offset:2048
	ds_read_b128 v[156:159], v128 offset:3072
	v_add_u32_e32 v128, s77, v193
	ds_read_b128 v[160:163], v128
	ds_read_b128 v[164:167], v128 offset:1024
	ds_read_b128 v[168:171], v128 offset:2048
	ds_read_b128 v[172:175], v128 offset:3072
	s_add_u32 s60, s60, s16
	s_addc_u32 s61, s61, s17
	s_mov_b32 m0, s62
	v_lshl_add_u64 v[222:223], s[60:61], 0, v[130:131]
	ds_read_b128 v[176:179], v250 offset:32768
	ds_read_b128 v[180:183], v250 offset:33792
	ds_read_b128 v[184:187], v250 offset:34816
	ds_read_b128 v[188:191], v250 offset:35840
	ds_read_b128 v[194:197], v250 offset:36864
	ds_read_b128 v[198:201], v250 offset:37888
	ds_read_b128 v[202:205], v250 offset:38912
	ds_read_b128 v[206:209], v250 offset:39936
	global_load_lds_dwordx4 v[222:223], off
	v_lshl_add_u64 v[222:223], s[60:61], 0, v[134:135]
	s_mov_b32 m0, s63
	s_nop 0
	global_load_lds_dwordx4 v[222:223], off
	s_waitcnt vmcnt(8)
	s_waitcnt lgkmcnt(0)
	s_barrier
	s_waitcnt lgkmcnt(0)
	v_mfma_f32_16x16x32_bf16 v[124:127], v[144:147], v[176:179], v[124:127]
	v_mfma_f32_16x16x32_bf16 v[120:123], v[152:155], v[176:179], v[120:123]
	v_mfma_f32_16x16x32_bf16 v[116:119], v[144:147], v[184:187], v[116:119]
	v_mfma_f32_16x16x32_bf16 v[112:115], v[152:155], v[184:187], v[112:115]
	v_mfma_f32_16x16x32_bf16 v[104:107], v[144:147], v[194:197], v[104:107]
	v_mfma_f32_16x16x32_bf16 v[96:99], v[152:155], v[194:197], v[96:99]
	v_mfma_f32_16x16x32_bf16 v[88:91], v[144:147], v[202:205], v[88:91]
	v_mfma_f32_16x16x32_bf16 v[80:83], v[152:155], v[202:205], v[80:83]
	v_mfma_f32_16x16x32_bf16 v[124:127], v[148:151], v[180:183], v[124:127]
	v_mfma_f32_16x16x32_bf16 v[120:123], v[156:159], v[180:183], v[120:123]
	v_mfma_f32_16x16x32_bf16 v[116:119], v[148:151], v[188:191], v[116:119]
	v_mfma_f32_16x16x32_bf16 v[112:115], v[156:159], v[188:191], v[112:115]
	v_mfma_f32_16x16x32_bf16 v[104:107], v[148:151], v[198:201], v[104:107]
	v_mfma_f32_16x16x32_bf16 v[96:99], v[156:159], v[198:201], v[96:99]
	v_mfma_f32_16x16x32_bf16 v[88:91], v[148:151], v[206:209], v[88:91]
	v_mfma_f32_16x16x32_bf16 v[80:83], v[156:159], v[206:209], v[80:83]
	v_mfma_f32_16x16x32_bf16 v[108:111], v[160:163], v[176:179], v[108:111]
	v_mfma_f32_16x16x32_bf16 v[100:103], v[168:171], v[176:179], v[100:103]
	v_mfma_f32_16x16x32_bf16 v[92:95], v[160:163], v[184:187], v[92:95]
	v_mfma_f32_16x16x32_bf16 v[84:87], v[168:171], v[184:187], v[84:87]
	v_mfma_f32_16x16x32_bf16 v[76:79], v[160:163], v[194:197], v[76:79]
	v_mfma_f32_16x16x32_bf16 v[72:75], v[168:171], v[194:197], v[72:75]
	v_mfma_f32_16x16x32_bf16 v[68:71], v[160:163], v[202:205], v[68:71]
	v_mfma_f32_16x16x32_bf16 v[64:67], v[168:171], v[202:205], v[64:67]
	v_mfma_f32_16x16x32_bf16 v[108:111], v[164:167], v[180:183], v[108:111]
	v_mfma_f32_16x16x32_bf16 v[100:103], v[172:175], v[180:183], v[100:103]
	v_mfma_f32_16x16x32_bf16 v[92:95], v[164:167], v[188:191], v[92:95]
	v_mfma_f32_16x16x32_bf16 v[84:87], v[172:175], v[188:191], v[84:87]
	v_mfma_f32_16x16x32_bf16 v[76:79], v[164:167], v[198:201], v[76:79]
	v_mfma_f32_16x16x32_bf16 v[72:75], v[172:175], v[198:201], v[72:75]
	v_mfma_f32_16x16x32_bf16 v[68:71], v[164:167], v[206:209], v[68:71]
	v_mfma_f32_16x16x32_bf16 v[64:67], v[172:175], v[206:209], v[64:67]
	s_barrier
; #define PG8_STAGE(bufoff, gbase, voff) do { _Pragma("unroll") for (int _i = 0; _i < 2; ++_i) \
;         __builtin_amdgcn_global_load_lds((const unsigned*)((const char*)(gbase) + (voff)[_i]), (PG8_LAS unsigned*)(lds + (bufoff) + ldsw + _i * 8192), 16, 0, 0); } while (0)
; #define PG8_LDA(dst, b, h) do { _Pragma("unroll") for (int m = 0; m < 4; ++m) _Pragma("unroll") for (int k = 0; k < 2; ++k) dst[m][k] = *(const PG8_LAS bf16x8*)(lds + PG8_SA(b, h) + aoff + m * 2048 + k * 1024); } while (0)
; #define PG8_MMA(ai, bj, At, Bt) do { __builtin_amdgcn_s_setprio(1); _Pragma("unroll") for (int m = 0; m < 4; ++m) _Pragma("unroll") for (int n = 0; n < 2; ++n) _Pragma("unroll") for (int k = 0; k < 2; ++k) \
;         acc[ai][bj][m][n] = __builtin_amdgcn_mfma_f32_16x16x32_bf16(Bt[n][k], At[m][k], acc[ai][bj][m][n], 0, 0, 0); __builtin_amdgcn_s_setprio(0); } while (0)
; #define PG8_WAIT_V(n) asm volatile("s_waitcnt vmcnt(" #n ")" ::: "memory")
; #define PG8_WAIT_L(n) asm volatile("s_waitcnt lgkmcnt(" #n ")" ::: "memory")
; #define PG8_BAR __builtin_amdgcn_s_barrier()
; #define PG8_SCHED __builtin_amdgcn_sched_barrier(0)
; template <class Epi, class Sched, bool ALIGN_EPI = false, bool SP2 = false>
; __device__ __forceinline__ void gemm_phase(PG8_LAS unsigned char* lds, const Gemm g, const Sched& S, const Epi& E) {
;     ...
;             PG8_LDA(At, 1, 1); PG8_STAGE(PG8_SB(1, 0), b3, voffB); PG8_STAGE(PG8_SB(1, 1), b3 + hstep, voffB); PG8_STAGE(PG8_SA(1, 0), a3, voffA);
;             PG8_WAIT_V(8); PG8_WAIT_L(0); PG8_BAR; PG8_MMA(1, 0, At, B0); PG8_MMA(1, 1, At, B1); PG8_BAR; PG8_SCHED;
	s_add_i32 s33, s33, s3
	v_lshl_add_u64 v[210:211], v[210:211], 0, s[36:37]
	s_mov_b32 m0, s33
	ds_read_b128 v[176:179], v250 offset:49152
	ds_read_b128 v[180:183], v250 offset:50176
	ds_read_b128 v[184:187], v250 offset:51200
	ds_read_b128 v[188:191], v250 offset:52224
	ds_read_b128 v[194:197], v250 offset:53248
	ds_read_b128 v[198:201], v250 offset:54272
	ds_read_b128 v[202:205], v250 offset:55296
	ds_read_b128 v[206:209], v250 offset:56320
	global_load_lds_dwordx4 v[210:211], off
	v_lshl_add_u64 v[210:211], v[212:213], 0, s[36:37]
	s_add_i32 m0, s33, 0x2000
	s_add_i32 s33, s77, s3
	global_load_lds_dwordx4 v[210:211], off
	v_lshl_add_u64 v[210:211], v[214:215], 0, s[36:37]
	s_mov_b32 m0, s33
	s_nop 0
	global_load_lds_dwordx4 v[210:211], off
	v_lshl_add_u64 v[210:211], v[216:217], 0, s[36:37]
	s_add_i32 m0, s33, 0x2000
	s_nop 0
	global_load_lds_dwordx4 v[210:211], off
	v_lshl_add_u64 v[210:211], v[218:219], 0, s[36:37]
	s_mov_b32 m0, s64
	s_nop 0
	global_load_lds_dwordx4 v[210:211], off
	v_lshl_add_u64 v[210:211], v[220:221], 0, s[36:37]
	s_mov_b32 m0, s65
	s_nop 0
	global_load_lds_dwordx4 v[210:211], off
	s_waitcnt vmcnt(8)
	s_waitcnt lgkmcnt(0)
	s_barrier
	s_waitcnt lgkmcnt(0)
	v_mfma_f32_16x16x32_bf16 v[60:63], v[144:147], v[176:179], v[60:63]
	v_mfma_f32_16x16x32_bf16 v[56:59], v[152:155], v[176:179], v[56:59]
	v_mfma_f32_16x16x32_bf16 v[52:55], v[144:147], v[184:187], v[52:55]
	v_mfma_f32_16x16x32_bf16 v[48:51], v[152:155], v[184:187], v[48:51]
	v_mfma_f32_16x16x32_bf16 v[40:43], v[144:147], v[194:197], v[40:43]
	v_mfma_f32_16x16x32_bf16 v[32:35], v[152:155], v[194:197], v[32:35]
	v_mfma_f32_16x16x32_bf16 v[24:27], v[144:147], v[202:205], v[24:27]
	v_mfma_f32_16x16x32_bf16 v[16:19], v[152:155], v[202:205], v[16:19]
	v_mfma_f32_16x16x32_bf16 v[60:63], v[148:151], v[180:183], v[60:63]
	v_mfma_f32_16x16x32_bf16 v[56:59], v[156:159], v[180:183], v[56:59]
	v_mfma_f32_16x16x32_bf16 v[52:55], v[148:151], v[188:191], v[52:55]
	v_mfma_f32_16x16x32_bf16 v[48:51], v[156:159], v[188:191], v[48:51]
	v_mfma_f32_16x16x32_bf16 v[40:43], v[148:151], v[198:201], v[40:43]
	v_mfma_f32_16x16x32_bf16 v[32:35], v[156:159], v[198:201], v[32:35]
	v_mfma_f32_16x16x32_bf16 v[24:27], v[148:151], v[206:209], v[24:27]
	v_mfma_f32_16x16x32_bf16 v[16:19], v[156:159], v[206:209], v[16:19]
	v_mfma_f32_16x16x32_bf16 v[44:47], v[160:163], v[176:179], v[44:47]
	v_mfma_f32_16x16x32_bf16 v[36:39], v[168:171], v[176:179], v[36:39]
	v_mfma_f32_16x16x32_bf16 v[28:31], v[160:163], v[184:187], v[28:31]
	v_mfma_f32_16x16x32_bf16 v[20:23], v[168:171], v[184:187], v[20:23]
	v_mfma_f32_16x16x32_bf16 v[12:15], v[160:163], v[194:197], v[12:15]
	v_mfma_f32_16x16x32_bf16 v[8:11], v[168:171], v[194:197], v[8:11]
	v_mfma_f32_16x16x32_bf16 v[4:7], v[160:163], v[202:205], v[4:7]
	v_mfma_f32_16x16x32_bf16 v[0:3], v[168:171], v[202:205], v[0:3]
	v_mfma_f32_16x16x32_bf16 v[44:47], v[164:167], v[180:183], v[44:47]
	v_mfma_f32_16x16x32_bf16 v[36:39], v[172:175], v[180:183], v[36:39]
	v_mfma_f32_16x16x32_bf16 v[28:31], v[164:167], v[188:191], v[28:31]
	v_mfma_f32_16x16x32_bf16 v[20:23], v[172:175], v[188:191], v[20:23]
	v_mfma_f32_16x16x32_bf16 v[12:15], v[164:167], v[198:201], v[12:15]
	v_mfma_f32_16x16x32_bf16 v[8:11], v[172:175], v[198:201], v[8:11]
	v_mfma_f32_16x16x32_bf16 v[4:7], v[164:167], v[206:209], v[4:7]
	v_mfma_f32_16x16x32_bf16 v[0:3], v[172:175], v[206:209], v[0:3]
	s_barrier
	s_add_u32 s58, s58, 0x100
	s_addc_u32 s59, s59, 0
	s_add_u32 s4, s4, 0x100
	s_addc_u32 s5, s5, 0
	s_cmp_ge_i32 s38, s67
	s_mov_b32 s33, s38
	s_cbranch_scc0 .LBB0_368
;     __device__ __forceinline__ void operator()(const f32x4 (&acc)[2][2][4][2], const Unit& u, int wr, int wc, int fr, int fq) const {
;     ...
;                     v0 += acc[ai][bj][m][0] * alpha; v1 += acc[ai][bj][m][1] * alpha;
	v_pk_mul_f32 v[222:223], v[126:127], 0.5 op_sel_hi:[1,0]
	v_pk_mul_f32 v[224:225], v[124:125], 0.5 op_sel_hi:[1,0]
	v_pk_mul_f32 v[226:227], v[122:123], 0.5 op_sel_hi:[1,0]
	v_pk_mul_f32 v[228:229], v[120:121], 0.5 op_sel_hi:[1,0]
	v_pk_mul_f32 v[216:217], v[110:111], 0.5 op_sel_hi:[1,0]
	v_pk_mul_f32 v[214:215], v[108:109], 0.5 op_sel_hi:[1,0]
	v_pk_mul_f32 v[212:213], v[102:103], 0.5 op_sel_hi:[1,0]
	v_pk_mul_f32 v[208:209], v[100:101], 0.5 op_sel_hi:[1,0]
	v_pk_mul_f32 v[200:201], v[118:119], 0.5 op_sel_hi:[1,0]
	v_pk_mul_f32 v[198:199], v[116:117], 0.5 op_sel_hi:[1,0]
	v_pk_mul_f32 v[196:197], v[114:115], 0.5 op_sel_hi:[1,0]
	v_pk_mul_f32 v[194:195], v[112:113], 0.5 op_sel_hi:[1,0]
	v_pk_mul_f32 v[190:191], v[94:95], 0.5 op_sel_hi:[1,0]
	v_pk_mul_f32 v[188:189], v[92:93], 0.5 op_sel_hi:[1,0]
	v_pk_mul_f32 v[186:187], v[86:87], 0.5 op_sel_hi:[1,0]
	v_pk_mul_f32 v[184:185], v[84:85], 0.5 op_sel_hi:[1,0]
	v_pk_mul_f32 v[178:179], v[106:107], 0.5 op_sel_hi:[1,0]
	v_pk_mul_f32 v[176:177], v[104:105], 0.5 op_sel_hi:[1,0]
	v_pk_mul_f32 v[174:175], v[98:99], 0.5 op_sel_hi:[1,0]
	v_pk_mul_f32 v[172:173], v[96:97], 0.5 op_sel_hi:[1,0]
	v_pk_mul_f32 v[170:171], v[78:79], 0.5 op_sel_hi:[1,0]
	v_pk_mul_f32 v[168:169], v[76:77], 0.5 op_sel_hi:[1,0]
	v_pk_mul_f32 v[166:167], v[74:75], 0.5 op_sel_hi:[1,0]
	v_pk_mul_f32 v[164:165], v[72:73], 0.5 op_sel_hi:[1,0]
	v_pk_mul_f32 v[160:161], v[90:91], 0.5 op_sel_hi:[1,0]
	v_pk_mul_f32 v[158:159], v[88:89], 0.5 op_sel_hi:[1,0]
	v_pk_mul_f32 v[156:157], v[82:83], 0.5 op_sel_hi:[1,0]
	v_pk_mul_f32 v[154:155], v[80:81], 0.5 op_sel_hi:[1,0]
	v_pk_mul_f32 v[150:151], v[70:71], 0.5 op_sel_hi:[1,0]
	v_pk_mul_f32 v[148:149], v[68:69], 0.5 op_sel_hi:[1,0]
	v_pk_mul_f32 v[146:147], v[66:67], 0.5 op_sel_hi:[1,0]
	v_pk_mul_f32 v[144:145], v[64:65], 0.5 op_sel_hi:[1,0]
	v_pk_mul_f32 v[126:127], v[62:63], 0.5 op_sel_hi:[1,0]
	v_pk_mul_f32 v[124:125], v[60:61], 0.5 op_sel_hi:[1,0]
	v_pk_mul_f32 v[122:123], v[58:59], 0.5 op_sel_hi:[1,0]
	v_pk_mul_f32 v[120:121], v[56:57], 0.5 op_sel_hi:[1,0]
	v_pk_mul_f32 v[118:119], v[46:47], 0.5 op_sel_hi:[1,0]
	v_pk_mul_f32 v[116:117], v[44:45], 0.5 op_sel_hi:[1,0]
	v_pk_mul_f32 v[114:115], v[38:39], 0.5 op_sel_hi:[1,0]
	v_pk_mul_f32 v[112:113], v[36:37], 0.5 op_sel_hi:[1,0]
	v_pk_mul_f32 v[110:111], v[54:55], 0.5 op_sel_hi:[1,0]
	v_pk_mul_f32 v[108:109], v[52:53], 0.5 op_sel_hi:[1,0]
	v_pk_mul_f32 v[106:107], v[50:51], 0.5 op_sel_hi:[1,0]
	v_pk_mul_f32 v[104:105], v[48:49], 0.5 op_sel_hi:[1,0]
	v_pk_mul_f32 v[102:103], v[30:31], 0.5 op_sel_hi:[1,0]
	v_pk_mul_f32 v[100:101], v[28:29], 0.5 op_sel_hi:[1,0]
	v_pk_mul_f32 v[98:99], v[22:23], 0.5 op_sel_hi:[1,0]
	v_pk_mul_f32 v[96:97], v[20:21], 0.5 op_sel_hi:[1,0]
	v_pk_mul_f32 v[94:95], v[42:43], 0.5 op_sel_hi:[1,0]
	v_pk_mul_f32 v[92:93], v[40:41], 0.5 op_sel_hi:[1,0]
	v_pk_mul_f32 v[90:91], v[34:35], 0.5 op_sel_hi:[1,0]
	v_pk_mul_f32 v[88:89], v[32:33], 0.5 op_sel_hi:[1,0]
	v_pk_mul_f32 v[86:87], v[14:15], 0.5 op_sel_hi:[1,0]
	v_pk_mul_f32 v[84:85], v[12:13], 0.5 op_sel_hi:[1,0]
	v_pk_mul_f32 v[82:83], v[10:11], 0.5 op_sel_hi:[1,0]
	v_pk_mul_f32 v[80:81], v[8:9], 0.5 op_sel_hi:[1,0]
	v_pk_mul_f32 v[78:79], v[26:27], 0.5 op_sel_hi:[1,0]
	v_pk_mul_f32 v[76:77], v[24:25], 0.5 op_sel_hi:[1,0]
	v_pk_mul_f32 v[74:75], v[18:19], 0.5 op_sel_hi:[1,0]
	v_pk_mul_f32 v[72:73], v[16:17], 0.5 op_sel_hi:[1,0]
	v_pk_mul_f32 v[70:71], v[6:7], 0.5 op_sel_hi:[1,0]
	v_pk_mul_f32 v[68:69], v[4:5], 0.5 op_sel_hi:[1,0]
	v_pk_mul_f32 v[66:67], v[2:3], 0.5 op_sel_hi:[1,0]
	v_pk_mul_f32 v[64:65], v[0:1], 0.5 op_sel_hi:[1,0]

; #define PG8_STAGE(bufoff, gbase, voff) do { _Pragma("unroll") for (int _i = 0; _i < 2; ++_i) \
;         __builtin_amdgcn_global_load_lds((const unsigned*)((const char*)(gbase) + (voff)[_i]), (PG8_LAS unsigned*)(lds + (bufoff) + ldsw + _i * 8192), 16, 0, 0); } while (0)
; #define PG8_LDA(dst, b, h) do { _Pragma("unroll") for (int m = 0; m < 4; ++m) _Pragma("unroll") for (int k = 0; k < 2; ++k) dst[m][k] = *(const PG8_LAS bf16x8*)(lds + PG8_SA(b, h) + aoff + m * 2048 + k * 1024); } while (0)
; #define PG8_LDB(dst, b, h) do { _Pragma("unroll") for (int n = 0; n < 2; ++n) _Pragma("unroll") for (int k = 0; k < 2; ++k) dst[n][k] = *(const PG8_LAS bf16x8*)(lds + PG8_SB(b, h) + boff + n * 2048 + k * 1024); } while (0)
; #define PG8_MMA(ai, bj, At, Bt) do { __builtin_amdgcn_s_setprio(1); _Pragma("unroll") for (int m = 0; m < 4; ++m) _Pragma("unroll") for (int n = 0; n < 2; ++n) _Pragma("unroll") for (int k = 0; k < 2; ++k) \
;         acc[ai][bj][m][n] = __builtin_amdgcn_mfma_f32_16x16x32_bf16(Bt[n][k], At[m][k], acc[ai][bj][m][n], 0, 0, 0); __builtin_amdgcn_s_setprio(0); } while (0)
; #define PG8_WAIT_V(n) asm volatile("s_waitcnt vmcnt(" #n ")" ::: "memory")
; #define PG8_WAIT_L(n) asm volatile("s_waitcnt lgkmcnt(" #n ")" ::: "memory")
; #define PG8_BAR __builtin_amdgcn_s_barrier()
; #define PG8_SCHED __builtin_amdgcn_sched_barrier(0)
; template <class Epi, class Sched, bool ALIGN_EPI = false, bool SP2 = false>
; __device__ __forceinline__ void gemm_phase(PG8_LAS unsigned char* lds, const Gemm g, const Sched& S, const Epi& E) {
;     ...
;             PG8_LDB(B0, 0, 0); PG8_LDB(B1, 0, 1); PG8_SCHED; PG8_LDA(At, 0, 0); PG8_STAGE(PG8_SA(1, 1), a1 + hstep, voffA);
;             PG8_WAIT_V(8); PG8_WAIT_L(0); PG8_BAR; PG8_MMA(0, 0, At, B0); PG8_MMA(0, 1, At, B1); PG8_BAR; PG8_SCHED;
;             PG8_LDA(At, 0, 1); PG8_STAGE(PG8_SB(0, 0), b2, voffB); PG8_STAGE(PG8_SB(0, 1), b2 + hstep, voffB); PG8_STAGE(PG8_SA(0, 0), a2, voffA);
;             PG8_WAIT_V(8); PG8_WAIT_L(0); PG8_BAR; PG8_MMA(1, 0, At, B0); PG8_MMA(1, 1, At, B1); PG8_BAR; PG8_SCHED;
;             PG8_LDB(B0, 1, 0); PG8_LDB(B1, 1, 1); PG8_SCHED; PG8_LDA(At, 1, 0); PG8_STAGE(PG8_SA(0, 1), a2 + hstep, voffA);
.LBB0_473:
	ds_read_b128 v[150:153], v190
	ds_read_b128 v[154:157], v190 offset:1024
	ds_read_b128 v[158:161], v190 offset:2048
	ds_read_b128 v[162:165], v190 offset:3072
	ds_read_b128 v[166:169], v191
	ds_read_b128 v[170:173], v191 offset:1024
	ds_read_b128 v[174:177], v191 offset:2048
	ds_read_b128 v[178:181], v191 offset:3072
	s_add_i32 s15, s12, 2
	s_add_u32 s33, s10, 0x80
	s_addc_u32 s13, s11, 0
	s_cmp_eq_u32 s73, s12
	s_cselect_b32 s12, s60, s33
	s_cselect_b32 s13, s61, s13
	s_cselect_b32 s65, s63, s14
	s_cselect_b32 s64, s62, s5
	v_lshl_add_u64 v[186:187], s[10:11], 0, v[142:143]
	s_add_i32 m0, s66, 0xc000
	ds_read_b128 v[182:185], v193
	ds_read_b128 v[196:199], v193 offset:1024
	ds_read_b128 v[200:203], v193 offset:2048
	ds_read_b128 v[204:207], v193 offset:3072
	ds_read_b128 v[208:211], v193 offset:4096
	ds_read_b128 v[212:215], v193 offset:5120
	ds_read_b128 v[216:219], v193 offset:6144
	ds_read_b128 v[220:223], v193 offset:7168
	global_load_lds_dwordx4 v[186:187], off
	v_lshl_add_u64 v[186:187], s[10:11], 0, v[144:145]
	s_add_i32 m0, s66, 0xe000
	s_nop 0
	global_load_lds_dwordx4 v[186:187], off
	s_waitcnt vmcnt(8)
	s_waitcnt lgkmcnt(0)
	s_barrier
	s_waitcnt lgkmcnt(0)
	v_mfma_f32_16x16x32_bf16 v[124:127], v[150:153], v[182:185], v[124:127]
	v_mfma_f32_16x16x32_bf16 v[120:123], v[158:161], v[182:185], v[120:123]
	v_mfma_f32_16x16x32_bf16 v[108:111], v[150:153], v[200:203], v[108:111]
	v_mfma_f32_16x16x32_bf16 v[104:107], v[158:161], v[200:203], v[104:107]
	v_mfma_f32_16x16x32_bf16 v[92:95], v[150:153], v[208:211], v[92:95]
	v_mfma_f32_16x16x32_bf16 v[88:91], v[158:161], v[208:211], v[88:91]
	v_mfma_f32_16x16x32_bf16 v[76:79], v[150:153], v[216:219], v[76:79]
	v_mfma_f32_16x16x32_bf16 v[72:75], v[158:161], v[216:219], v[72:75]
	v_mfma_f32_16x16x32_bf16 v[124:127], v[154:157], v[196:199], v[124:127]
	v_mfma_f32_16x16x32_bf16 v[120:123], v[162:165], v[196:199], v[120:123]
	v_mfma_f32_16x16x32_bf16 v[108:111], v[154:157], v[204:207], v[108:111]
	v_mfma_f32_16x16x32_bf16 v[104:107], v[162:165], v[204:207], v[104:107]
	v_mfma_f32_16x16x32_bf16 v[92:95], v[154:157], v[212:215], v[92:95]
	v_mfma_f32_16x16x32_bf16 v[88:91], v[162:165], v[212:215], v[88:91]
	v_mfma_f32_16x16x32_bf16 v[76:79], v[154:157], v[220:223], v[76:79]
	v_mfma_f32_16x16x32_bf16 v[72:75], v[162:165], v[220:223], v[72:75]
	v_mfma_f32_16x16x32_bf16 v[116:119], v[166:169], v[182:185], v[116:119]
	v_mfma_f32_16x16x32_bf16 v[112:115], v[174:177], v[182:185], v[112:115]
	v_mfma_f32_16x16x32_bf16 v[100:103], v[166:169], v[200:203], v[100:103]
	v_mfma_f32_16x16x32_bf16 v[96:99], v[174:177], v[200:203], v[96:99]
	v_mfma_f32_16x16x32_bf16 v[84:87], v[166:169], v[208:211], v[84:87]
	v_mfma_f32_16x16x32_bf16 v[80:83], v[174:177], v[208:211], v[80:83]
	v_mfma_f32_16x16x32_bf16 v[68:71], v[166:169], v[216:219], v[68:71]
	v_mfma_f32_16x16x32_bf16 v[64:67], v[174:177], v[216:219], v[64:67]
	v_mfma_f32_16x16x32_bf16 v[116:119], v[170:173], v[196:199], v[116:119]
	v_mfma_f32_16x16x32_bf16 v[112:115], v[178:181], v[196:199], v[112:115]
	v_mfma_f32_16x16x32_bf16 v[100:103], v[170:173], v[204:207], v[100:103]
	v_mfma_f32_16x16x32_bf16 v[96:99], v[178:181], v[204:207], v[96:99]
	v_mfma_f32_16x16x32_bf16 v[84:87], v[170:173], v[212:215], v[84:87]
	v_mfma_f32_16x16x32_bf16 v[80:83], v[178:181], v[212:215], v[80:83]
	v_mfma_f32_16x16x32_bf16 v[68:71], v[170:173], v[220:223], v[68:71]
	v_mfma_f32_16x16x32_bf16 v[64:67], v[178:181], v[220:223], v[64:67]
	s_barrier
	s_add_i32 s33, s78, s49
	v_lshl_add_u64 v[186:187], s[64:65], 0, v[132:133]
	s_mov_b32 m0, s33
	ds_read_b128 v[182:185], v193 offset:16384
	ds_read_b128 v[196:199], v193 offset:17408
	ds_read_b128 v[200:203], v193 offset:18432
	ds_read_b128 v[204:207], v193 offset:19456
	ds_read_b128 v[208:211], v193 offset:20480
	ds_read_b128 v[212:215], v193 offset:21504
	ds_read_b128 v[216:219], v193 offset:22528
	ds_read_b128 v[220:223], v193 offset:23552
	global_load_lds_dwordx4 v[186:187], off
	s_add_i32 m0, s33, 0x2000
	v_lshl_add_u64 v[224:225], s[64:65], 0, v[136:137]
	s_add_u32 s64, s64, s18
	s_addc_u32 s65, s65, s19
	s_add_i32 s33, s79, s49
	global_load_lds_dwordx4 v[224:225], off
	v_lshl_add_u64 v[226:227], s[64:65], 0, v[132:133]
	s_mov_b32 m0, s33
	v_lshl_add_u64 v[228:229], s[64:65], 0, v[136:137]
	global_load_lds_dwordx4 v[226:227], off
	s_add_i32 m0, s33, 0x2000
	v_lshl_add_u64 v[230:231], s[12:13], 0, v[130:131]
	global_load_lds_dwordx4 v[228:229], off
	s_mov_b32 m0, s66
	v_lshl_add_u64 v[232:233], s[12:13], 0, v[134:135]
	global_load_lds_dwordx4 v[230:231], off
	s_mov_b32 m0, s67
	s_nop 0
	global_load_lds_dwordx4 v[232:233], off
	s_waitcnt vmcnt(8)
	s_waitcnt lgkmcnt(0)
	s_barrier
; #define PG8_STAGE(bufoff, gbase, voff) do { _Pragma("unroll") for (int _i = 0; _i < 2; ++_i) \
;         __builtin_amdgcn_global_load_lds((const unsigned*)((const char*)(gbase) + (voff)[_i]), (PG8_LAS unsigned*)(lds + (bufoff) + ldsw + _i * 8192), 16, 0, 0); } while (0)
; #define PG8_LDA(dst, b, h) do { _Pragma("unroll") for (int m = 0; m < 4; ++m) _Pragma("unroll") for (int k = 0; k < 2; ++k) dst[m][k] = *(const PG8_LAS bf16x8*)(lds + PG8_SA(b, h) + aoff + m * 2048 + k * 1024); } while (0)
; #define PG8_LDB(dst, b, h) do { _Pragma("unroll") for (int n = 0; n < 2; ++n) _Pragma("unroll") for (int k = 0; k < 2; ++k) dst[n][k] = *(const PG8_LAS bf16x8*)(lds + PG8_SB(b, h) + boff + n * 2048 + k * 1024); } while (0)
; #define PG8_MMA(ai, bj, At, Bt) do { __builtin_amdgcn_s_setprio(1); _Pragma("unroll") for (int m = 0; m < 4; ++m) _Pragma("unroll") for (int n = 0; n < 2; ++n) _Pragma("unroll") for (int k = 0; k < 2; ++k) \
;         acc[ai][bj][m][n] = __builtin_amdgcn_mfma_f32_16x16x32_bf16(Bt[n][k], At[m][k], acc[ai][bj][m][n], 0, 0, 0); __builtin_amdgcn_s_setprio(0); } while (0)
; #define PG8_WAIT_V(n) asm volatile("s_waitcnt vmcnt(" #n ")" ::: "memory")
; #define PG8_WAIT_L(n) asm volatile("s_waitcnt lgkmcnt(" #n ")" ::: "memory")
; #define PG8_BAR __builtin_amdgcn_s_barrier()
; #define PG8_SCHED __builtin_amdgcn_sched_barrier(0)
; template <class Epi, class Sched, bool ALIGN_EPI = false, bool SP2 = false>
; __device__ __forceinline__ void gemm_phase(PG8_LAS unsigned char* lds, const Gemm g, const Sched& S, const Epi& E) {
;     ...
;             PG8_WAIT_V(8); PG8_WAIT_L(0); PG8_BAR; PG8_MMA(1, 0, At, B0); PG8_MMA(1, 1, At, B1); PG8_BAR; PG8_SCHED;
;             PG8_LDB(B0, 1, 0); PG8_LDB(B1, 1, 1); PG8_SCHED; PG8_LDA(At, 1, 0); PG8_STAGE(PG8_SA(0, 1), a2 + hstep, voffA);
;             PG8_WAIT_V(8); PG8_WAIT_L(0); PG8_BAR; PG8_MMA(0, 0, At, B0); PG8_MMA(0, 1, At, B1); PG8_BAR; PG8_SCHED;
	s_waitcnt lgkmcnt(0)
	v_mfma_f32_16x16x32_bf16 v[60:63], v[150:153], v[182:185], v[60:63]
	v_mfma_f32_16x16x32_bf16 v[56:59], v[158:161], v[182:185], v[56:59]
	v_mfma_f32_16x16x32_bf16 v[44:47], v[150:153], v[200:203], v[44:47]
	v_mfma_f32_16x16x32_bf16 v[40:43], v[158:161], v[200:203], v[40:43]
	v_mfma_f32_16x16x32_bf16 v[28:31], v[150:153], v[208:211], v[28:31]
	v_mfma_f32_16x16x32_bf16 v[24:27], v[158:161], v[208:211], v[24:27]
	v_mfma_f32_16x16x32_bf16 v[12:15], v[150:153], v[216:219], v[12:15]
	v_mfma_f32_16x16x32_bf16 v[8:11], v[158:161], v[216:219], v[8:11]
	v_mfma_f32_16x16x32_bf16 v[60:63], v[154:157], v[196:199], v[60:63]
	v_mfma_f32_16x16x32_bf16 v[56:59], v[162:165], v[196:199], v[56:59]
	v_mfma_f32_16x16x32_bf16 v[44:47], v[154:157], v[204:207], v[44:47]
	v_mfma_f32_16x16x32_bf16 v[40:43], v[162:165], v[204:207], v[40:43]
	v_mfma_f32_16x16x32_bf16 v[28:31], v[154:157], v[212:215], v[28:31]
	v_mfma_f32_16x16x32_bf16 v[24:27], v[162:165], v[212:215], v[24:27]
	v_mfma_f32_16x16x32_bf16 v[12:15], v[154:157], v[220:223], v[12:15]
	v_mfma_f32_16x16x32_bf16 v[8:11], v[162:165], v[220:223], v[8:11]
	v_mfma_f32_16x16x32_bf16 v[52:55], v[166:169], v[182:185], v[52:55]
	v_mfma_f32_16x16x32_bf16 v[48:51], v[174:177], v[182:185], v[48:51]
	v_mfma_f32_16x16x32_bf16 v[36:39], v[166:169], v[200:203], v[36:39]
	v_mfma_f32_16x16x32_bf16 v[32:35], v[174:177], v[200:203], v[32:35]
	v_mfma_f32_16x16x32_bf16 v[20:23], v[166:169], v[208:211], v[20:23]
	v_mfma_f32_16x16x32_bf16 v[16:19], v[174:177], v[208:211], v[16:19]
	v_mfma_f32_16x16x32_bf16 v[4:7], v[166:169], v[216:219], v[4:7]
	v_mfma_f32_16x16x32_bf16 v[0:3], v[174:177], v[216:219], v[0:3]
	v_mfma_f32_16x16x32_bf16 v[52:55], v[170:173], v[196:199], v[52:55]
	v_mfma_f32_16x16x32_bf16 v[48:51], v[178:181], v[196:199], v[48:51]
	v_mfma_f32_16x16x32_bf16 v[36:39], v[170:173], v[204:207], v[36:39]
	v_mfma_f32_16x16x32_bf16 v[32:35], v[178:181], v[204:207], v[32:35]
	v_mfma_f32_16x16x32_bf16 v[20:23], v[170:173], v[212:215], v[20:23]
	v_mfma_f32_16x16x32_bf16 v[16:19], v[178:181], v[212:215], v[16:19]
	v_mfma_f32_16x16x32_bf16 v[4:7], v[170:173], v[220:223], v[4:7]
	v_mfma_f32_16x16x32_bf16 v[0:3], v[178:181], v[220:223], v[0:3]
	s_barrier
	s_add_i32 s33, 0, 0x18000
	v_add_u32_e32 v128, s33, v188
	s_add_i32 s38, 0, 0x1c000
	ds_read_b128 v[150:153], v128
	ds_read_b128 v[154:157], v128 offset:1024
	ds_read_b128 v[158:161], v128 offset:2048
	ds_read_b128 v[162:165], v128 offset:3072
	v_add_u32_e32 v128, s38, v188
	ds_read_b128 v[166:169], v128
	ds_read_b128 v[170:173], v128 offset:1024
	ds_read_b128 v[174:177], v128 offset:2048
	ds_read_b128 v[178:181], v128 offset:3072
	s_add_u32 s12, s12, s18
	s_addc_u32 s13, s13, s19
	s_mov_b32 m0, s68
	v_lshl_add_u64 v[234:235], s[12:13], 0, v[130:131]
	ds_read_b128 v[182:185], v193 offset:32768
	ds_read_b128 v[196:199], v193 offset:33792
	ds_read_b128 v[200:203], v193 offset:34816
	ds_read_b128 v[204:207], v193 offset:35840
	ds_read_b128 v[208:211], v193 offset:36864
	ds_read_b128 v[212:215], v193 offset:37888
	ds_read_b128 v[216:219], v193 offset:38912
	ds_read_b128 v[220:223], v193 offset:39936
	global_load_lds_dwordx4 v[234:235], off
	v_lshl_add_u64 v[234:235], s[12:13], 0, v[134:135]
	s_mov_b32 m0, s69
	s_nop 0
	global_load_lds_dwordx4 v[234:235], off
	s_waitcnt vmcnt(8)
	s_waitcnt lgkmcnt(0)
	s_barrier
	s_waitcnt lgkmcnt(0)
	v_mfma_f32_16x16x32_bf16 v[124:127], v[150:153], v[182:185], v[124:127]
	v_mfma_f32_16x16x32_bf16 v[120:123], v[158:161], v[182:185], v[120:123]
	v_mfma_f32_16x16x32_bf16 v[108:111], v[150:153], v[200:203], v[108:111]
	v_mfma_f32_16x16x32_bf16 v[104:107], v[158:161], v[200:203], v[104:107]
	v_mfma_f32_16x16x32_bf16 v[92:95], v[150:153], v[208:211], v[92:95]
	v_mfma_f32_16x16x32_bf16 v[88:91], v[158:161], v[208:211], v[88:91]
	v_mfma_f32_16x16x32_bf16 v[76:79], v[150:153], v[216:219], v[76:79]
	v_mfma_f32_16x16x32_bf16 v[72:75], v[158:161], v[216:219], v[72:75]
	v_mfma_f32_16x16x32_bf16 v[124:127], v[154:157], v[196:199], v[124:127]
	v_mfma_f32_16x16x32_bf16 v[120:123], v[162:165], v[196:199], v[120:123]
	v_mfma_f32_16x16x32_bf16 v[108:111], v[154:157], v[204:207], v[108:111]
	v_mfma_f32_16x16x32_bf16 v[104:107], v[162:165], v[204:207], v[104:107]
	v_mfma_f32_16x16x32_bf16 v[92:95], v[154:157], v[212:215], v[92:95]
	v_mfma_f32_16x16x32_bf16 v[88:91], v[162:165], v[212:215], v[88:91]
	v_mfma_f32_16x16x32_bf16 v[76:79], v[154:157], v[220:223], v[76:79]
	v_mfma_f32_16x16x32_bf16 v[72:75], v[162:165], v[220:223], v[72:75]
	v_mfma_f32_16x16x32_bf16 v[116:119], v[166:169], v[182:185], v[116:119]
	v_mfma_f32_16x16x32_bf16 v[112:115], v[174:177], v[182:185], v[112:115]
	v_mfma_f32_16x16x32_bf16 v[100:103], v[166:169], v[200:203], v[100:103]
	v_mfma_f32_16x16x32_bf16 v[96:99], v[174:177], v[200:203], v[96:99]
	v_mfma_f32_16x16x32_bf16 v[84:87], v[166:169], v[208:211], v[84:87]
	v_mfma_f32_16x16x32_bf16 v[80:83], v[174:177], v[208:211], v[80:83]
	v_mfma_f32_16x16x32_bf16 v[68:71], v[166:169], v[216:219], v[68:71]
	v_mfma_f32_16x16x32_bf16 v[64:67], v[174:177], v[216:219], v[64:67]
	v_mfma_f32_16x16x32_bf16 v[116:119], v[170:173], v[196:199], v[116:119]
	v_mfma_f32_16x16x32_bf16 v[112:115], v[178:181], v[196:199], v[112:115]
	v_mfma_f32_16x16x32_bf16 v[100:103], v[170:173], v[204:207], v[100:103]
	v_mfma_f32_16x16x32_bf16 v[96:99], v[178:181], v[204:207], v[96:99]
	v_mfma_f32_16x16x32_bf16 v[84:87], v[170:173], v[212:215], v[84:87]
	v_mfma_f32_16x16x32_bf16 v[80:83], v[178:181], v[212:215], v[80:83]
	v_mfma_f32_16x16x32_bf16 v[68:71], v[170:173], v[220:223], v[68:71]
	v_mfma_f32_16x16x32_bf16 v[64:67], v[178:181], v[220:223], v[64:67]
	s_barrier
; #define PG8_STAGE(bufoff, gbase, voff) do { _Pragma("unroll") for (int _i = 0; _i < 2; ++_i) \
;         __builtin_amdgcn_global_load_lds((const unsigned*)((const char*)(gbase) + (voff)[_i]), (PG8_LAS unsigned*)(lds + (bufoff) + ldsw + _i * 8192), 16, 0, 0); } while (0)
; #define PG8_LDA(dst, b, h) do { _Pragma("unroll") for (int m = 0; m < 4; ++m) _Pragma("unroll") for (int k = 0; k < 2; ++k) dst[m][k] = *(const PG8_LAS bf16x8*)(lds + PG8_SA(b, h) + aoff + m * 2048 + k * 1024); } while (0)
; #define PG8_MMA(ai, bj, At, Bt) do { __builtin_amdgcn_s_setprio(1); _Pragma("unroll") for (int m = 0; m < 4; ++m) _Pragma("unroll") for (int n = 0; n < 2; ++n) _Pragma("unroll") for (int k = 0; k < 2; ++k) \
;         acc[ai][bj][m][n] = __builtin_amdgcn_mfma_f32_16x16x32_bf16(Bt[n][k], At[m][k], acc[ai][bj][m][n], 0, 0, 0); __builtin_amdgcn_s_setprio(0); } while (0)
; #define PG8_WAIT_V(n) asm volatile("s_waitcnt vmcnt(" #n ")" ::: "memory")
; #define PG8_WAIT_L(n) asm volatile("s_waitcnt lgkmcnt(" #n ")" ::: "memory")
; #define PG8_BAR __builtin_amdgcn_s_barrier()
; #define PG8_SCHED __builtin_amdgcn_sched_barrier(0)
; template <class Epi, class Sched, bool ALIGN_EPI = false, bool SP2 = false>
; __device__ __forceinline__ void gemm_phase(PG8_LAS unsigned char* lds, const Gemm g, const Sched& S, const Epi& E) {
;     ...
;             PG8_LDA(At, 1, 1); PG8_STAGE(PG8_SB(1, 0), b3, voffB); PG8_STAGE(PG8_SB(1, 1), b3 + hstep, voffB); PG8_STAGE(PG8_SA(1, 0), a3, voffA);
;             PG8_WAIT_V(8); PG8_WAIT_L(0); PG8_BAR; PG8_MMA(1, 0, At, B0); PG8_MMA(1, 1, At, B1); PG8_BAR; PG8_SCHED;
	s_add_i32 s12, s33, s49
	v_lshl_add_u64 v[186:187], v[186:187], 0, s[42:43]
	s_mov_b32 m0, s12
	ds_read_b128 v[182:185], v193 offset:49152
	ds_read_b128 v[196:199], v193 offset:50176
	ds_read_b128 v[200:203], v193 offset:51200
	ds_read_b128 v[204:207], v193 offset:52224
	ds_read_b128 v[208:211], v193 offset:53248
	ds_read_b128 v[212:215], v193 offset:54272
	ds_read_b128 v[216:219], v193 offset:55296
	ds_read_b128 v[220:223], v193 offset:56320
	global_load_lds_dwordx4 v[186:187], off
	v_lshl_add_u64 v[186:187], v[224:225], 0, s[42:43]
	s_add_i32 m0, s12, 0x2000
	s_add_i32 s12, s38, s49
	global_load_lds_dwordx4 v[186:187], off
	v_lshl_add_u64 v[186:187], v[226:227], 0, s[42:43]
	s_mov_b32 m0, s12
	s_nop 0
	global_load_lds_dwordx4 v[186:187], off
	v_lshl_add_u64 v[186:187], v[228:229], 0, s[42:43]
	s_add_i32 m0, s12, 0x2000
	s_nop 0
	global_load_lds_dwordx4 v[186:187], off
	v_lshl_add_u64 v[186:187], v[230:231], 0, s[42:43]
	s_mov_b32 m0, s70
	s_nop 0
	global_load_lds_dwordx4 v[186:187], off
	v_lshl_add_u64 v[186:187], v[232:233], 0, s[42:43]
	s_mov_b32 m0, s71
	s_nop 0
	global_load_lds_dwordx4 v[186:187], off
	s_waitcnt vmcnt(8)
	s_waitcnt lgkmcnt(0)
	s_barrier
	s_waitcnt lgkmcnt(0)
	v_mfma_f32_16x16x32_bf16 v[60:63], v[150:153], v[182:185], v[60:63]
	v_mfma_f32_16x16x32_bf16 v[56:59], v[158:161], v[182:185], v[56:59]
	v_mfma_f32_16x16x32_bf16 v[44:47], v[150:153], v[200:203], v[44:47]
	v_mfma_f32_16x16x32_bf16 v[40:43], v[158:161], v[200:203], v[40:43]
	v_mfma_f32_16x16x32_bf16 v[28:31], v[150:153], v[208:211], v[28:31]
	v_mfma_f32_16x16x32_bf16 v[24:27], v[158:161], v[208:211], v[24:27]
	v_mfma_f32_16x16x32_bf16 v[12:15], v[150:153], v[216:219], v[12:15]
	v_mfma_f32_16x16x32_bf16 v[8:11], v[158:161], v[216:219], v[8:11]
	v_mfma_f32_16x16x32_bf16 v[60:63], v[154:157], v[196:199], v[60:63]
	v_mfma_f32_16x16x32_bf16 v[56:59], v[162:165], v[196:199], v[56:59]
	v_mfma_f32_16x16x32_bf16 v[44:47], v[154:157], v[204:207], v[44:47]
	v_mfma_f32_16x16x32_bf16 v[40:43], v[162:165], v[204:207], v[40:43]
	v_mfma_f32_16x16x32_bf16 v[28:31], v[154:157], v[212:215], v[28:31]
	v_mfma_f32_16x16x32_bf16 v[24:27], v[162:165], v[212:215], v[24:27]
	v_mfma_f32_16x16x32_bf16 v[12:15], v[154:157], v[220:223], v[12:15]
	v_mfma_f32_16x16x32_bf16 v[8:11], v[162:165], v[220:223], v[8:11]
	v_mfma_f32_16x16x32_bf16 v[52:55], v[166:169], v[182:185], v[52:55]
	v_mfma_f32_16x16x32_bf16 v[48:51], v[174:177], v[182:185], v[48:51]
	v_mfma_f32_16x16x32_bf16 v[36:39], v[166:169], v[200:203], v[36:39]
	v_mfma_f32_16x16x32_bf16 v[32:35], v[174:177], v[200:203], v[32:35]
	v_mfma_f32_16x16x32_bf16 v[20:23], v[166:169], v[208:211], v[20:23]
	v_mfma_f32_16x16x32_bf16 v[16:19], v[174:177], v[208:211], v[16:19]
	v_mfma_f32_16x16x32_bf16 v[4:7], v[166:169], v[216:219], v[4:7]
	v_mfma_f32_16x16x32_bf16 v[0:3], v[174:177], v[216:219], v[0:3]
	v_mfma_f32_16x16x32_bf16 v[52:55], v[170:173], v[196:199], v[52:55]
	v_mfma_f32_16x16x32_bf16 v[48:51], v[178:181], v[196:199], v[48:51]
	v_mfma_f32_16x16x32_bf16 v[36:39], v[170:173], v[204:207], v[36:39]
	v_mfma_f32_16x16x32_bf16 v[32:35], v[178:181], v[204:207], v[32:35]
	v_mfma_f32_16x16x32_bf16 v[20:23], v[170:173], v[212:215], v[20:23]
	v_mfma_f32_16x16x32_bf16 v[16:19], v[178:181], v[212:215], v[16:19]
	v_mfma_f32_16x16x32_bf16 v[4:7], v[170:173], v[220:223], v[4:7]
	v_mfma_f32_16x16x32_bf16 v[0:3], v[178:181], v[220:223], v[0:3]
	s_barrier
	s_add_u32 s10, s10, 0x100
	s_addc_u32 s11, s11, 0
	s_add_u32 s5, s5, 0x100
	s_addc_u32 s14, s14, 0
	s_cmp_ge_i32 s15, s72
	s_mov_b32 s12, s15
	s_cbranch_scc0 .LBB0_473

; #define PG8_STAGE(bufoff, gbase, voff) do { _Pragma("unroll") for (int _i = 0; _i < 2; ++_i) \
;         __builtin_amdgcn_global_load_lds((const unsigned*)((const char*)(gbase) + (voff)[_i]), (PG8_LAS unsigned*)(lds + (bufoff) + ldsw + _i * 8192), 16, 0, 0); } while (0)
; #define PG8_LDA(dst, b, h) do { _Pragma("unroll") for (int m = 0; m < 4; ++m) _Pragma("unroll") for (int k = 0; k < 2; ++k) dst[m][k] = *(const PG8_LAS bf16x8*)(lds + PG8_SA(b, h) + aoff + m * 2048 + k * 1024); } while (0)
; #define PG8_LDB(dst, b, h) do { _Pragma("unroll") for (int n = 0; n < 2; ++n) _Pragma("unroll") for (int k = 0; k < 2; ++k) dst[n][k] = *(const PG8_LAS bf16x8*)(lds + PG8_SB(b, h) + boff + n * 2048 + k * 1024); } while (0)
; #define PG8_MMA(ai, bj, At, Bt) do { __builtin_amdgcn_s_setprio(1); _Pragma("unroll") for (int m = 0; m < 4; ++m) _Pragma("unroll") for (int n = 0; n < 2; ++n) _Pragma("unroll") for (int k = 0; k < 2; ++k) \
;         acc[ai][bj][m][n] = __builtin_amdgcn_mfma_f32_16x16x32_bf16(Bt[n][k], At[m][k], acc[ai][bj][m][n], 0, 0, 0); __builtin_amdgcn_s_setprio(0); } while (0)
; #define PG8_WAIT_V(n) asm volatile("s_waitcnt vmcnt(" #n ")" ::: "memory")
; #define PG8_WAIT_L(n) asm volatile("s_waitcnt lgkmcnt(" #n ")" ::: "memory")
; #define PG8_BAR __builtin_amdgcn_s_barrier()
; #define PG8_SCHED __builtin_amdgcn_sched_barrier(0)
; template <class Epi, class Sched, bool ALIGN_EPI = false, bool SP2 = false>
; __device__ __forceinline__ void gemm_phase(PG8_LAS unsigned char* lds, const Gemm g, const Sched& S, const Epi& E) {
;     ...
;             PG8_LDB(B0, 0, 0); PG8_LDB(B1, 0, 1); PG8_SCHED; PG8_LDA(At, 0, 0); PG8_STAGE(PG8_SA(1, 1), a1 + hstep, voffA);
;             PG8_WAIT_V(8); PG8_WAIT_L(0); PG8_BAR; PG8_MMA(0, 0, At, B0); PG8_MMA(0, 1, At, B1); PG8_BAR; PG8_SCHED;
;             PG8_LDA(At, 0, 1); PG8_STAGE(PG8_SB(0, 0), b2, voffB); PG8_STAGE(PG8_SB(0, 1), b2 + hstep, voffB); PG8_STAGE(PG8_SA(0, 0), a2, voffA);
;             PG8_WAIT_V(8); PG8_WAIT_L(0); PG8_BAR; PG8_MMA(1, 0, At, B0); PG8_MMA(1, 1, At, B1); PG8_BAR; PG8_SCHED;
;             PG8_LDB(B0, 1, 0); PG8_LDB(B1, 1, 1); PG8_SCHED; PG8_LDA(At, 1, 0); PG8_STAGE(PG8_SA(0, 1), a2 + hstep, voffA);
.LBB0_633:
	ds_read_b128 v[150:153], v144
	ds_read_b128 v[154:157], v144 offset:1024
	ds_read_b128 v[158:161], v144 offset:2048
	ds_read_b128 v[162:165], v144 offset:3072
	ds_read_b128 v[166:169], v145
	ds_read_b128 v[170:173], v145 offset:1024
	ds_read_b128 v[174:177], v145 offset:2048
	ds_read_b128 v[178:181], v145 offset:3072
	s_add_i32 s90, s60, 2
	s_add_u32 s91, s58, 0x80
	s_addc_u32 s61, s59, 0
	s_cmp_eq_u32 s72, s60
	s_cselect_b32 s60, s42, s91
	s_cselect_b32 s61, s43, s61
	s_cselect_b32 s93, s57, s89
	s_cselect_b32 s92, s56, s33
	s_mov_b32 m0, s74
	v_lshl_add_u64 v[190:191], s[58:59], 0, v[140:141]
	ds_read_b128 v[182:185], v146
	ds_read_b128 v[186:189], v146 offset:1024
	ds_read_b128 v[194:197], v146 offset:2048
	ds_read_b128 v[198:201], v146 offset:3072
	ds_read_b128 v[202:205], v146 offset:4096
	ds_read_b128 v[206:209], v146 offset:5120
	ds_read_b128 v[210:213], v146 offset:6144
	ds_read_b128 v[214:217], v146 offset:7168
	global_load_lds_dwordx4 v[190:191], off
	v_lshl_add_u64 v[190:191], s[58:59], 0, v[142:143]
	s_mov_b32 m0, s75
	s_nop 0
	global_load_lds_dwordx4 v[190:191], off
	s_waitcnt vmcnt(8)
	s_waitcnt lgkmcnt(0)
	s_barrier
	s_waitcnt lgkmcnt(0)
	v_mfma_f32_16x16x32_bf16 v[124:127], v[150:153], v[182:185], v[124:127]
	v_mfma_f32_16x16x32_bf16 v[120:123], v[158:161], v[182:185], v[120:123]
	v_mfma_f32_16x16x32_bf16 v[108:111], v[150:153], v[194:197], v[108:111]
	v_mfma_f32_16x16x32_bf16 v[104:107], v[158:161], v[194:197], v[104:107]
	v_mfma_f32_16x16x32_bf16 v[92:95], v[150:153], v[202:205], v[92:95]
	v_mfma_f32_16x16x32_bf16 v[88:91], v[158:161], v[202:205], v[88:91]
	v_mfma_f32_16x16x32_bf16 v[76:79], v[150:153], v[210:213], v[76:79]
	v_mfma_f32_16x16x32_bf16 v[72:75], v[158:161], v[210:213], v[72:75]
	v_mfma_f32_16x16x32_bf16 v[124:127], v[154:157], v[186:189], v[124:127]
	v_mfma_f32_16x16x32_bf16 v[120:123], v[162:165], v[186:189], v[120:123]
	v_mfma_f32_16x16x32_bf16 v[108:111], v[154:157], v[198:201], v[108:111]
	v_mfma_f32_16x16x32_bf16 v[104:107], v[162:165], v[198:201], v[104:107]
	v_mfma_f32_16x16x32_bf16 v[92:95], v[154:157], v[206:209], v[92:95]
	v_mfma_f32_16x16x32_bf16 v[88:91], v[162:165], v[206:209], v[88:91]
	v_mfma_f32_16x16x32_bf16 v[76:79], v[154:157], v[214:217], v[76:79]
	v_mfma_f32_16x16x32_bf16 v[72:75], v[162:165], v[214:217], v[72:75]
	v_mfma_f32_16x16x32_bf16 v[116:119], v[166:169], v[182:185], v[116:119]
	v_mfma_f32_16x16x32_bf16 v[112:115], v[174:177], v[182:185], v[112:115]
	v_mfma_f32_16x16x32_bf16 v[100:103], v[166:169], v[194:197], v[100:103]
	v_mfma_f32_16x16x32_bf16 v[96:99], v[174:177], v[194:197], v[96:99]
	v_mfma_f32_16x16x32_bf16 v[84:87], v[166:169], v[202:205], v[84:87]
	v_mfma_f32_16x16x32_bf16 v[80:83], v[174:177], v[202:205], v[80:83]
	v_mfma_f32_16x16x32_bf16 v[68:71], v[166:169], v[210:213], v[68:71]
	v_mfma_f32_16x16x32_bf16 v[64:67], v[174:177], v[210:213], v[64:67]
	v_mfma_f32_16x16x32_bf16 v[116:119], v[170:173], v[186:189], v[116:119]
	v_mfma_f32_16x16x32_bf16 v[112:115], v[178:181], v[186:189], v[112:115]
	v_mfma_f32_16x16x32_bf16 v[100:103], v[170:173], v[198:201], v[100:103]
	v_mfma_f32_16x16x32_bf16 v[96:99], v[178:181], v[198:201], v[96:99]
	v_mfma_f32_16x16x32_bf16 v[84:87], v[170:173], v[206:209], v[84:87]
	v_mfma_f32_16x16x32_bf16 v[80:83], v[178:181], v[206:209], v[80:83]
	v_mfma_f32_16x16x32_bf16 v[68:71], v[170:173], v[214:217], v[68:71]
	v_mfma_f32_16x16x32_bf16 v[64:67], v[178:181], v[214:217], v[64:67]
	s_barrier
	s_mov_b32 m0, s76
	v_lshl_add_u64 v[190:191], s[92:93], 0, v[134:135]
	v_lshl_add_u64 v[218:219], s[92:93], 0, v[130:131]
	s_add_u32 s92, s92, s8
	ds_read_b128 v[182:185], v146 offset:16384
	ds_read_b128 v[186:189], v146 offset:17408
	ds_read_b128 v[194:197], v146 offset:18432
	ds_read_b128 v[198:201], v146 offset:19456
	ds_read_b128 v[202:205], v146 offset:20480
	ds_read_b128 v[206:209], v146 offset:21504
	ds_read_b128 v[210:213], v146 offset:22528
	ds_read_b128 v[214:217], v146 offset:23552
	global_load_lds_dwordx4 v[190:191], off
	s_mov_b32 m0, s77
	s_addc_u32 s93, s93, s9
	global_load_lds_dwordx4 v[218:219], off
	v_lshl_add_u64 v[220:221], s[92:93], 0, v[134:135]
	s_mov_b32 m0, s78
	v_lshl_add_u64 v[222:223], s[92:93], 0, v[130:131]
	global_load_lds_dwordx4 v[220:221], off
	s_mov_b32 m0, s79
	v_lshl_add_u64 v[224:225], s[60:61], 0, v[136:137]
	global_load_lds_dwordx4 v[222:223], off
	s_mov_b32 m0, s4
	v_lshl_add_u64 v[226:227], s[60:61], 0, v[132:133]
	global_load_lds_dwordx4 v[224:225], off
	s_mov_b32 m0, s5
	s_nop 0
	global_load_lds_dwordx4 v[226:227], off
	s_waitcnt vmcnt(8)
	s_waitcnt lgkmcnt(0)
	s_barrier
; #define PG8_STAGE(bufoff, gbase, voff) do { _Pragma("unroll") for (int _i = 0; _i < 2; ++_i) \
;         __builtin_amdgcn_global_load_lds((const unsigned*)((const char*)(gbase) + (voff)[_i]), (PG8_LAS unsigned*)(lds + (bufoff) + ldsw + _i * 8192), 16, 0, 0); } while (0)
; #define PG8_LDA(dst, b, h) do { _Pragma("unroll") for (int m = 0; m < 4; ++m) _Pragma("unroll") for (int k = 0; k < 2; ++k) dst[m][k] = *(const PG8_LAS bf16x8*)(lds + PG8_SA(b, h) + aoff + m * 2048 + k * 1024); } while (0)
; #define PG8_LDB(dst, b, h) do { _Pragma("unroll") for (int n = 0; n < 2; ++n) _Pragma("unroll") for (int k = 0; k < 2; ++k) dst[n][k] = *(const PG8_LAS bf16x8*)(lds + PG8_SB(b, h) + boff + n * 2048 + k * 1024); } while (0)
; #define PG8_MMA(ai, bj, At, Bt) do { __builtin_amdgcn_s_setprio(1); _Pragma("unroll") for (int m = 0; m < 4; ++m) _Pragma("unroll") for (int n = 0; n < 2; ++n) _Pragma("unroll") for (int k = 0; k < 2; ++k) \
;         acc[ai][bj][m][n] = __builtin_amdgcn_mfma_f32_16x16x32_bf16(Bt[n][k], At[m][k], acc[ai][bj][m][n], 0, 0, 0); __builtin_amdgcn_s_setprio(0); } while (0)
; #define PG8_WAIT_V(n) asm volatile("s_waitcnt vmcnt(" #n ")" ::: "memory")
; #define PG8_WAIT_L(n) asm volatile("s_waitcnt lgkmcnt(" #n ")" ::: "memory")
; #define PG8_BAR __builtin_amdgcn_s_barrier()
; #define PG8_SCHED __builtin_amdgcn_sched_barrier(0)
; template <class Epi, class Sched, bool ALIGN_EPI = false, bool SP2 = false>
; __device__ __forceinline__ void gemm_phase(PG8_LAS unsigned char* lds, const Gemm g, const Sched& S, const Epi& E) {
;     ...
;             PG8_WAIT_V(8); PG8_WAIT_L(0); PG8_BAR; PG8_MMA(1, 0, At, B0); PG8_MMA(1, 1, At, B1); PG8_BAR; PG8_SCHED;
;             PG8_LDB(B0, 1, 0); PG8_LDB(B1, 1, 1); PG8_SCHED; PG8_LDA(At, 1, 0); PG8_STAGE(PG8_SA(0, 1), a2 + hstep, voffA);
;             PG8_WAIT_V(8); PG8_WAIT_L(0); PG8_BAR; PG8_MMA(0, 0, At, B0); PG8_MMA(0, 1, At, B1); PG8_BAR; PG8_SCHED;
	s_waitcnt lgkmcnt(0)
	v_mfma_f32_16x16x32_bf16 v[60:63], v[150:153], v[182:185], v[60:63]
	v_mfma_f32_16x16x32_bf16 v[56:59], v[158:161], v[182:185], v[56:59]
	v_mfma_f32_16x16x32_bf16 v[44:47], v[150:153], v[194:197], v[44:47]
	v_mfma_f32_16x16x32_bf16 v[40:43], v[158:161], v[194:197], v[40:43]
	v_mfma_f32_16x16x32_bf16 v[28:31], v[150:153], v[202:205], v[28:31]
	v_mfma_f32_16x16x32_bf16 v[24:27], v[158:161], v[202:205], v[24:27]
	v_mfma_f32_16x16x32_bf16 v[12:15], v[150:153], v[210:213], v[12:15]
	v_mfma_f32_16x16x32_bf16 v[8:11], v[158:161], v[210:213], v[8:11]
	v_mfma_f32_16x16x32_bf16 v[60:63], v[154:157], v[186:189], v[60:63]
	v_mfma_f32_16x16x32_bf16 v[56:59], v[162:165], v[186:189], v[56:59]
	v_mfma_f32_16x16x32_bf16 v[44:47], v[154:157], v[198:201], v[44:47]
	v_mfma_f32_16x16x32_bf16 v[40:43], v[162:165], v[198:201], v[40:43]
	v_mfma_f32_16x16x32_bf16 v[28:31], v[154:157], v[206:209], v[28:31]
	v_mfma_f32_16x16x32_bf16 v[24:27], v[162:165], v[206:209], v[24:27]
	v_mfma_f32_16x16x32_bf16 v[12:15], v[154:157], v[214:217], v[12:15]
	v_mfma_f32_16x16x32_bf16 v[8:11], v[162:165], v[214:217], v[8:11]
	v_mfma_f32_16x16x32_bf16 v[52:55], v[166:169], v[182:185], v[52:55]
	v_mfma_f32_16x16x32_bf16 v[48:51], v[174:177], v[182:185], v[48:51]
	v_mfma_f32_16x16x32_bf16 v[36:39], v[166:169], v[194:197], v[36:39]
	v_mfma_f32_16x16x32_bf16 v[32:35], v[174:177], v[194:197], v[32:35]
	v_mfma_f32_16x16x32_bf16 v[20:23], v[166:169], v[202:205], v[20:23]
	v_mfma_f32_16x16x32_bf16 v[16:19], v[174:177], v[202:205], v[16:19]
	v_mfma_f32_16x16x32_bf16 v[4:7], v[166:169], v[210:213], v[4:7]
	v_mfma_f32_16x16x32_bf16 v[0:3], v[174:177], v[210:213], v[0:3]
	v_mfma_f32_16x16x32_bf16 v[52:55], v[170:173], v[186:189], v[52:55]
	v_mfma_f32_16x16x32_bf16 v[48:51], v[178:181], v[186:189], v[48:51]
	v_mfma_f32_16x16x32_bf16 v[36:39], v[170:173], v[198:201], v[36:39]
	v_mfma_f32_16x16x32_bf16 v[32:35], v[178:181], v[198:201], v[32:35]
	v_mfma_f32_16x16x32_bf16 v[20:23], v[170:173], v[206:209], v[20:23]
	v_mfma_f32_16x16x32_bf16 v[16:19], v[178:181], v[206:209], v[16:19]
	v_mfma_f32_16x16x32_bf16 v[4:7], v[170:173], v[214:217], v[4:7]
	v_mfma_f32_16x16x32_bf16 v[0:3], v[178:181], v[214:217], v[0:3]
	s_barrier
	ds_read_b128 v[150:153], v147
	ds_read_b128 v[154:157], v147 offset:1024
	ds_read_b128 v[158:161], v147 offset:2048
	ds_read_b128 v[162:165], v147 offset:3072
	ds_read_b128 v[166:169], v148
	ds_read_b128 v[170:173], v148 offset:1024
	ds_read_b128 v[174:177], v148 offset:2048
	ds_read_b128 v[178:181], v148 offset:3072
	s_add_u32 s60, s60, s8
	s_addc_u32 s61, s61, s9
	s_mov_b32 m0, s63
	v_lshl_add_u64 v[228:229], s[60:61], 0, v[136:137]
	ds_read_b128 v[182:185], v146 offset:32768
	ds_read_b128 v[186:189], v146 offset:33792
	ds_read_b128 v[194:197], v146 offset:34816
	ds_read_b128 v[198:201], v146 offset:35840
	ds_read_b128 v[202:205], v146 offset:36864
	ds_read_b128 v[206:209], v146 offset:37888
	ds_read_b128 v[210:213], v146 offset:38912
	ds_read_b128 v[214:217], v146 offset:39936
	global_load_lds_dwordx4 v[228:229], off
	v_lshl_add_u64 v[228:229], s[60:61], 0, v[132:133]
	s_mov_b32 m0, s64
	s_nop 0
	global_load_lds_dwordx4 v[228:229], off
	s_waitcnt vmcnt(8)
	s_waitcnt lgkmcnt(0)
	s_barrier
	s_waitcnt lgkmcnt(0)
	v_mfma_f32_16x16x32_bf16 v[124:127], v[150:153], v[182:185], v[124:127]
	v_mfma_f32_16x16x32_bf16 v[120:123], v[158:161], v[182:185], v[120:123]
	v_mfma_f32_16x16x32_bf16 v[108:111], v[150:153], v[194:197], v[108:111]
	v_mfma_f32_16x16x32_bf16 v[104:107], v[158:161], v[194:197], v[104:107]
	v_mfma_f32_16x16x32_bf16 v[92:95], v[150:153], v[202:205], v[92:95]
	v_mfma_f32_16x16x32_bf16 v[88:91], v[158:161], v[202:205], v[88:91]
	v_mfma_f32_16x16x32_bf16 v[76:79], v[150:153], v[210:213], v[76:79]
	v_mfma_f32_16x16x32_bf16 v[72:75], v[158:161], v[210:213], v[72:75]
	v_mfma_f32_16x16x32_bf16 v[124:127], v[154:157], v[186:189], v[124:127]
	v_mfma_f32_16x16x32_bf16 v[120:123], v[162:165], v[186:189], v[120:123]
	v_mfma_f32_16x16x32_bf16 v[108:111], v[154:157], v[198:201], v[108:111]
	v_mfma_f32_16x16x32_bf16 v[104:107], v[162:165], v[198:201], v[104:107]
	v_mfma_f32_16x16x32_bf16 v[92:95], v[154:157], v[206:209], v[92:95]
	v_mfma_f32_16x16x32_bf16 v[88:91], v[162:165], v[206:209], v[88:91]
	v_mfma_f32_16x16x32_bf16 v[76:79], v[154:157], v[214:217], v[76:79]
	v_mfma_f32_16x16x32_bf16 v[72:75], v[162:165], v[214:217], v[72:75]
	v_mfma_f32_16x16x32_bf16 v[116:119], v[166:169], v[182:185], v[116:119]
	v_mfma_f32_16x16x32_bf16 v[112:115], v[174:177], v[182:185], v[112:115]
	v_mfma_f32_16x16x32_bf16 v[100:103], v[166:169], v[194:197], v[100:103]
	v_mfma_f32_16x16x32_bf16 v[96:99], v[174:177], v[194:197], v[96:99]
	v_mfma_f32_16x16x32_bf16 v[84:87], v[166:169], v[202:205], v[84:87]
	v_mfma_f32_16x16x32_bf16 v[80:83], v[174:177], v[202:205], v[80:83]
	v_mfma_f32_16x16x32_bf16 v[68:71], v[166:169], v[210:213], v[68:71]
	v_mfma_f32_16x16x32_bf16 v[64:67], v[174:177], v[210:213], v[64:67]
	v_mfma_f32_16x16x32_bf16 v[116:119], v[170:173], v[186:189], v[116:119]
	v_mfma_f32_16x16x32_bf16 v[112:115], v[178:181], v[186:189], v[112:115]
	v_mfma_f32_16x16x32_bf16 v[100:103], v[170:173], v[198:201], v[100:103]
	v_mfma_f32_16x16x32_bf16 v[96:99], v[178:181], v[198:201], v[96:99]
	v_mfma_f32_16x16x32_bf16 v[84:87], v[170:173], v[206:209], v[84:87]
	v_mfma_f32_16x16x32_bf16 v[80:83], v[178:181], v[206:209], v[80:83]
	v_mfma_f32_16x16x32_bf16 v[68:71], v[170:173], v[214:217], v[68:71]
	v_mfma_f32_16x16x32_bf16 v[64:67], v[178:181], v[214:217], v[64:67]
	s_barrier
; #define PG8_STAGE(bufoff, gbase, voff) do { _Pragma("unroll") for (int _i = 0; _i < 2; ++_i) \
;         __builtin_amdgcn_global_load_lds((const unsigned*)((const char*)(gbase) + (voff)[_i]), (PG8_LAS unsigned*)(lds + (bufoff) + ldsw + _i * 8192), 16, 0, 0); } while (0)
; #define PG8_LDA(dst, b, h) do { _Pragma("unroll") for (int m = 0; m < 4; ++m) _Pragma("unroll") for (int k = 0; k < 2; ++k) dst[m][k] = *(const PG8_LAS bf16x8*)(lds + PG8_SA(b, h) + aoff + m * 2048 + k * 1024); } while (0)
; #define PG8_MMA(ai, bj, At, Bt) do { __builtin_amdgcn_s_setprio(1); _Pragma("unroll") for (int m = 0; m < 4; ++m) _Pragma("unroll") for (int n = 0; n < 2; ++n) _Pragma("unroll") for (int k = 0; k < 2; ++k) \
;         acc[ai][bj][m][n] = __builtin_amdgcn_mfma_f32_16x16x32_bf16(Bt[n][k], At[m][k], acc[ai][bj][m][n], 0, 0, 0); __builtin_amdgcn_s_setprio(0); } while (0)
; #define PG8_WAIT_V(n) asm volatile("s_waitcnt vmcnt(" #n ")" ::: "memory")
; #define PG8_WAIT_L(n) asm volatile("s_waitcnt lgkmcnt(" #n ")" ::: "memory")
; #define PG8_BAR __builtin_amdgcn_s_barrier()
; #define PG8_SCHED __builtin_amdgcn_sched_barrier(0)
; template <class Epi, class Sched, bool ALIGN_EPI = false, bool SP2 = false>
; __device__ __forceinline__ void gemm_phase(PG8_LAS unsigned char* lds, const Gemm g, const Sched& S, const Epi& E) {
;     ...
;             PG8_LDA(At, 1, 1); PG8_STAGE(PG8_SB(1, 0), b3, voffB); PG8_STAGE(PG8_SB(1, 1), b3 + hstep, voffB); PG8_STAGE(PG8_SA(1, 0), a3, voffA);
;             PG8_WAIT_V(8); PG8_WAIT_L(0); PG8_BAR; PG8_MMA(1, 0, At, B0); PG8_MMA(1, 1, At, B1); PG8_BAR; PG8_SCHED;
	s_mov_b32 m0, s80
	v_lshl_add_u64 v[190:191], v[190:191], 0, s[14:15]
	ds_read_b128 v[182:185], v146 offset:49152
	ds_read_b128 v[186:189], v146 offset:50176
	ds_read_b128 v[194:197], v146 offset:51200
	ds_read_b128 v[198:201], v146 offset:52224
	ds_read_b128 v[202:205], v146 offset:53248
	ds_read_b128 v[206:209], v146 offset:54272
	ds_read_b128 v[210:213], v146 offset:55296
	ds_read_b128 v[214:217], v146 offset:56320
	global_load_lds_dwordx4 v[190:191], off
	v_lshl_add_u64 v[190:191], v[218:219], 0, s[14:15]
	s_mov_b32 m0, s81
	s_nop 0
	global_load_lds_dwordx4 v[190:191], off
	v_lshl_add_u64 v[190:191], v[220:221], 0, s[14:15]
	s_mov_b32 m0, s82
	s_nop 0
	global_load_lds_dwordx4 v[190:191], off
	v_lshl_add_u64 v[190:191], v[222:223], 0, s[14:15]
	s_mov_b32 m0, s83
	s_nop 0
	global_load_lds_dwordx4 v[190:191], off
	v_lshl_add_u64 v[190:191], v[224:225], 0, s[14:15]
	s_mov_b32 m0, s67
	s_nop 0
	global_load_lds_dwordx4 v[190:191], off
	v_lshl_add_u64 v[190:191], v[226:227], 0, s[14:15]
	s_mov_b32 m0, s68
	s_nop 0
	global_load_lds_dwordx4 v[190:191], off
	s_waitcnt vmcnt(8)
	s_waitcnt lgkmcnt(0)
	s_barrier
	s_waitcnt lgkmcnt(0)
	v_mfma_f32_16x16x32_bf16 v[60:63], v[150:153], v[182:185], v[60:63]
	v_mfma_f32_16x16x32_bf16 v[56:59], v[158:161], v[182:185], v[56:59]
	v_mfma_f32_16x16x32_bf16 v[44:47], v[150:153], v[194:197], v[44:47]
	v_mfma_f32_16x16x32_bf16 v[40:43], v[158:161], v[194:197], v[40:43]
	v_mfma_f32_16x16x32_bf16 v[28:31], v[150:153], v[202:205], v[28:31]
	v_mfma_f32_16x16x32_bf16 v[24:27], v[158:161], v[202:205], v[24:27]
	v_mfma_f32_16x16x32_bf16 v[12:15], v[150:153], v[210:213], v[12:15]
	v_mfma_f32_16x16x32_bf16 v[8:11], v[158:161], v[210:213], v[8:11]
	v_mfma_f32_16x16x32_bf16 v[60:63], v[154:157], v[186:189], v[60:63]
	v_mfma_f32_16x16x32_bf16 v[56:59], v[162:165], v[186:189], v[56:59]
	v_mfma_f32_16x16x32_bf16 v[44:47], v[154:157], v[198:201], v[44:47]
	v_mfma_f32_16x16x32_bf16 v[40:43], v[162:165], v[198:201], v[40:43]
	v_mfma_f32_16x16x32_bf16 v[28:31], v[154:157], v[206:209], v[28:31]
	v_mfma_f32_16x16x32_bf16 v[24:27], v[162:165], v[206:209], v[24:27]
	v_mfma_f32_16x16x32_bf16 v[12:15], v[154:157], v[214:217], v[12:15]
	v_mfma_f32_16x16x32_bf16 v[8:11], v[162:165], v[214:217], v[8:11]
	v_mfma_f32_16x16x32_bf16 v[52:55], v[166:169], v[182:185], v[52:55]
	v_mfma_f32_16x16x32_bf16 v[48:51], v[174:177], v[182:185], v[48:51]
	v_mfma_f32_16x16x32_bf16 v[36:39], v[166:169], v[194:197], v[36:39]
	v_mfma_f32_16x16x32_bf16 v[32:35], v[174:177], v[194:197], v[32:35]
	v_mfma_f32_16x16x32_bf16 v[20:23], v[166:169], v[202:205], v[20:23]
	v_mfma_f32_16x16x32_bf16 v[16:19], v[174:177], v[202:205], v[16:19]
	v_mfma_f32_16x16x32_bf16 v[4:7], v[166:169], v[210:213], v[4:7]
	v_mfma_f32_16x16x32_bf16 v[0:3], v[174:177], v[210:213], v[0:3]
	v_mfma_f32_16x16x32_bf16 v[52:55], v[170:173], v[186:189], v[52:55]
	v_mfma_f32_16x16x32_bf16 v[48:51], v[178:181], v[186:189], v[48:51]
	v_mfma_f32_16x16x32_bf16 v[36:39], v[170:173], v[198:201], v[36:39]
	v_mfma_f32_16x16x32_bf16 v[32:35], v[178:181], v[198:201], v[32:35]
	v_mfma_f32_16x16x32_bf16 v[20:23], v[170:173], v[206:209], v[20:23]
	v_mfma_f32_16x16x32_bf16 v[16:19], v[178:181], v[206:209], v[16:19]
	v_mfma_f32_16x16x32_bf16 v[4:7], v[170:173], v[214:217], v[4:7]
	v_mfma_f32_16x16x32_bf16 v[0:3], v[178:181], v[214:217], v[0:3]
	s_barrier
	s_add_u32 s58, s58, 0x100
	s_addc_u32 s59, s59, 0
	s_add_u32 s33, s33, 0x100
	s_addc_u32 s89, s89, 0
	s_cmp_ge_i32 s90, s70
	s_mov_b32 s60, s90
	s_cbranch_scc0 .LBB0_633

; #define PG8_STAGE(bufoff, gbase, voff) do { _Pragma("unroll") for (int _i = 0; _i < 2; ++_i) \
;         __builtin_amdgcn_global_load_lds((const unsigned*)((const char*)(gbase) + (voff)[_i]), (PG8_LAS unsigned*)(lds + (bufoff) + ldsw + _i * 8192), 16, 0, 0); } while (0)
; #define PG8_LDA(dst, b, h) do { _Pragma("unroll") for (int m = 0; m < 4; ++m) _Pragma("unroll") for (int k = 0; k < 2; ++k) dst[m][k] = *(const PG8_LAS bf16x8*)(lds + PG8_SA(b, h) + aoff + m * 2048 + k * 1024); } while (0)
; #define PG8_LDB(dst, b, h) do { _Pragma("unroll") for (int n = 0; n < 2; ++n) _Pragma("unroll") for (int k = 0; k < 2; ++k) dst[n][k] = *(const PG8_LAS bf16x8*)(lds + PG8_SB(b, h) + boff + n * 2048 + k * 1024); } while (0)
; #define PG8_MMA(ai, bj, At, Bt) do { __builtin_amdgcn_s_setprio(1); _Pragma("unroll") for (int m = 0; m < 4; ++m) _Pragma("unroll") for (int n = 0; n < 2; ++n) _Pragma("unroll") for (int k = 0; k < 2; ++k) \
;         acc[ai][bj][m][n] = __builtin_amdgcn_mfma_f32_16x16x32_bf16(Bt[n][k], At[m][k], acc[ai][bj][m][n], 0, 0, 0); __builtin_amdgcn_s_setprio(0); } while (0)
; #define PG8_WAIT_V(n) asm volatile("s_waitcnt vmcnt(" #n ")" ::: "memory")
; #define PG8_WAIT_L(n) asm volatile("s_waitcnt lgkmcnt(" #n ")" ::: "memory")
; #define PG8_BAR __builtin_amdgcn_s_barrier()
; #define PG8_SCHED __builtin_amdgcn_sched_barrier(0)
; template <class Epi, class Sched, bool ALIGN_EPI = false, bool SP2 = false>
; __device__ __forceinline__ void gemm_phase(PG8_LAS unsigned char* lds, const Gemm g, const Sched& S, const Epi& E) {
;     ...
;             PG8_LDB(B0, 0, 0); PG8_LDB(B1, 0, 1); PG8_SCHED; PG8_LDA(At, 0, 0); PG8_STAGE(PG8_SA(1, 1), a1 + hstep, voffA);
;             PG8_WAIT_V(8); PG8_WAIT_L(0); PG8_BAR; PG8_MMA(0, 0, At, B0); PG8_MMA(0, 1, At, B1); PG8_BAR; PG8_SCHED;
;             PG8_LDA(At, 0, 1); PG8_STAGE(PG8_SB(0, 0), b2, voffB); PG8_STAGE(PG8_SB(0, 1), b2 + hstep, voffB); PG8_STAGE(PG8_SA(0, 0), a2, voffA);
;             PG8_WAIT_V(8); PG8_WAIT_L(0); PG8_BAR; PG8_MMA(1, 0, At, B0); PG8_MMA(1, 1, At, B1); PG8_BAR; PG8_SCHED;
;             PG8_LDB(B0, 1, 0); PG8_LDB(B1, 1, 1); PG8_SCHED; PG8_LDA(At, 1, 0); PG8_STAGE(PG8_SA(0, 1), a2 + hstep, voffA);
.LBB0_921:
	ds_read_b128 v[128:131], v247
	ds_read_b128 v[132:135], v247 offset:1024
	ds_read_b128 v[136:139], v247 offset:2048
	ds_read_b128 v[140:143], v247 offset:3072
	ds_read_b128 v[144:147], v248
	ds_read_b128 v[148:151], v248 offset:1024
	ds_read_b128 v[152:155], v248 offset:2048
	ds_read_b128 v[156:159], v248 offset:3072
	s_add_i32 s75, s58, 2
	s_add_u32 s76, s42, 0x80
	s_addc_u32 s59, s43, 0
	s_cmp_eq_u32 s66, s58
	s_cselect_b32 s58, s8, s76
	s_cselect_b32 s59, s9, s59
	s_cselect_b32 s77, s41, s33
	s_cselect_b32 s76, s40, s5
	v_lshl_add_u64 v[208:209], s[42:43], 0, v[202:203]
	s_add_i32 m0, s48, 0xc000
	ds_read_b128 v[160:163], v249
	ds_read_b128 v[164:167], v249 offset:1024
	ds_read_b128 v[168:171], v249 offset:2048
	ds_read_b128 v[172:175], v249 offset:3072
	ds_read_b128 v[176:179], v249 offset:4096
	ds_read_b128 v[180:183], v249 offset:5120
	ds_read_b128 v[184:187], v249 offset:6144
	ds_read_b128 v[188:191], v249 offset:7168
	global_load_lds_dwordx4 v[208:209], off
	v_lshl_add_u64 v[208:209], s[42:43], 0, v[204:205]
	s_add_i32 m0, s48, 0xe000
	s_nop 0
	global_load_lds_dwordx4 v[208:209], off
	s_waitcnt vmcnt(8)
	s_waitcnt lgkmcnt(0)
	s_barrier
	s_waitcnt lgkmcnt(0)
	v_mfma_f32_16x16x32_bf16 v[120:123], v[128:131], v[160:163], v[120:123]
	v_mfma_f32_16x16x32_bf16 v[124:127], v[136:139], v[160:163], v[124:127]
	v_mfma_f32_16x16x32_bf16 v[108:111], v[128:131], v[168:171], v[108:111]
	v_mfma_f32_16x16x32_bf16 v[104:107], v[136:139], v[168:171], v[104:107]
	v_mfma_f32_16x16x32_bf16 v[92:95], v[128:131], v[176:179], v[92:95]
	v_mfma_f32_16x16x32_bf16 v[88:91], v[136:139], v[176:179], v[88:91]
	v_mfma_f32_16x16x32_bf16 v[76:79], v[128:131], v[184:187], v[76:79]
	v_mfma_f32_16x16x32_bf16 v[72:75], v[136:139], v[184:187], v[72:75]
	v_mfma_f32_16x16x32_bf16 v[120:123], v[132:135], v[164:167], v[120:123]
	v_mfma_f32_16x16x32_bf16 v[124:127], v[140:143], v[164:167], v[124:127]
	v_mfma_f32_16x16x32_bf16 v[108:111], v[132:135], v[172:175], v[108:111]
	v_mfma_f32_16x16x32_bf16 v[104:107], v[140:143], v[172:175], v[104:107]
	v_mfma_f32_16x16x32_bf16 v[92:95], v[132:135], v[180:183], v[92:95]
	v_mfma_f32_16x16x32_bf16 v[88:91], v[140:143], v[180:183], v[88:91]
	v_mfma_f32_16x16x32_bf16 v[76:79], v[132:135], v[188:191], v[76:79]
	v_mfma_f32_16x16x32_bf16 v[72:75], v[140:143], v[188:191], v[72:75]
	v_mfma_f32_16x16x32_bf16 v[116:119], v[144:147], v[160:163], v[116:119]
	v_mfma_f32_16x16x32_bf16 v[112:115], v[152:155], v[160:163], v[112:115]
	v_mfma_f32_16x16x32_bf16 v[100:103], v[144:147], v[168:171], v[100:103]
	v_mfma_f32_16x16x32_bf16 v[96:99], v[152:155], v[168:171], v[96:99]
	v_mfma_f32_16x16x32_bf16 v[84:87], v[144:147], v[176:179], v[84:87]
	v_mfma_f32_16x16x32_bf16 v[80:83], v[152:155], v[176:179], v[80:83]
	v_mfma_f32_16x16x32_bf16 v[68:71], v[144:147], v[184:187], v[68:71]
	v_mfma_f32_16x16x32_bf16 v[64:67], v[152:155], v[184:187], v[64:67]
	v_mfma_f32_16x16x32_bf16 v[116:119], v[148:151], v[164:167], v[116:119]
	v_mfma_f32_16x16x32_bf16 v[112:115], v[156:159], v[164:167], v[112:115]
	v_mfma_f32_16x16x32_bf16 v[100:103], v[148:151], v[172:175], v[100:103]
	v_mfma_f32_16x16x32_bf16 v[96:99], v[156:159], v[172:175], v[96:99]
	v_mfma_f32_16x16x32_bf16 v[84:87], v[148:151], v[180:183], v[84:87]
	v_mfma_f32_16x16x32_bf16 v[80:83], v[156:159], v[180:183], v[80:83]
	v_mfma_f32_16x16x32_bf16 v[68:71], v[148:151], v[188:191], v[68:71]
	v_mfma_f32_16x16x32_bf16 v[64:67], v[156:159], v[188:191], v[64:67]
	s_barrier
	s_add_i32 s78, s70, s3
	v_lshl_add_u64 v[208:209], s[76:77], 0, v[196:197]
	s_mov_b32 m0, s78
	ds_read_b128 v[160:163], v249 offset:16384
	ds_read_b128 v[164:167], v249 offset:17408
	ds_read_b128 v[168:171], v249 offset:18432
	ds_read_b128 v[172:175], v249 offset:19456
	ds_read_b128 v[176:179], v249 offset:20480
	ds_read_b128 v[180:183], v249 offset:21504
	ds_read_b128 v[184:187], v249 offset:22528
	ds_read_b128 v[188:191], v249 offset:23552
	global_load_lds_dwordx4 v[208:209], off
	s_add_i32 m0, s78, 0x2000
	v_lshl_add_u64 v[210:211], s[76:77], 0, v[200:201]
	s_add_u32 s76, s76, s14
	s_addc_u32 s77, s77, s15
	s_add_i32 s78, s71, s3
	global_load_lds_dwordx4 v[210:211], off
	v_lshl_add_u64 v[212:213], s[76:77], 0, v[196:197]
	s_mov_b32 m0, s78
	v_lshl_add_u64 v[214:215], s[76:77], 0, v[200:201]
	global_load_lds_dwordx4 v[212:213], off
	s_add_i32 m0, s78, 0x2000
	v_lshl_add_u64 v[216:217], s[58:59], 0, v[194:195]
	global_load_lds_dwordx4 v[214:215], off
	s_mov_b32 m0, s48
	v_lshl_add_u64 v[218:219], s[58:59], 0, v[198:199]
	global_load_lds_dwordx4 v[216:217], off
	s_mov_b32 m0, s49
	s_nop 0
	global_load_lds_dwordx4 v[218:219], off
	s_waitcnt vmcnt(8)
	s_waitcnt lgkmcnt(0)
	s_barrier
; #define PG8_STAGE(bufoff, gbase, voff) do { _Pragma("unroll") for (int _i = 0; _i < 2; ++_i) \
;         __builtin_amdgcn_global_load_lds((const unsigned*)((const char*)(gbase) + (voff)[_i]), (PG8_LAS unsigned*)(lds + (bufoff) + ldsw + _i * 8192), 16, 0, 0); } while (0)
; #define PG8_LDA(dst, b, h) do { _Pragma("unroll") for (int m = 0; m < 4; ++m) _Pragma("unroll") for (int k = 0; k < 2; ++k) dst[m][k] = *(const PG8_LAS bf16x8*)(lds + PG8_SA(b, h) + aoff + m * 2048 + k * 1024); } while (0)
; #define PG8_LDB(dst, b, h) do { _Pragma("unroll") for (int n = 0; n < 2; ++n) _Pragma("unroll") for (int k = 0; k < 2; ++k) dst[n][k] = *(const PG8_LAS bf16x8*)(lds + PG8_SB(b, h) + boff + n * 2048 + k * 1024); } while (0)
; #define PG8_MMA(ai, bj, At, Bt) do { __builtin_amdgcn_s_setprio(1); _Pragma("unroll") for (int m = 0; m < 4; ++m) _Pragma("unroll") for (int n = 0; n < 2; ++n) _Pragma("unroll") for (int k = 0; k < 2; ++k) \
;         acc[ai][bj][m][n] = __builtin_amdgcn_mfma_f32_16x16x32_bf16(Bt[n][k], At[m][k], acc[ai][bj][m][n], 0, 0, 0); __builtin_amdgcn_s_setprio(0); } while (0)
; #define PG8_WAIT_V(n) asm volatile("s_waitcnt vmcnt(" #n ")" ::: "memory")
; #define PG8_WAIT_L(n) asm volatile("s_waitcnt lgkmcnt(" #n ")" ::: "memory")
; #define PG8_BAR __builtin_amdgcn_s_barrier()
; #define PG8_SCHED __builtin_amdgcn_sched_barrier(0)
; template <class Epi, class Sched, bool ALIGN_EPI = false, bool SP2 = false>
; __device__ __forceinline__ void gemm_phase(PG8_LAS unsigned char* lds, const Gemm g, const Sched& S, const Epi& E) {
;     ...
;             PG8_WAIT_V(8); PG8_WAIT_L(0); PG8_BAR; PG8_MMA(1, 0, At, B0); PG8_MMA(1, 1, At, B1); PG8_BAR; PG8_SCHED;
;             PG8_LDB(B0, 1, 0); PG8_LDB(B1, 1, 1); PG8_SCHED; PG8_LDA(At, 1, 0); PG8_STAGE(PG8_SA(0, 1), a2 + hstep, voffA);
;             PG8_WAIT_V(8); PG8_WAIT_L(0); PG8_BAR; PG8_MMA(0, 0, At, B0); PG8_MMA(0, 1, At, B1); PG8_BAR; PG8_SCHED;
	s_waitcnt lgkmcnt(0)
	v_mfma_f32_16x16x32_bf16 v[60:63], v[128:131], v[160:163], v[60:63]
	v_mfma_f32_16x16x32_bf16 v[56:59], v[136:139], v[160:163], v[56:59]
	v_mfma_f32_16x16x32_bf16 v[44:47], v[128:131], v[168:171], v[44:47]
	v_mfma_f32_16x16x32_bf16 v[40:43], v[136:139], v[168:171], v[40:43]
	v_mfma_f32_16x16x32_bf16 v[28:31], v[128:131], v[176:179], v[28:31]
	v_mfma_f32_16x16x32_bf16 v[24:27], v[136:139], v[176:179], v[24:27]
	v_mfma_f32_16x16x32_bf16 v[12:15], v[128:131], v[184:187], v[12:15]
	v_mfma_f32_16x16x32_bf16 v[8:11], v[136:139], v[184:187], v[8:11]
	v_mfma_f32_16x16x32_bf16 v[60:63], v[132:135], v[164:167], v[60:63]
	v_mfma_f32_16x16x32_bf16 v[56:59], v[140:143], v[164:167], v[56:59]
	v_mfma_f32_16x16x32_bf16 v[44:47], v[132:135], v[172:175], v[44:47]
	v_mfma_f32_16x16x32_bf16 v[40:43], v[140:143], v[172:175], v[40:43]
	v_mfma_f32_16x16x32_bf16 v[28:31], v[132:135], v[180:183], v[28:31]
	v_mfma_f32_16x16x32_bf16 v[24:27], v[140:143], v[180:183], v[24:27]
	v_mfma_f32_16x16x32_bf16 v[12:15], v[132:135], v[188:191], v[12:15]
	v_mfma_f32_16x16x32_bf16 v[8:11], v[140:143], v[188:191], v[8:11]
	v_mfma_f32_16x16x32_bf16 v[52:55], v[144:147], v[160:163], v[52:55]
	v_mfma_f32_16x16x32_bf16 v[48:51], v[152:155], v[160:163], v[48:51]
	v_mfma_f32_16x16x32_bf16 v[36:39], v[144:147], v[168:171], v[36:39]
	v_mfma_f32_16x16x32_bf16 v[32:35], v[152:155], v[168:171], v[32:35]
	v_mfma_f32_16x16x32_bf16 v[20:23], v[144:147], v[176:179], v[20:23]
	v_mfma_f32_16x16x32_bf16 v[16:19], v[152:155], v[176:179], v[16:19]
	v_mfma_f32_16x16x32_bf16 v[4:7], v[144:147], v[184:187], v[4:7]
	v_mfma_f32_16x16x32_bf16 v[0:3], v[152:155], v[184:187], v[0:3]
	v_mfma_f32_16x16x32_bf16 v[52:55], v[148:151], v[164:167], v[52:55]
	v_mfma_f32_16x16x32_bf16 v[48:51], v[156:159], v[164:167], v[48:51]
	v_mfma_f32_16x16x32_bf16 v[36:39], v[148:151], v[172:175], v[36:39]
	v_mfma_f32_16x16x32_bf16 v[32:35], v[156:159], v[172:175], v[32:35]
	v_mfma_f32_16x16x32_bf16 v[20:23], v[148:151], v[180:183], v[20:23]
	v_mfma_f32_16x16x32_bf16 v[16:19], v[156:159], v[180:183], v[16:19]
	v_mfma_f32_16x16x32_bf16 v[4:7], v[148:151], v[188:191], v[4:7]
	v_mfma_f32_16x16x32_bf16 v[0:3], v[156:159], v[188:191], v[0:3]
	s_barrier
	s_add_i32 s76, 0, 0x18000
	s_add_i32 s77, 0, 0x1c000
	v_add_u32_e32 v140, s76, v244
	v_add_u32_e32 v156, s77, v244
	ds_read_b128 v[128:131], v140
	ds_read_b128 v[132:135], v140 offset:1024
	ds_read_b128 v[136:139], v140 offset:2048
	ds_read_b128 v[140:143], v140 offset:3072
	ds_read_b128 v[144:147], v156
	ds_read_b128 v[148:151], v156 offset:1024
	ds_read_b128 v[152:155], v156 offset:2048
	ds_read_b128 v[156:159], v156 offset:3072
	s_add_u32 s58, s58, s14
	s_addc_u32 s59, s59, s15
	s_mov_b32 m0, s60
	v_lshl_add_u64 v[220:221], s[58:59], 0, v[194:195]
	ds_read_b128 v[160:163], v249 offset:32768
	ds_read_b128 v[164:167], v249 offset:33792
	ds_read_b128 v[168:171], v249 offset:34816
	ds_read_b128 v[172:175], v249 offset:35840
	ds_read_b128 v[176:179], v249 offset:36864
	ds_read_b128 v[180:183], v249 offset:37888
	ds_read_b128 v[184:187], v249 offset:38912
	ds_read_b128 v[188:191], v249 offset:39936
	global_load_lds_dwordx4 v[220:221], off
	v_lshl_add_u64 v[220:221], s[58:59], 0, v[198:199]
	s_mov_b32 m0, s61
	s_nop 0
	global_load_lds_dwordx4 v[220:221], off
	s_waitcnt vmcnt(8)
	s_waitcnt lgkmcnt(0)
	s_barrier
	s_waitcnt lgkmcnt(0)
	v_mfma_f32_16x16x32_bf16 v[120:123], v[128:131], v[160:163], v[120:123]
	v_mfma_f32_16x16x32_bf16 v[124:127], v[136:139], v[160:163], v[124:127]
	v_mfma_f32_16x16x32_bf16 v[108:111], v[128:131], v[168:171], v[108:111]
	v_mfma_f32_16x16x32_bf16 v[104:107], v[136:139], v[168:171], v[104:107]
	v_mfma_f32_16x16x32_bf16 v[92:95], v[128:131], v[176:179], v[92:95]
	v_mfma_f32_16x16x32_bf16 v[88:91], v[136:139], v[176:179], v[88:91]
	v_mfma_f32_16x16x32_bf16 v[76:79], v[128:131], v[184:187], v[76:79]
	v_mfma_f32_16x16x32_bf16 v[72:75], v[136:139], v[184:187], v[72:75]
	v_mfma_f32_16x16x32_bf16 v[120:123], v[132:135], v[164:167], v[120:123]
	v_mfma_f32_16x16x32_bf16 v[124:127], v[140:143], v[164:167], v[124:127]
	v_mfma_f32_16x16x32_bf16 v[108:111], v[132:135], v[172:175], v[108:111]
	v_mfma_f32_16x16x32_bf16 v[104:107], v[140:143], v[172:175], v[104:107]
	v_mfma_f32_16x16x32_bf16 v[92:95], v[132:135], v[180:183], v[92:95]
	v_mfma_f32_16x16x32_bf16 v[88:91], v[140:143], v[180:183], v[88:91]
	v_mfma_f32_16x16x32_bf16 v[76:79], v[132:135], v[188:191], v[76:79]
	v_mfma_f32_16x16x32_bf16 v[72:75], v[140:143], v[188:191], v[72:75]
	v_mfma_f32_16x16x32_bf16 v[116:119], v[144:147], v[160:163], v[116:119]
	v_mfma_f32_16x16x32_bf16 v[112:115], v[152:155], v[160:163], v[112:115]
	v_mfma_f32_16x16x32_bf16 v[100:103], v[144:147], v[168:171], v[100:103]
	v_mfma_f32_16x16x32_bf16 v[96:99], v[152:155], v[168:171], v[96:99]
	v_mfma_f32_16x16x32_bf16 v[84:87], v[144:147], v[176:179], v[84:87]
	v_mfma_f32_16x16x32_bf16 v[80:83], v[152:155], v[176:179], v[80:83]
	v_mfma_f32_16x16x32_bf16 v[68:71], v[144:147], v[184:187], v[68:71]
	v_mfma_f32_16x16x32_bf16 v[64:67], v[152:155], v[184:187], v[64:67]
	v_mfma_f32_16x16x32_bf16 v[116:119], v[148:151], v[164:167], v[116:119]
	v_mfma_f32_16x16x32_bf16 v[112:115], v[156:159], v[164:167], v[112:115]
	v_mfma_f32_16x16x32_bf16 v[100:103], v[148:151], v[172:175], v[100:103]
	v_mfma_f32_16x16x32_bf16 v[96:99], v[156:159], v[172:175], v[96:99]
	v_mfma_f32_16x16x32_bf16 v[84:87], v[148:151], v[180:183], v[84:87]
	v_mfma_f32_16x16x32_bf16 v[80:83], v[156:159], v[180:183], v[80:83]
	v_mfma_f32_16x16x32_bf16 v[68:71], v[148:151], v[188:191], v[68:71]
	v_mfma_f32_16x16x32_bf16 v[64:67], v[156:159], v[188:191], v[64:67]
	s_barrier
; #define PG8_STAGE(bufoff, gbase, voff) do { _Pragma("unroll") for (int _i = 0; _i < 2; ++_i) \
;         __builtin_amdgcn_global_load_lds((const unsigned*)((const char*)(gbase) + (voff)[_i]), (PG8_LAS unsigned*)(lds + (bufoff) + ldsw + _i * 8192), 16, 0, 0); } while (0)
; #define PG8_LDA(dst, b, h) do { _Pragma("unroll") for (int m = 0; m < 4; ++m) _Pragma("unroll") for (int k = 0; k < 2; ++k) dst[m][k] = *(const PG8_LAS bf16x8*)(lds + PG8_SA(b, h) + aoff + m * 2048 + k * 1024); } while (0)
; #define PG8_MMA(ai, bj, At, Bt) do { __builtin_amdgcn_s_setprio(1); _Pragma("unroll") for (int m = 0; m < 4; ++m) _Pragma("unroll") for (int n = 0; n < 2; ++n) _Pragma("unroll") for (int k = 0; k < 2; ++k) \
;         acc[ai][bj][m][n] = __builtin_amdgcn_mfma_f32_16x16x32_bf16(Bt[n][k], At[m][k], acc[ai][bj][m][n], 0, 0, 0); __builtin_amdgcn_s_setprio(0); } while (0)
; #define PG8_WAIT_V(n) asm volatile("s_waitcnt vmcnt(" #n ")" ::: "memory")
; #define PG8_WAIT_L(n) asm volatile("s_waitcnt lgkmcnt(" #n ")" ::: "memory")
; #define PG8_BAR __builtin_amdgcn_s_barrier()
; #define PG8_SCHED __builtin_amdgcn_sched_barrier(0)
; template <class Epi, class Sched, bool ALIGN_EPI = false, bool SP2 = false>
; __device__ __forceinline__ void gemm_phase(PG8_LAS unsigned char* lds, const Gemm g, const Sched& S, const Epi& E) {
;     ...
;             PG8_LDA(At, 1, 1); PG8_STAGE(PG8_SB(1, 0), b3, voffB); PG8_STAGE(PG8_SB(1, 1), b3 + hstep, voffB); PG8_STAGE(PG8_SA(1, 0), a3, voffA);
;             PG8_WAIT_V(8); PG8_WAIT_L(0); PG8_BAR; PG8_MMA(1, 0, At, B0); PG8_MMA(1, 1, At, B1); PG8_BAR; PG8_SCHED;
	s_add_i32 s58, s76, s3
	v_lshl_add_u64 v[208:209], v[208:209], 0, s[22:23]
	s_mov_b32 m0, s58
	ds_read_b128 v[160:163], v249 offset:49152
	ds_read_b128 v[164:167], v249 offset:50176
	ds_read_b128 v[168:171], v249 offset:51200
	ds_read_b128 v[172:175], v249 offset:52224
	ds_read_b128 v[176:179], v249 offset:53248
	ds_read_b128 v[180:183], v249 offset:54272
	ds_read_b128 v[184:187], v249 offset:55296
	ds_read_b128 v[188:191], v249 offset:56320
	global_load_lds_dwordx4 v[208:209], off
	v_lshl_add_u64 v[208:209], v[210:211], 0, s[22:23]
	s_add_i32 m0, s58, 0x2000
	s_add_i32 s58, s77, s3
	global_load_lds_dwordx4 v[208:209], off
	v_lshl_add_u64 v[208:209], v[212:213], 0, s[22:23]
	s_mov_b32 m0, s58
	s_nop 0
	global_load_lds_dwordx4 v[208:209], off
	v_lshl_add_u64 v[208:209], v[214:215], 0, s[22:23]
	s_add_i32 m0, s58, 0x2000
	s_nop 0
	global_load_lds_dwordx4 v[208:209], off
	v_lshl_add_u64 v[208:209], v[216:217], 0, s[22:23]
	s_mov_b32 m0, s62
	s_nop 0
	global_load_lds_dwordx4 v[208:209], off
	v_lshl_add_u64 v[208:209], v[218:219], 0, s[22:23]
	s_mov_b32 m0, s63
	s_nop 0
	global_load_lds_dwordx4 v[208:209], off
	s_waitcnt vmcnt(8)
	s_waitcnt lgkmcnt(0)
	s_barrier
	s_waitcnt lgkmcnt(0)
	v_mfma_f32_16x16x32_bf16 v[60:63], v[128:131], v[160:163], v[60:63]
	v_mfma_f32_16x16x32_bf16 v[56:59], v[136:139], v[160:163], v[56:59]
	v_mfma_f32_16x16x32_bf16 v[44:47], v[128:131], v[168:171], v[44:47]
	v_mfma_f32_16x16x32_bf16 v[40:43], v[136:139], v[168:171], v[40:43]
	v_mfma_f32_16x16x32_bf16 v[28:31], v[128:131], v[176:179], v[28:31]
	v_mfma_f32_16x16x32_bf16 v[24:27], v[136:139], v[176:179], v[24:27]
	v_mfma_f32_16x16x32_bf16 v[12:15], v[128:131], v[184:187], v[12:15]
	v_mfma_f32_16x16x32_bf16 v[8:11], v[136:139], v[184:187], v[8:11]
	v_mfma_f32_16x16x32_bf16 v[60:63], v[132:135], v[164:167], v[60:63]
	v_mfma_f32_16x16x32_bf16 v[56:59], v[140:143], v[164:167], v[56:59]
	v_mfma_f32_16x16x32_bf16 v[44:47], v[132:135], v[172:175], v[44:47]
	v_mfma_f32_16x16x32_bf16 v[40:43], v[140:143], v[172:175], v[40:43]
	v_mfma_f32_16x16x32_bf16 v[28:31], v[132:135], v[180:183], v[28:31]
	v_mfma_f32_16x16x32_bf16 v[24:27], v[140:143], v[180:183], v[24:27]
	v_mfma_f32_16x16x32_bf16 v[12:15], v[132:135], v[188:191], v[12:15]
	v_mfma_f32_16x16x32_bf16 v[8:11], v[140:143], v[188:191], v[8:11]
	v_mfma_f32_16x16x32_bf16 v[52:55], v[144:147], v[160:163], v[52:55]
	v_mfma_f32_16x16x32_bf16 v[48:51], v[152:155], v[160:163], v[48:51]
	v_mfma_f32_16x16x32_bf16 v[36:39], v[144:147], v[168:171], v[36:39]
	v_mfma_f32_16x16x32_bf16 v[32:35], v[152:155], v[168:171], v[32:35]
	v_mfma_f32_16x16x32_bf16 v[20:23], v[144:147], v[176:179], v[20:23]
	v_mfma_f32_16x16x32_bf16 v[16:19], v[152:155], v[176:179], v[16:19]
	v_mfma_f32_16x16x32_bf16 v[4:7], v[144:147], v[184:187], v[4:7]
	v_mfma_f32_16x16x32_bf16 v[0:3], v[152:155], v[184:187], v[0:3]
	v_mfma_f32_16x16x32_bf16 v[52:55], v[148:151], v[164:167], v[52:55]
	v_mfma_f32_16x16x32_bf16 v[48:51], v[156:159], v[164:167], v[48:51]
	v_mfma_f32_16x16x32_bf16 v[36:39], v[148:151], v[172:175], v[36:39]
	v_mfma_f32_16x16x32_bf16 v[32:35], v[156:159], v[172:175], v[32:35]
	v_mfma_f32_16x16x32_bf16 v[20:23], v[148:151], v[180:183], v[20:23]
	v_mfma_f32_16x16x32_bf16 v[16:19], v[156:159], v[180:183], v[16:19]
	v_mfma_f32_16x16x32_bf16 v[4:7], v[148:151], v[188:191], v[4:7]
	v_mfma_f32_16x16x32_bf16 v[0:3], v[156:159], v[188:191], v[0:3]
	s_barrier
	s_add_u32 s42, s42, 0x100
	s_addc_u32 s43, s43, 0
	s_add_u32 s5, s5, 0x100
	s_addc_u32 s33, s33, 0
	s_cmp_ge_i32 s75, s65
	s_mov_b32 s58, s75
	s_cbranch_scc0 .LBB0_921

; #define PG8_STAGE(bufoff, gbase, voff) do { _Pragma("unroll") for (int _i = 0; _i < 2; ++_i) \
;         __builtin_amdgcn_global_load_lds((const unsigned*)((const char*)(gbase) + (voff)[_i]), (PG8_LAS unsigned*)(lds + (bufoff) + ldsw + _i * 8192), 16, 0, 0); } while (0)
; #define PG8_LDA(dst, b, h) do { _Pragma("unroll") for (int m = 0; m < 4; ++m) _Pragma("unroll") for (int k = 0; k < 2; ++k) dst[m][k] = *(const PG8_LAS bf16x8*)(lds + PG8_SA(b, h) + aoff + m * 2048 + k * 1024); } while (0)
; #define PG8_LDB(dst, b, h) do { _Pragma("unroll") for (int n = 0; n < 2; ++n) _Pragma("unroll") for (int k = 0; k < 2; ++k) dst[n][k] = *(const PG8_LAS bf16x8*)(lds + PG8_SB(b, h) + boff + n * 2048 + k * 1024); } while (0)
; #define PG8_MMA(ai, bj, At, Bt) do { __builtin_amdgcn_s_setprio(1); _Pragma("unroll") for (int m = 0; m < 4; ++m) _Pragma("unroll") for (int n = 0; n < 2; ++n) _Pragma("unroll") for (int k = 0; k < 2; ++k) \
;         acc[ai][bj][m][n] = __builtin_amdgcn_mfma_f32_16x16x32_bf16(Bt[n][k], At[m][k], acc[ai][bj][m][n], 0, 0, 0); __builtin_amdgcn_s_setprio(0); } while (0)
; #define PG8_WAIT_V(n) asm volatile("s_waitcnt vmcnt(" #n ")" ::: "memory")
; #define PG8_WAIT_L(n) asm volatile("s_waitcnt lgkmcnt(" #n ")" ::: "memory")
; #define PG8_BAR __builtin_amdgcn_s_barrier()
; #define PG8_SCHED __builtin_amdgcn_sched_barrier(0)
; template <class Epi, class Sched, bool ALIGN_EPI = false, bool SP2 = false>
; __device__ __forceinline__ void gemm_phase(PG8_LAS unsigned char* lds, const Gemm g, const Sched& S, const Epi& E) {
;     ...
;             PG8_LDB(B0, 0, 0); PG8_LDB(B1, 0, 1); PG8_SCHED; PG8_LDA(At, 0, 0); PG8_STAGE(PG8_SA(1, 1), a1 + hstep, voffA);
;             PG8_WAIT_V(8); PG8_WAIT_L(0); PG8_BAR; PG8_MMA(0, 0, At, B0); PG8_MMA(0, 1, At, B1); PG8_BAR; PG8_SCHED;
;             PG8_LDA(At, 0, 1); PG8_STAGE(PG8_SB(0, 0), b2, voffB); PG8_STAGE(PG8_SB(0, 1), b2 + hstep, voffB); PG8_STAGE(PG8_SA(0, 0), a2, voffA);
;             PG8_WAIT_V(8); PG8_WAIT_L(0); PG8_BAR; PG8_MMA(1, 0, At, B0); PG8_MMA(1, 1, At, B1); PG8_BAR; PG8_SCHED;
;             PG8_LDB(B0, 1, 0); PG8_LDB(B1, 1, 1); PG8_SCHED; PG8_LDA(At, 1, 0); PG8_STAGE(PG8_SA(0, 1), a2 + hstep, voffA);
.LBB0_1014:
	ds_read_b128 v[146:149], v167
	ds_read_b128 v[150:153], v167 offset:1024
	ds_read_b128 v[154:157], v167 offset:2048
	ds_read_b128 v[158:161], v167 offset:3072
	ds_read_b128 v[172:175], v168
	ds_read_b128 v[176:179], v168 offset:1024
	ds_read_b128 v[180:183], v168 offset:2048
	ds_read_b128 v[184:187], v168 offset:3072
	s_add_i32 s71, s38, 2
	s_add_u32 s72, s36, 0x80
	s_addc_u32 s39, s37, 0
	s_cmp_eq_u32 s62, s38
	s_cselect_b32 s38, s6, s72
	s_cselect_b32 s39, s7, s39
	s_cselect_b32 s73, s23, s70
	s_cselect_b32 s72, s22, s33
	v_lshl_add_u64 v[162:163], s[36:37], 0, v[138:139]
	s_add_i32 m0, s48, 0xc000
	ds_read_b128 v[188:191], v169
	ds_read_b128 v[194:197], v169 offset:1024
	ds_read_b128 v[198:201], v169 offset:2048
	ds_read_b128 v[202:205], v169 offset:3072
	ds_read_b128 v[206:209], v169 offset:4096
	ds_read_b128 v[210:213], v169 offset:5120
	ds_read_b128 v[214:217], v169 offset:6144
	ds_read_b128 v[218:221], v169 offset:7168
	global_load_lds_dwordx4 v[162:163], off
	v_lshl_add_u64 v[162:163], s[36:37], 0, v[140:141]
	s_add_i32 m0, s48, 0xe000
	s_nop 0
	global_load_lds_dwordx4 v[162:163], off
	s_waitcnt vmcnt(8)
	s_waitcnt lgkmcnt(0)
	s_barrier
	s_waitcnt lgkmcnt(0)
	v_mfma_f32_16x16x32_bf16 v[120:123], v[146:149], v[188:191], v[120:123]
	v_mfma_f32_16x16x32_bf16 v[116:119], v[154:157], v[188:191], v[116:119]
	v_mfma_f32_16x16x32_bf16 v[108:111], v[146:149], v[198:201], v[108:111]
	v_mfma_f32_16x16x32_bf16 v[100:103], v[154:157], v[198:201], v[100:103]
	v_mfma_f32_16x16x32_bf16 v[92:95], v[146:149], v[206:209], v[92:95]
	v_mfma_f32_16x16x32_bf16 v[84:87], v[154:157], v[206:209], v[84:87]
	v_mfma_f32_16x16x32_bf16 v[76:79], v[146:149], v[214:217], v[76:79]
	v_mfma_f32_16x16x32_bf16 v[68:71], v[154:157], v[214:217], v[68:71]
	v_mfma_f32_16x16x32_bf16 v[120:123], v[150:153], v[194:197], v[120:123]
	v_mfma_f32_16x16x32_bf16 v[116:119], v[158:161], v[194:197], v[116:119]
	v_mfma_f32_16x16x32_bf16 v[108:111], v[150:153], v[202:205], v[108:111]
	v_mfma_f32_16x16x32_bf16 v[100:103], v[158:161], v[202:205], v[100:103]
	v_mfma_f32_16x16x32_bf16 v[92:95], v[150:153], v[210:213], v[92:95]
	v_mfma_f32_16x16x32_bf16 v[84:87], v[158:161], v[210:213], v[84:87]
	v_mfma_f32_16x16x32_bf16 v[76:79], v[150:153], v[218:221], v[76:79]
	v_mfma_f32_16x16x32_bf16 v[68:71], v[158:161], v[218:221], v[68:71]
	v_mfma_f32_16x16x32_bf16 v[124:127], v[172:175], v[188:191], v[124:127]
	v_mfma_f32_16x16x32_bf16 v[112:115], v[180:183], v[188:191], v[112:115]
	v_mfma_f32_16x16x32_bf16 v[104:107], v[172:175], v[198:201], v[104:107]
	v_mfma_f32_16x16x32_bf16 v[96:99], v[180:183], v[198:201], v[96:99]
	v_mfma_f32_16x16x32_bf16 v[88:91], v[172:175], v[206:209], v[88:91]
	v_mfma_f32_16x16x32_bf16 v[80:83], v[180:183], v[206:209], v[80:83]
	v_mfma_f32_16x16x32_bf16 v[72:75], v[172:175], v[214:217], v[72:75]
	v_mfma_f32_16x16x32_bf16 v[64:67], v[180:183], v[214:217], v[64:67]
	v_mfma_f32_16x16x32_bf16 v[124:127], v[176:179], v[194:197], v[124:127]
	v_mfma_f32_16x16x32_bf16 v[112:115], v[184:187], v[194:197], v[112:115]
	v_mfma_f32_16x16x32_bf16 v[104:107], v[176:179], v[202:205], v[104:107]
	v_mfma_f32_16x16x32_bf16 v[96:99], v[184:187], v[202:205], v[96:99]
	v_mfma_f32_16x16x32_bf16 v[88:91], v[176:179], v[210:213], v[88:91]
	v_mfma_f32_16x16x32_bf16 v[80:83], v[184:187], v[210:213], v[80:83]
	v_mfma_f32_16x16x32_bf16 v[72:75], v[176:179], v[218:221], v[72:75]
	v_mfma_f32_16x16x32_bf16 v[64:67], v[184:187], v[218:221], v[64:67]
	s_barrier
	s_add_i32 s74, s65, s41
	v_lshl_add_u64 v[162:163], s[72:73], 0, v[132:133]
	s_mov_b32 m0, s74
	ds_read_b128 v[188:191], v169 offset:16384
	ds_read_b128 v[194:197], v169 offset:17408
	ds_read_b128 v[198:201], v169 offset:18432
	ds_read_b128 v[202:205], v169 offset:19456
	ds_read_b128 v[206:209], v169 offset:20480
	ds_read_b128 v[210:213], v169 offset:21504
	ds_read_b128 v[214:217], v169 offset:22528
	ds_read_b128 v[218:221], v169 offset:23552
	global_load_lds_dwordx4 v[162:163], off
	s_add_i32 m0, s74, 0x2000
	v_lshl_add_u64 v[222:223], s[72:73], 0, v[128:129]
	s_add_u32 s72, s72, s10
	s_addc_u32 s73, s73, s11
	s_add_i32 s74, s66, s41
	global_load_lds_dwordx4 v[222:223], off
	v_lshl_add_u64 v[224:225], s[72:73], 0, v[132:133]
	s_mov_b32 m0, s74
	v_lshl_add_u64 v[226:227], s[72:73], 0, v[128:129]
	global_load_lds_dwordx4 v[224:225], off
	s_add_i32 m0, s74, 0x2000
	v_lshl_add_u64 v[228:229], s[38:39], 0, v[134:135]
	global_load_lds_dwordx4 v[226:227], off
	s_mov_b32 m0, s48
	v_lshl_add_u64 v[230:231], s[38:39], 0, v[130:131]
	global_load_lds_dwordx4 v[228:229], off
	s_mov_b32 m0, s49
	s_nop 0
	global_load_lds_dwordx4 v[230:231], off
	s_cmp_lg_u32 s71, 2
	s_cbranch_scc1 .Lss_p6_skip
	s_lshl_b32 s84, s4, 14
	s_mov_b32 s85, 0
	s_add_i32 m0, s48, 0x20000
	v_lshl_add_u64 v[238:239], v[236:237], 0, s[84:85]
	s_add_u32 s84, s84, 0x2000
	global_load_lds_dwordx4 v[238:239], off
	s_add_i32 m0, s48, 0x22000
	v_lshl_add_u64 v[238:239], v[236:237], 0, s[84:85]
	global_load_lds_dwordx4 v[238:239], off
; #define PG8_STAGE(bufoff, gbase, voff) do { _Pragma("unroll") for (int _i = 0; _i < 2; ++_i) \
;         __builtin_amdgcn_global_load_lds((const unsigned*)((const char*)(gbase) + (voff)[_i]), (PG8_LAS unsigned*)(lds + (bufoff) + ldsw + _i * 8192), 16, 0, 0); } while (0)
; #define PG8_LDA(dst, b, h) do { _Pragma("unroll") for (int m = 0; m < 4; ++m) _Pragma("unroll") for (int k = 0; k < 2; ++k) dst[m][k] = *(const PG8_LAS bf16x8*)(lds + PG8_SA(b, h) + aoff + m * 2048 + k * 1024); } while (0)
; #define PG8_LDB(dst, b, h) do { _Pragma("unroll") for (int n = 0; n < 2; ++n) _Pragma("unroll") for (int k = 0; k < 2; ++k) dst[n][k] = *(const PG8_LAS bf16x8*)(lds + PG8_SB(b, h) + boff + n * 2048 + k * 1024); } while (0)
; #define PG8_MMA(ai, bj, At, Bt) do { __builtin_amdgcn_s_setprio(1); _Pragma("unroll") for (int m = 0; m < 4; ++m) _Pragma("unroll") for (int n = 0; n < 2; ++n) _Pragma("unroll") for (int k = 0; k < 2; ++k) \
;         acc[ai][bj][m][n] = __builtin_amdgcn_mfma_f32_16x16x32_bf16(Bt[n][k], At[m][k], acc[ai][bj][m][n], 0, 0, 0); __builtin_amdgcn_s_setprio(0); } while (0)
; #define PG8_WAIT_V(n) asm volatile("s_waitcnt vmcnt(" #n ")" ::: "memory")
; #define PG8_WAIT_L(n) asm volatile("s_waitcnt lgkmcnt(" #n ")" ::: "memory")
; #define PG8_BAR __builtin_amdgcn_s_barrier()
; #define PG8_SCHED __builtin_amdgcn_sched_barrier(0)
; template <class Epi, class Sched, bool ALIGN_EPI = false, bool SP2 = false>
; __device__ __forceinline__ void gemm_phase(PG8_LAS unsigned char* lds, const Gemm g, const Sched& S, const Epi& E) {
;     ...
;             PG8_WAIT_V(8); PG8_WAIT_L(0); PG8_BAR; PG8_MMA(1, 0, At, B0); PG8_MMA(1, 1, At, B1); PG8_BAR; PG8_SCHED;
;             PG8_LDB(B0, 1, 0); PG8_LDB(B1, 1, 1); PG8_SCHED; PG8_LDA(At, 1, 0); PG8_STAGE(PG8_SA(0, 1), a2 + hstep, voffA);
;             PG8_WAIT_V(8); PG8_WAIT_L(0); PG8_BAR; PG8_MMA(0, 0, At, B0); PG8_MMA(0, 1, At, B1); PG8_BAR; PG8_SCHED;
.Lss_p6_skip:
	s_waitcnt vmcnt(8)
	s_waitcnt lgkmcnt(0)
	s_barrier
	s_waitcnt lgkmcnt(0)
	v_mfma_f32_16x16x32_bf16 v[60:63], v[146:149], v[188:191], v[60:63]
	v_mfma_f32_16x16x32_bf16 v[52:55], v[154:157], v[188:191], v[52:55]
	v_mfma_f32_16x16x32_bf16 v[44:47], v[146:149], v[198:201], v[44:47]
	v_mfma_f32_16x16x32_bf16 v[36:39], v[154:157], v[198:201], v[36:39]
	v_mfma_f32_16x16x32_bf16 v[28:31], v[146:149], v[206:209], v[28:31]
	v_mfma_f32_16x16x32_bf16 v[20:23], v[154:157], v[206:209], v[20:23]
	v_mfma_f32_16x16x32_bf16 v[12:15], v[146:149], v[214:217], v[12:15]
	v_mfma_f32_16x16x32_bf16 v[4:7], v[154:157], v[214:217], v[4:7]
	v_mfma_f32_16x16x32_bf16 v[60:63], v[150:153], v[194:197], v[60:63]
	v_mfma_f32_16x16x32_bf16 v[52:55], v[158:161], v[194:197], v[52:55]
	v_mfma_f32_16x16x32_bf16 v[44:47], v[150:153], v[202:205], v[44:47]
	v_mfma_f32_16x16x32_bf16 v[36:39], v[158:161], v[202:205], v[36:39]
	v_mfma_f32_16x16x32_bf16 v[28:31], v[150:153], v[210:213], v[28:31]
	v_mfma_f32_16x16x32_bf16 v[20:23], v[158:161], v[210:213], v[20:23]
	v_mfma_f32_16x16x32_bf16 v[12:15], v[150:153], v[218:221], v[12:15]
	v_mfma_f32_16x16x32_bf16 v[4:7], v[158:161], v[218:221], v[4:7]
	v_mfma_f32_16x16x32_bf16 v[56:59], v[172:175], v[188:191], v[56:59]
	v_mfma_f32_16x16x32_bf16 v[48:51], v[180:183], v[188:191], v[48:51]
	v_mfma_f32_16x16x32_bf16 v[40:43], v[172:175], v[198:201], v[40:43]
	v_mfma_f32_16x16x32_bf16 v[32:35], v[180:183], v[198:201], v[32:35]
	v_mfma_f32_16x16x32_bf16 v[24:27], v[172:175], v[206:209], v[24:27]
	v_mfma_f32_16x16x32_bf16 v[16:19], v[180:183], v[206:209], v[16:19]
	v_mfma_f32_16x16x32_bf16 v[8:11], v[172:175], v[214:217], v[8:11]
	v_mfma_f32_16x16x32_bf16 v[0:3], v[180:183], v[214:217], v[0:3]
	v_mfma_f32_16x16x32_bf16 v[56:59], v[176:179], v[194:197], v[56:59]
	v_mfma_f32_16x16x32_bf16 v[48:51], v[184:187], v[194:197], v[48:51]
	v_mfma_f32_16x16x32_bf16 v[40:43], v[176:179], v[202:205], v[40:43]
	v_mfma_f32_16x16x32_bf16 v[32:35], v[184:187], v[202:205], v[32:35]
	v_mfma_f32_16x16x32_bf16 v[24:27], v[176:179], v[210:213], v[24:27]
	v_mfma_f32_16x16x32_bf16 v[16:19], v[184:187], v[210:213], v[16:19]
	v_mfma_f32_16x16x32_bf16 v[8:11], v[176:179], v[218:221], v[8:11]
	v_mfma_f32_16x16x32_bf16 v[0:3], v[184:187], v[218:221], v[0:3]
	s_barrier
	s_add_i32 s72, 0, 0x18000
	s_add_i32 s73, 0, 0x1c000
	v_add_u32_e32 v158, s72, v165
	v_add_u32_e32 v184, s73, v165
	ds_read_b128 v[146:149], v158
	ds_read_b128 v[150:153], v158 offset:1024
	ds_read_b128 v[154:157], v158 offset:2048
	ds_read_b128 v[158:161], v158 offset:3072
	ds_read_b128 v[172:175], v184
	ds_read_b128 v[176:179], v184 offset:1024
	ds_read_b128 v[180:183], v184 offset:2048
	ds_read_b128 v[184:187], v184 offset:3072
	s_add_u32 s38, s38, s10
	s_addc_u32 s39, s39, s11
	s_mov_b32 m0, s56
	v_lshl_add_u64 v[232:233], s[38:39], 0, v[134:135]
	ds_read_b128 v[188:191], v169 offset:32768
	ds_read_b128 v[194:197], v169 offset:33792
	ds_read_b128 v[198:201], v169 offset:34816
	ds_read_b128 v[202:205], v169 offset:35840
	ds_read_b128 v[206:209], v169 offset:36864
	ds_read_b128 v[210:213], v169 offset:37888
	ds_read_b128 v[214:217], v169 offset:38912
	ds_read_b128 v[218:221], v169 offset:39936
	global_load_lds_dwordx4 v[232:233], off
	v_lshl_add_u64 v[232:233], s[38:39], 0, v[130:131]
	s_mov_b32 m0, s57
	s_nop 0
	global_load_lds_dwordx4 v[232:233], off
	s_waitcnt vmcnt(8)
	s_waitcnt lgkmcnt(0)
	s_barrier
	s_waitcnt lgkmcnt(0)
	v_mfma_f32_16x16x32_bf16 v[120:123], v[146:149], v[188:191], v[120:123]
	v_mfma_f32_16x16x32_bf16 v[116:119], v[154:157], v[188:191], v[116:119]
	v_mfma_f32_16x16x32_bf16 v[108:111], v[146:149], v[198:201], v[108:111]
	v_mfma_f32_16x16x32_bf16 v[100:103], v[154:157], v[198:201], v[100:103]
	v_mfma_f32_16x16x32_bf16 v[92:95], v[146:149], v[206:209], v[92:95]
	v_mfma_f32_16x16x32_bf16 v[84:87], v[154:157], v[206:209], v[84:87]
	v_mfma_f32_16x16x32_bf16 v[76:79], v[146:149], v[214:217], v[76:79]
	v_mfma_f32_16x16x32_bf16 v[68:71], v[154:157], v[214:217], v[68:71]
	v_mfma_f32_16x16x32_bf16 v[120:123], v[150:153], v[194:197], v[120:123]
	v_mfma_f32_16x16x32_bf16 v[116:119], v[158:161], v[194:197], v[116:119]
	v_mfma_f32_16x16x32_bf16 v[108:111], v[150:153], v[202:205], v[108:111]
	v_mfma_f32_16x16x32_bf16 v[100:103], v[158:161], v[202:205], v[100:103]
	v_mfma_f32_16x16x32_bf16 v[92:95], v[150:153], v[210:213], v[92:95]
	v_mfma_f32_16x16x32_bf16 v[84:87], v[158:161], v[210:213], v[84:87]
	v_mfma_f32_16x16x32_bf16 v[76:79], v[150:153], v[218:221], v[76:79]
	v_mfma_f32_16x16x32_bf16 v[68:71], v[158:161], v[218:221], v[68:71]
	v_mfma_f32_16x16x32_bf16 v[124:127], v[172:175], v[188:191], v[124:127]
	v_mfma_f32_16x16x32_bf16 v[112:115], v[180:183], v[188:191], v[112:115]
	v_mfma_f32_16x16x32_bf16 v[104:107], v[172:175], v[198:201], v[104:107]
	v_mfma_f32_16x16x32_bf16 v[96:99], v[180:183], v[198:201], v[96:99]
	v_mfma_f32_16x16x32_bf16 v[88:91], v[172:175], v[206:209], v[88:91]
	v_mfma_f32_16x16x32_bf16 v[80:83], v[180:183], v[206:209], v[80:83]
	v_mfma_f32_16x16x32_bf16 v[72:75], v[172:175], v[214:217], v[72:75]
	v_mfma_f32_16x16x32_bf16 v[64:67], v[180:183], v[214:217], v[64:67]
	v_mfma_f32_16x16x32_bf16 v[124:127], v[176:179], v[194:197], v[124:127]
	v_mfma_f32_16x16x32_bf16 v[112:115], v[184:187], v[194:197], v[112:115]
	v_mfma_f32_16x16x32_bf16 v[104:107], v[176:179], v[202:205], v[104:107]
	v_mfma_f32_16x16x32_bf16 v[96:99], v[184:187], v[202:205], v[96:99]
	v_mfma_f32_16x16x32_bf16 v[88:91], v[176:179], v[210:213], v[88:91]
	v_mfma_f32_16x16x32_bf16 v[80:83], v[184:187], v[210:213], v[80:83]
	v_mfma_f32_16x16x32_bf16 v[72:75], v[176:179], v[218:221], v[72:75]
	v_mfma_f32_16x16x32_bf16 v[64:67], v[184:187], v[218:221], v[64:67]
	s_barrier
; #define PG8_STAGE(bufoff, gbase, voff) do { _Pragma("unroll") for (int _i = 0; _i < 2; ++_i) \
;         __builtin_amdgcn_global_load_lds((const unsigned*)((const char*)(gbase) + (voff)[_i]), (PG8_LAS unsigned*)(lds + (bufoff) + ldsw + _i * 8192), 16, 0, 0); } while (0)
; #define PG8_LDA(dst, b, h) do { _Pragma("unroll") for (int m = 0; m < 4; ++m) _Pragma("unroll") for (int k = 0; k < 2; ++k) dst[m][k] = *(const PG8_LAS bf16x8*)(lds + PG8_SA(b, h) + aoff + m * 2048 + k * 1024); } while (0)
; #define PG8_MMA(ai, bj, At, Bt) do { __builtin_amdgcn_s_setprio(1); _Pragma("unroll") for (int m = 0; m < 4; ++m) _Pragma("unroll") for (int n = 0; n < 2; ++n) _Pragma("unroll") for (int k = 0; k < 2; ++k) \
;         acc[ai][bj][m][n] = __builtin_amdgcn_mfma_f32_16x16x32_bf16(Bt[n][k], At[m][k], acc[ai][bj][m][n], 0, 0, 0); __builtin_amdgcn_s_setprio(0); } while (0)
; #define PG8_WAIT_V(n) asm volatile("s_waitcnt vmcnt(" #n ")" ::: "memory")
; #define PG8_WAIT_L(n) asm volatile("s_waitcnt lgkmcnt(" #n ")" ::: "memory")
; #define PG8_BAR __builtin_amdgcn_s_barrier()
; #define PG8_SCHED __builtin_amdgcn_sched_barrier(0)
; template <class Epi, class Sched, bool ALIGN_EPI = false, bool SP2 = false>
; __device__ __forceinline__ void gemm_phase(PG8_LAS unsigned char* lds, const Gemm g, const Sched& S, const Epi& E) {
;     ...
;             PG8_LDA(At, 1, 1); PG8_STAGE(PG8_SB(1, 0), b3, voffB); PG8_STAGE(PG8_SB(1, 1), b3 + hstep, voffB); PG8_STAGE(PG8_SA(1, 0), a3, voffA);
;             PG8_WAIT_V(8); PG8_WAIT_L(0); PG8_BAR; PG8_MMA(1, 0, At, B0); PG8_MMA(1, 1, At, B1); PG8_BAR; PG8_SCHED;
	s_add_i32 s38, s72, s41
	v_lshl_add_u64 v[162:163], v[162:163], 0, s[16:17]
	s_mov_b32 m0, s38
	ds_read_b128 v[188:191], v169 offset:49152
	ds_read_b128 v[194:197], v169 offset:50176
	ds_read_b128 v[198:201], v169 offset:51200
	ds_read_b128 v[202:205], v169 offset:52224
	ds_read_b128 v[206:209], v169 offset:53248
	ds_read_b128 v[210:213], v169 offset:54272
	ds_read_b128 v[214:217], v169 offset:55296
	ds_read_b128 v[218:221], v169 offset:56320
	global_load_lds_dwordx4 v[162:163], off
	v_lshl_add_u64 v[162:163], v[222:223], 0, s[16:17]
	s_add_i32 m0, s38, 0x2000
	s_add_i32 s38, s73, s41
	global_load_lds_dwordx4 v[162:163], off
	v_lshl_add_u64 v[162:163], v[224:225], 0, s[16:17]
	s_mov_b32 m0, s38
	s_nop 0
	global_load_lds_dwordx4 v[162:163], off
	v_lshl_add_u64 v[162:163], v[226:227], 0, s[16:17]
	s_add_i32 m0, s38, 0x2000
	s_nop 0
	global_load_lds_dwordx4 v[162:163], off
	v_lshl_add_u64 v[162:163], v[228:229], 0, s[16:17]
	s_mov_b32 m0, s59
	s_nop 0
	global_load_lds_dwordx4 v[162:163], off
	v_lshl_add_u64 v[162:163], v[230:231], 0, s[16:17]
	s_mov_b32 m0, s60
	s_nop 0
	global_load_lds_dwordx4 v[162:163], off
	s_waitcnt vmcnt(8)
	s_waitcnt lgkmcnt(0)
	s_barrier
	s_waitcnt lgkmcnt(0)
	v_mfma_f32_16x16x32_bf16 v[60:63], v[146:149], v[188:191], v[60:63]
	v_mfma_f32_16x16x32_bf16 v[52:55], v[154:157], v[188:191], v[52:55]
	v_mfma_f32_16x16x32_bf16 v[44:47], v[146:149], v[198:201], v[44:47]
	v_mfma_f32_16x16x32_bf16 v[36:39], v[154:157], v[198:201], v[36:39]
	v_mfma_f32_16x16x32_bf16 v[28:31], v[146:149], v[206:209], v[28:31]
	v_mfma_f32_16x16x32_bf16 v[20:23], v[154:157], v[206:209], v[20:23]
	v_mfma_f32_16x16x32_bf16 v[12:15], v[146:149], v[214:217], v[12:15]
	v_mfma_f32_16x16x32_bf16 v[4:7], v[154:157], v[214:217], v[4:7]
	v_mfma_f32_16x16x32_bf16 v[60:63], v[150:153], v[194:197], v[60:63]
	v_mfma_f32_16x16x32_bf16 v[52:55], v[158:161], v[194:197], v[52:55]
	v_mfma_f32_16x16x32_bf16 v[44:47], v[150:153], v[202:205], v[44:47]
	v_mfma_f32_16x16x32_bf16 v[36:39], v[158:161], v[202:205], v[36:39]
	v_mfma_f32_16x16x32_bf16 v[28:31], v[150:153], v[210:213], v[28:31]
	v_mfma_f32_16x16x32_bf16 v[20:23], v[158:161], v[210:213], v[20:23]
	v_mfma_f32_16x16x32_bf16 v[12:15], v[150:153], v[218:221], v[12:15]
	v_mfma_f32_16x16x32_bf16 v[4:7], v[158:161], v[218:221], v[4:7]
	v_mfma_f32_16x16x32_bf16 v[56:59], v[172:175], v[188:191], v[56:59]
	v_mfma_f32_16x16x32_bf16 v[48:51], v[180:183], v[188:191], v[48:51]
	v_mfma_f32_16x16x32_bf16 v[40:43], v[172:175], v[198:201], v[40:43]
	v_mfma_f32_16x16x32_bf16 v[32:35], v[180:183], v[198:201], v[32:35]
	v_mfma_f32_16x16x32_bf16 v[24:27], v[172:175], v[206:209], v[24:27]
	v_mfma_f32_16x16x32_bf16 v[16:19], v[180:183], v[206:209], v[16:19]
	v_mfma_f32_16x16x32_bf16 v[8:11], v[172:175], v[214:217], v[8:11]
	v_mfma_f32_16x16x32_bf16 v[0:3], v[180:183], v[214:217], v[0:3]
	v_mfma_f32_16x16x32_bf16 v[56:59], v[176:179], v[194:197], v[56:59]
	v_mfma_f32_16x16x32_bf16 v[48:51], v[184:187], v[194:197], v[48:51]
	v_mfma_f32_16x16x32_bf16 v[40:43], v[176:179], v[202:205], v[40:43]
	v_mfma_f32_16x16x32_bf16 v[32:35], v[184:187], v[202:205], v[32:35]
	v_mfma_f32_16x16x32_bf16 v[24:27], v[176:179], v[210:213], v[24:27]
	v_mfma_f32_16x16x32_bf16 v[16:19], v[184:187], v[210:213], v[16:19]
	v_mfma_f32_16x16x32_bf16 v[8:11], v[176:179], v[218:221], v[8:11]
	v_mfma_f32_16x16x32_bf16 v[0:3], v[184:187], v[218:221], v[0:3]
	s_barrier
	s_add_u32 s36, s36, 0x100
	s_addc_u32 s37, s37, 0
	s_add_u32 s33, s33, 0x100
	s_addc_u32 s70, s70, 0
	s_cmp_ge_i32 s71, s61
	s_mov_b32 s38, s71
	s_cbranch_scc0 .LBB0_1014

; #define PG8_STAGE(bufoff, gbase, voff) do { _Pragma("unroll") for (int _i = 0; _i < 2; ++_i) \
;         __builtin_amdgcn_global_load_lds((const unsigned*)((const char*)(gbase) + (voff)[_i]), (PG8_LAS unsigned*)(lds + (bufoff) + ldsw + _i * 8192), 16, 0, 0); } while (0)
; #define PG8_LDA(dst, b, h) do { _Pragma("unroll") for (int m = 0; m < 4; ++m) _Pragma("unroll") for (int k = 0; k < 2; ++k) dst[m][k] = *(const PG8_LAS bf16x8*)(lds + PG8_SA(b, h) + aoff + m * 2048 + k * 1024); } while (0)
; #define PG8_LDB(dst, b, h) do { _Pragma("unroll") for (int n = 0; n < 2; ++n) _Pragma("unroll") for (int k = 0; k < 2; ++k) dst[n][k] = *(const PG8_LAS bf16x8*)(lds + PG8_SB(b, h) + boff + n * 2048 + k * 1024); } while (0)
; #define PG8_MMA(ai, bj, At, Bt) do { __builtin_amdgcn_s_setprio(1); _Pragma("unroll") for (int m = 0; m < 4; ++m) _Pragma("unroll") for (int n = 0; n < 2; ++n) _Pragma("unroll") for (int k = 0; k < 2; ++k) \
;         acc[ai][bj][m][n] = __builtin_amdgcn_mfma_f32_16x16x32_bf16(Bt[n][k], At[m][k], acc[ai][bj][m][n], 0, 0, 0); __builtin_amdgcn_s_setprio(0); } while (0)
; #define PG8_WAIT_V(n) asm volatile("s_waitcnt vmcnt(" #n ")" ::: "memory")
; #define PG8_BAR __builtin_amdgcn_s_barrier()
; template <class Epi, class Sched, bool ALIGN_EPI = false, bool SP2 = false>
; __device__ __forceinline__ void gemm_phase(PG8_LAS unsigned char* lds, const Gemm g, const Sched& S, const Epi& E) {
;     ...
;         for (int t = 0; t < nt; t += 2) {
;             const bool last = (t == nt - 2);
;             const char* a1 = cA + (size_t)(t + 1) * kstep;
;             const char* a2 = last ? nA : cA + (size_t)(t + 2) * kstep; const char* b2 = last ? nB : cB + (size_t)(t + 2) * kstep;
;             const char* a3 = a2 + kstep; const char* b3 = b2 + kstep;
;             if (last && has_next) S.a_ready(nxt);
;             if constexpr (SP2) {
;             PG8_LDB(B0, 0, 0); PG8_LDB(B1, 0, 1); PG8_SCHED; PG8_LDA(At, 0, 0); PG8_STAGE(PG8_SA(1, 1), a1 + hstep, voffA);
;             PG8_WAIT_V(8); PG8_WAIT_L(0); PG8_BAR; PG8_MMA(0, 0, At, B0); PG8_MMA(0, 1, At, B1); PG8_BAR; PG8_SCHED;
;             PG8_LDA(At, 0, 1); PG8_STAGE(PG8_SB(0, 0), b2, voffB); PG8_STAGE(PG8_SB(0, 1), b2 + hstep, voffB); PG8_STAGE(PG8_SA(0, 0), a2, voffA);
;             PG8_WAIT_V(8); PG8_WAIT_L(0); PG8_BAR; PG8_MMA(1, 0, At, B0); PG8_MMA(1, 1, At, B1); PG8_BAR; PG8_SCHED;
.LBB0_1034:
	ds_read_b128 v[150:153], v143
	ds_read_b128 v[154:157], v143 offset:1024
	ds_read_b128 v[158:161], v143 offset:2048
	ds_read_b128 v[162:165], v143 offset:3072
	ds_read_b128 v[166:169], v144
	ds_read_b128 v[170:173], v144 offset:1024
	ds_read_b128 v[174:177], v144 offset:2048
	ds_read_b128 v[178:181], v144 offset:3072
	s_add_i32 s86, s56, 2
	s_add_u32 s87, s54, 0x80
	s_addc_u32 s57, s55, 0
	s_cmp_eq_u32 s69, s56
	s_cselect_b32 s56, s40, s87
	s_cselect_b32 s57, s41, s57
	s_cselect_b32 s89, s43, s85
	s_cselect_b32 s88, s42, s33
	s_mov_b32 m0, s70
	v_lshl_add_u64 v[190:191], s[54:55], 0, v[138:139]
	ds_read_b128 v[182:185], v145
	ds_read_b128 v[186:189], v145 offset:1024
	ds_read_b128 v[194:197], v145 offset:2048
	ds_read_b128 v[198:201], v145 offset:3072
	ds_read_b128 v[202:205], v145 offset:4096
	ds_read_b128 v[206:209], v145 offset:5120
	ds_read_b128 v[210:213], v145 offset:6144
	ds_read_b128 v[214:217], v145 offset:7168
	global_load_lds_dwordx4 v[190:191], off
	v_lshl_add_u64 v[190:191], s[54:55], 0, v[140:141]
	s_mov_b32 m0, s71
	s_nop 0
	global_load_lds_dwordx4 v[190:191], off
	s_waitcnt vmcnt(8)
	s_waitcnt lgkmcnt(0)
	s_barrier
	s_waitcnt lgkmcnt(0)
	v_mfma_f32_16x16x32_bf16 v[124:127], v[150:153], v[182:185], v[124:127]
	v_mfma_f32_16x16x32_bf16 v[120:123], v[158:161], v[182:185], v[120:123]
	v_mfma_f32_16x16x32_bf16 v[108:111], v[150:153], v[194:197], v[108:111]
	v_mfma_f32_16x16x32_bf16 v[104:107], v[158:161], v[194:197], v[104:107]
	v_mfma_f32_16x16x32_bf16 v[92:95], v[150:153], v[202:205], v[92:95]
	v_mfma_f32_16x16x32_bf16 v[88:91], v[158:161], v[202:205], v[88:91]
	v_mfma_f32_16x16x32_bf16 v[76:79], v[150:153], v[210:213], v[76:79]
	v_mfma_f32_16x16x32_bf16 v[72:75], v[158:161], v[210:213], v[72:75]
	v_mfma_f32_16x16x32_bf16 v[124:127], v[154:157], v[186:189], v[124:127]
	v_mfma_f32_16x16x32_bf16 v[120:123], v[162:165], v[186:189], v[120:123]
	v_mfma_f32_16x16x32_bf16 v[108:111], v[154:157], v[198:201], v[108:111]
	v_mfma_f32_16x16x32_bf16 v[104:107], v[162:165], v[198:201], v[104:107]
	v_mfma_f32_16x16x32_bf16 v[92:95], v[154:157], v[206:209], v[92:95]
	v_mfma_f32_16x16x32_bf16 v[88:91], v[162:165], v[206:209], v[88:91]
	v_mfma_f32_16x16x32_bf16 v[76:79], v[154:157], v[214:217], v[76:79]
	v_mfma_f32_16x16x32_bf16 v[72:75], v[162:165], v[214:217], v[72:75]
	v_mfma_f32_16x16x32_bf16 v[116:119], v[166:169], v[182:185], v[116:119]
	v_mfma_f32_16x16x32_bf16 v[112:115], v[174:177], v[182:185], v[112:115]
	v_mfma_f32_16x16x32_bf16 v[100:103], v[166:169], v[194:197], v[100:103]
	v_mfma_f32_16x16x32_bf16 v[96:99], v[174:177], v[194:197], v[96:99]
	v_mfma_f32_16x16x32_bf16 v[84:87], v[166:169], v[202:205], v[84:87]
	v_mfma_f32_16x16x32_bf16 v[80:83], v[174:177], v[202:205], v[80:83]
	v_mfma_f32_16x16x32_bf16 v[68:71], v[166:169], v[210:213], v[68:71]
	v_mfma_f32_16x16x32_bf16 v[64:67], v[174:177], v[210:213], v[64:67]
	v_mfma_f32_16x16x32_bf16 v[116:119], v[170:173], v[186:189], v[116:119]
	v_mfma_f32_16x16x32_bf16 v[112:115], v[178:181], v[186:189], v[112:115]
	v_mfma_f32_16x16x32_bf16 v[100:103], v[170:173], v[198:201], v[100:103]
	v_mfma_f32_16x16x32_bf16 v[96:99], v[178:181], v[198:201], v[96:99]
	v_mfma_f32_16x16x32_bf16 v[84:87], v[170:173], v[206:209], v[84:87]
	v_mfma_f32_16x16x32_bf16 v[80:83], v[178:181], v[206:209], v[80:83]
	v_mfma_f32_16x16x32_bf16 v[68:71], v[170:173], v[214:217], v[68:71]
	v_mfma_f32_16x16x32_bf16 v[64:67], v[178:181], v[214:217], v[64:67]
	s_barrier
	s_mov_b32 m0, s72
	v_lshl_add_u64 v[190:191], s[88:89], 0, v[132:133]
	v_lshl_add_u64 v[218:219], s[88:89], 0, v[128:129]
	s_add_u32 s88, s88, s10
	ds_read_b128 v[182:185], v145 offset:16384
	ds_read_b128 v[186:189], v145 offset:17408
	ds_read_b128 v[194:197], v145 offset:18432
	ds_read_b128 v[198:201], v145 offset:19456
	ds_read_b128 v[202:205], v145 offset:20480
	ds_read_b128 v[206:209], v145 offset:21504
	ds_read_b128 v[210:213], v145 offset:22528
	ds_read_b128 v[214:217], v145 offset:23552
	global_load_lds_dwordx4 v[190:191], off
	s_mov_b32 m0, s73
	s_addc_u32 s89, s89, s11
	global_load_lds_dwordx4 v[218:219], off
	v_lshl_add_u64 v[220:221], s[88:89], 0, v[132:133]
	s_mov_b32 m0, s74
	v_lshl_add_u64 v[222:223], s[88:89], 0, v[128:129]
	global_load_lds_dwordx4 v[220:221], off
	s_mov_b32 m0, s75
	v_lshl_add_u64 v[224:225], s[56:57], 0, v[134:135]
	global_load_lds_dwordx4 v[222:223], off
	s_mov_b32 m0, s4
	v_lshl_add_u64 v[226:227], s[56:57], 0, v[130:131]
	global_load_lds_dwordx4 v[224:225], off
	s_mov_b32 m0, s5
	s_nop 0
	global_load_lds_dwordx4 v[226:227], off
	s_waitcnt vmcnt(8)
	s_waitcnt lgkmcnt(0)
	s_barrier
; #define PG8_STAGE(bufoff, gbase, voff) do { _Pragma("unroll") for (int _i = 0; _i < 2; ++_i) \
;         __builtin_amdgcn_global_load_lds((const unsigned*)((const char*)(gbase) + (voff)[_i]), (PG8_LAS unsigned*)(lds + (bufoff) + ldsw + _i * 8192), 16, 0, 0); } while (0)
; #define PG8_LDA(dst, b, h) do { _Pragma("unroll") for (int m = 0; m < 4; ++m) _Pragma("unroll") for (int k = 0; k < 2; ++k) dst[m][k] = *(const PG8_LAS bf16x8*)(lds + PG8_SA(b, h) + aoff + m * 2048 + k * 1024); } while (0)
; #define PG8_LDB(dst, b, h) do { _Pragma("unroll") for (int n = 0; n < 2; ++n) _Pragma("unroll") for (int k = 0; k < 2; ++k) dst[n][k] = *(const PG8_LAS bf16x8*)(lds + PG8_SB(b, h) + boff + n * 2048 + k * 1024); } while (0)
; #define PG8_MMA(ai, bj, At, Bt) do { __builtin_amdgcn_s_setprio(1); _Pragma("unroll") for (int m = 0; m < 4; ++m) _Pragma("unroll") for (int n = 0; n < 2; ++n) _Pragma("unroll") for (int k = 0; k < 2; ++k) \
;         acc[ai][bj][m][n] = __builtin_amdgcn_mfma_f32_16x16x32_bf16(Bt[n][k], At[m][k], acc[ai][bj][m][n], 0, 0, 0); __builtin_amdgcn_s_setprio(0); } while (0)
; #define PG8_WAIT_V(n) asm volatile("s_waitcnt vmcnt(" #n ")" ::: "memory")
; #define PG8_WAIT_L(n) asm volatile("s_waitcnt lgkmcnt(" #n ")" ::: "memory")
; #define PG8_BAR __builtin_amdgcn_s_barrier()
; #define PG8_SCHED __builtin_amdgcn_sched_barrier(0)
; template <class Epi, class Sched, bool ALIGN_EPI = false, bool SP2 = false>
; __device__ __forceinline__ void gemm_phase(PG8_LAS unsigned char* lds, const Gemm g, const Sched& S, const Epi& E) {
;     ...
;             PG8_WAIT_V(8); PG8_WAIT_L(0); PG8_BAR; PG8_MMA(1, 0, At, B0); PG8_MMA(1, 1, At, B1); PG8_BAR; PG8_SCHED;
;             PG8_LDB(B0, 1, 0); PG8_LDB(B1, 1, 1); PG8_SCHED; PG8_LDA(At, 1, 0); PG8_STAGE(PG8_SA(0, 1), a2 + hstep, voffA);
;             PG8_WAIT_V(8); PG8_WAIT_L(0); PG8_BAR; PG8_MMA(0, 0, At, B0); PG8_MMA(0, 1, At, B1); PG8_BAR; PG8_SCHED;
	s_waitcnt lgkmcnt(0)
	v_mfma_f32_16x16x32_bf16 v[60:63], v[150:153], v[182:185], v[60:63]
	v_mfma_f32_16x16x32_bf16 v[56:59], v[158:161], v[182:185], v[56:59]
	v_mfma_f32_16x16x32_bf16 v[44:47], v[150:153], v[194:197], v[44:47]
	v_mfma_f32_16x16x32_bf16 v[40:43], v[158:161], v[194:197], v[40:43]
	v_mfma_f32_16x16x32_bf16 v[28:31], v[150:153], v[202:205], v[28:31]
	v_mfma_f32_16x16x32_bf16 v[24:27], v[158:161], v[202:205], v[24:27]
	v_mfma_f32_16x16x32_bf16 v[12:15], v[150:153], v[210:213], v[12:15]
	v_mfma_f32_16x16x32_bf16 v[8:11], v[158:161], v[210:213], v[8:11]
	v_mfma_f32_16x16x32_bf16 v[60:63], v[154:157], v[186:189], v[60:63]
	v_mfma_f32_16x16x32_bf16 v[56:59], v[162:165], v[186:189], v[56:59]
	v_mfma_f32_16x16x32_bf16 v[44:47], v[154:157], v[198:201], v[44:47]
	v_mfma_f32_16x16x32_bf16 v[40:43], v[162:165], v[198:201], v[40:43]
	v_mfma_f32_16x16x32_bf16 v[28:31], v[154:157], v[206:209], v[28:31]
	v_mfma_f32_16x16x32_bf16 v[24:27], v[162:165], v[206:209], v[24:27]
	v_mfma_f32_16x16x32_bf16 v[12:15], v[154:157], v[214:217], v[12:15]
	v_mfma_f32_16x16x32_bf16 v[8:11], v[162:165], v[214:217], v[8:11]
	v_mfma_f32_16x16x32_bf16 v[52:55], v[166:169], v[182:185], v[52:55]
	v_mfma_f32_16x16x32_bf16 v[48:51], v[174:177], v[182:185], v[48:51]
	v_mfma_f32_16x16x32_bf16 v[36:39], v[166:169], v[194:197], v[36:39]
	v_mfma_f32_16x16x32_bf16 v[32:35], v[174:177], v[194:197], v[32:35]
	v_mfma_f32_16x16x32_bf16 v[20:23], v[166:169], v[202:205], v[20:23]
	v_mfma_f32_16x16x32_bf16 v[16:19], v[174:177], v[202:205], v[16:19]
	v_mfma_f32_16x16x32_bf16 v[4:7], v[166:169], v[210:213], v[4:7]
	v_mfma_f32_16x16x32_bf16 v[0:3], v[174:177], v[210:213], v[0:3]
	v_mfma_f32_16x16x32_bf16 v[52:55], v[170:173], v[186:189], v[52:55]
	v_mfma_f32_16x16x32_bf16 v[48:51], v[178:181], v[186:189], v[48:51]
	v_mfma_f32_16x16x32_bf16 v[36:39], v[170:173], v[198:201], v[36:39]
	v_mfma_f32_16x16x32_bf16 v[32:35], v[178:181], v[198:201], v[32:35]
	v_mfma_f32_16x16x32_bf16 v[20:23], v[170:173], v[206:209], v[20:23]
	v_mfma_f32_16x16x32_bf16 v[16:19], v[178:181], v[206:209], v[16:19]
	v_mfma_f32_16x16x32_bf16 v[4:7], v[170:173], v[214:217], v[4:7]
	v_mfma_f32_16x16x32_bf16 v[0:3], v[178:181], v[214:217], v[0:3]
	s_barrier
	ds_read_b128 v[150:153], v146
	ds_read_b128 v[154:157], v146 offset:1024
	ds_read_b128 v[158:161], v146 offset:2048
	ds_read_b128 v[162:165], v146 offset:3072
	ds_read_b128 v[166:169], v147
	ds_read_b128 v[170:173], v147 offset:1024
	ds_read_b128 v[174:177], v147 offset:2048
	ds_read_b128 v[178:181], v147 offset:3072
	s_add_u32 s56, s56, s10
	s_addc_u32 s57, s57, s11
	s_mov_b32 m0, s60
	v_lshl_add_u64 v[228:229], s[56:57], 0, v[134:135]
	ds_read_b128 v[182:185], v145 offset:32768
	ds_read_b128 v[186:189], v145 offset:33792
	ds_read_b128 v[194:197], v145 offset:34816
	ds_read_b128 v[198:201], v145 offset:35840
	ds_read_b128 v[202:205], v145 offset:36864
	ds_read_b128 v[206:209], v145 offset:37888
	ds_read_b128 v[210:213], v145 offset:38912
	ds_read_b128 v[214:217], v145 offset:39936
	global_load_lds_dwordx4 v[228:229], off
	v_lshl_add_u64 v[228:229], s[56:57], 0, v[130:131]
	s_mov_b32 m0, s61
	s_nop 0
	global_load_lds_dwordx4 v[228:229], off
	s_waitcnt vmcnt(8)
	s_waitcnt lgkmcnt(0)
	s_barrier
	s_waitcnt lgkmcnt(0)
	v_mfma_f32_16x16x32_bf16 v[124:127], v[150:153], v[182:185], v[124:127]
	v_mfma_f32_16x16x32_bf16 v[120:123], v[158:161], v[182:185], v[120:123]
	v_mfma_f32_16x16x32_bf16 v[108:111], v[150:153], v[194:197], v[108:111]
	v_mfma_f32_16x16x32_bf16 v[104:107], v[158:161], v[194:197], v[104:107]
	v_mfma_f32_16x16x32_bf16 v[92:95], v[150:153], v[202:205], v[92:95]
	v_mfma_f32_16x16x32_bf16 v[88:91], v[158:161], v[202:205], v[88:91]
	v_mfma_f32_16x16x32_bf16 v[76:79], v[150:153], v[210:213], v[76:79]
	v_mfma_f32_16x16x32_bf16 v[72:75], v[158:161], v[210:213], v[72:75]
	v_mfma_f32_16x16x32_bf16 v[124:127], v[154:157], v[186:189], v[124:127]
	v_mfma_f32_16x16x32_bf16 v[120:123], v[162:165], v[186:189], v[120:123]
	v_mfma_f32_16x16x32_bf16 v[108:111], v[154:157], v[198:201], v[108:111]
	v_mfma_f32_16x16x32_bf16 v[104:107], v[162:165], v[198:201], v[104:107]
	v_mfma_f32_16x16x32_bf16 v[92:95], v[154:157], v[206:209], v[92:95]
	v_mfma_f32_16x16x32_bf16 v[88:91], v[162:165], v[206:209], v[88:91]
	v_mfma_f32_16x16x32_bf16 v[76:79], v[154:157], v[214:217], v[76:79]
	v_mfma_f32_16x16x32_bf16 v[72:75], v[162:165], v[214:217], v[72:75]
	v_mfma_f32_16x16x32_bf16 v[116:119], v[166:169], v[182:185], v[116:119]
	v_mfma_f32_16x16x32_bf16 v[112:115], v[174:177], v[182:185], v[112:115]
	v_mfma_f32_16x16x32_bf16 v[100:103], v[166:169], v[194:197], v[100:103]
	v_mfma_f32_16x16x32_bf16 v[96:99], v[174:177], v[194:197], v[96:99]
	v_mfma_f32_16x16x32_bf16 v[84:87], v[166:169], v[202:205], v[84:87]
	v_mfma_f32_16x16x32_bf16 v[80:83], v[174:177], v[202:205], v[80:83]
	v_mfma_f32_16x16x32_bf16 v[68:71], v[166:169], v[210:213], v[68:71]
	v_mfma_f32_16x16x32_bf16 v[64:67], v[174:177], v[210:213], v[64:67]
	v_mfma_f32_16x16x32_bf16 v[116:119], v[170:173], v[186:189], v[116:119]
	v_mfma_f32_16x16x32_bf16 v[112:115], v[178:181], v[186:189], v[112:115]
	v_mfma_f32_16x16x32_bf16 v[100:103], v[170:173], v[198:201], v[100:103]
	v_mfma_f32_16x16x32_bf16 v[96:99], v[178:181], v[198:201], v[96:99]
	v_mfma_f32_16x16x32_bf16 v[84:87], v[170:173], v[206:209], v[84:87]
	v_mfma_f32_16x16x32_bf16 v[80:83], v[178:181], v[206:209], v[80:83]
	v_mfma_f32_16x16x32_bf16 v[68:71], v[170:173], v[214:217], v[68:71]
	v_mfma_f32_16x16x32_bf16 v[64:67], v[178:181], v[214:217], v[64:67]
	s_barrier
; #define PG8_STAGE(bufoff, gbase, voff) do { _Pragma("unroll") for (int _i = 0; _i < 2; ++_i) \
;         __builtin_amdgcn_global_load_lds((const unsigned*)((const char*)(gbase) + (voff)[_i]), (PG8_LAS unsigned*)(lds + (bufoff) + ldsw + _i * 8192), 16, 0, 0); } while (0)
; #define PG8_LDA(dst, b, h) do { _Pragma("unroll") for (int m = 0; m < 4; ++m) _Pragma("unroll") for (int k = 0; k < 2; ++k) dst[m][k] = *(const PG8_LAS bf16x8*)(lds + PG8_SA(b, h) + aoff + m * 2048 + k * 1024); } while (0)
; #define PG8_LDB(dst, b, h) do { _Pragma("unroll") for (int n = 0; n < 2; ++n) _Pragma("unroll") for (int k = 0; k < 2; ++k) dst[n][k] = *(const PG8_LAS bf16x8*)(lds + PG8_SB(b, h) + boff + n * 2048 + k * 1024); } while (0)
; #define PG8_MMA(ai, bj, At, Bt) do { __builtin_amdgcn_s_setprio(1); _Pragma("unroll") for (int m = 0; m < 4; ++m) _Pragma("unroll") for (int n = 0; n < 2; ++n) _Pragma("unroll") for (int k = 0; k < 2; ++k) \
;         acc[ai][bj][m][n] = __builtin_amdgcn_mfma_f32_16x16x32_bf16(Bt[n][k], At[m][k], acc[ai][bj][m][n], 0, 0, 0); __builtin_amdgcn_s_setprio(0); } while (0)
; #define PG8_WAIT_V(n) asm volatile("s_waitcnt vmcnt(" #n ")" ::: "memory")
; #define PG8_WAIT_L(n) asm volatile("s_waitcnt lgkmcnt(" #n ")" ::: "memory")
; template <class Epi, class Sched, bool ALIGN_EPI = false, bool SP2 = false>
; __device__ __forceinline__ void gemm_phase(PG8_LAS unsigned char* lds, const Gemm g, const Sched& S, const Epi& E) {
;     ...
;         for (int t = 0; t < nt; t += 2) {
;             const bool last = (t == nt - 2);
;             const char* a1 = cA + (size_t)(t + 1) * kstep;
;             const char* a2 = last ? nA : cA + (size_t)(t + 2) * kstep; const char* b2 = last ? nB : cB + (size_t)(t + 2) * kstep;
;             const char* a3 = a2 + kstep; const char* b3 = b2 + kstep;
;             if (last && has_next) S.a_ready(nxt);
;     ...
;             PG8_LDB(B0, 1, 0); PG8_LDB(B1, 1, 1); PG8_SCHED; PG8_LDA(At, 1, 0); PG8_STAGE(PG8_SA(0, 1), a2 + hstep, voffA);
;             PG8_WAIT_V(8); PG8_WAIT_L(0); PG8_BAR; PG8_MMA(0, 0, At, B0); PG8_MMA(0, 1, At, B1); PG8_BAR; PG8_SCHED;
;             PG8_LDA(At, 1, 1); PG8_STAGE(PG8_SB(1, 0), b3, voffB); PG8_STAGE(PG8_SB(1, 1), b3 + hstep, voffB); PG8_STAGE(PG8_SA(1, 0), a3, voffA);
;             PG8_WAIT_V(8); PG8_WAIT_L(0); PG8_BAR; PG8_MMA(1, 0, At, B0); PG8_MMA(1, 1, At, B1); PG8_BAR; PG8_SCHED;
	s_mov_b32 m0, s79
	v_lshl_add_u64 v[190:191], v[190:191], 0, s[16:17]
	ds_read_b128 v[182:185], v145 offset:49152
	ds_read_b128 v[186:189], v145 offset:50176
	ds_read_b128 v[194:197], v145 offset:51200
	ds_read_b128 v[198:201], v145 offset:52224
	ds_read_b128 v[202:205], v145 offset:53248
	ds_read_b128 v[206:209], v145 offset:54272
	ds_read_b128 v[210:213], v145 offset:55296
	ds_read_b128 v[214:217], v145 offset:56320
	global_load_lds_dwordx4 v[190:191], off
	v_lshl_add_u64 v[190:191], v[218:219], 0, s[16:17]
	s_mov_b32 m0, s80
	s_nop 0
	global_load_lds_dwordx4 v[190:191], off
	v_lshl_add_u64 v[190:191], v[220:221], 0, s[16:17]
	s_mov_b32 m0, s81
	s_nop 0
	global_load_lds_dwordx4 v[190:191], off
	v_lshl_add_u64 v[190:191], v[222:223], 0, s[16:17]
	s_mov_b32 m0, s82
	s_nop 0
	global_load_lds_dwordx4 v[190:191], off
	v_lshl_add_u64 v[190:191], v[224:225], 0, s[16:17]
	s_mov_b32 m0, s64
	s_nop 0
	global_load_lds_dwordx4 v[190:191], off
	v_lshl_add_u64 v[190:191], v[226:227], 0, s[16:17]
	s_mov_b32 m0, s65
	s_nop 0
	global_load_lds_dwordx4 v[190:191], off
	s_waitcnt vmcnt(8)
	s_waitcnt lgkmcnt(0)
	s_barrier
	s_waitcnt lgkmcnt(0)
	v_mfma_f32_16x16x32_bf16 v[60:63], v[150:153], v[182:185], v[60:63]
	v_mfma_f32_16x16x32_bf16 v[56:59], v[158:161], v[182:185], v[56:59]
	v_mfma_f32_16x16x32_bf16 v[44:47], v[150:153], v[194:197], v[44:47]
	v_mfma_f32_16x16x32_bf16 v[40:43], v[158:161], v[194:197], v[40:43]
	v_mfma_f32_16x16x32_bf16 v[28:31], v[150:153], v[202:205], v[28:31]
	v_mfma_f32_16x16x32_bf16 v[24:27], v[158:161], v[202:205], v[24:27]
	v_mfma_f32_16x16x32_bf16 v[12:15], v[150:153], v[210:213], v[12:15]
	v_mfma_f32_16x16x32_bf16 v[8:11], v[158:161], v[210:213], v[8:11]
	v_mfma_f32_16x16x32_bf16 v[60:63], v[154:157], v[186:189], v[60:63]
	v_mfma_f32_16x16x32_bf16 v[56:59], v[162:165], v[186:189], v[56:59]
	v_mfma_f32_16x16x32_bf16 v[44:47], v[154:157], v[198:201], v[44:47]
	v_mfma_f32_16x16x32_bf16 v[40:43], v[162:165], v[198:201], v[40:43]
	v_mfma_f32_16x16x32_bf16 v[28:31], v[154:157], v[206:209], v[28:31]
	v_mfma_f32_16x16x32_bf16 v[24:27], v[162:165], v[206:209], v[24:27]
	v_mfma_f32_16x16x32_bf16 v[12:15], v[154:157], v[214:217], v[12:15]
	v_mfma_f32_16x16x32_bf16 v[8:11], v[162:165], v[214:217], v[8:11]
	v_mfma_f32_16x16x32_bf16 v[52:55], v[166:169], v[182:185], v[52:55]
	v_mfma_f32_16x16x32_bf16 v[48:51], v[174:177], v[182:185], v[48:51]
	v_mfma_f32_16x16x32_bf16 v[36:39], v[166:169], v[194:197], v[36:39]
	v_mfma_f32_16x16x32_bf16 v[32:35], v[174:177], v[194:197], v[32:35]
	v_mfma_f32_16x16x32_bf16 v[20:23], v[166:169], v[202:205], v[20:23]
	v_mfma_f32_16x16x32_bf16 v[16:19], v[174:177], v[202:205], v[16:19]
	v_mfma_f32_16x16x32_bf16 v[4:7], v[166:169], v[210:213], v[4:7]
	v_mfma_f32_16x16x32_bf16 v[0:3], v[174:177], v[210:213], v[0:3]
	v_mfma_f32_16x16x32_bf16 v[52:55], v[170:173], v[186:189], v[52:55]
	v_mfma_f32_16x16x32_bf16 v[48:51], v[178:181], v[186:189], v[48:51]
	v_mfma_f32_16x16x32_bf16 v[36:39], v[170:173], v[198:201], v[36:39]
	v_mfma_f32_16x16x32_bf16 v[32:35], v[178:181], v[198:201], v[32:35]
	v_mfma_f32_16x16x32_bf16 v[20:23], v[170:173], v[206:209], v[20:23]
	v_mfma_f32_16x16x32_bf16 v[16:19], v[178:181], v[206:209], v[16:19]
	v_mfma_f32_16x16x32_bf16 v[4:7], v[170:173], v[214:217], v[4:7]
	v_mfma_f32_16x16x32_bf16 v[0:3], v[178:181], v[214:217], v[0:3]
	s_barrier
	s_add_u32 s54, s54, 0x100
	s_addc_u32 s55, s55, 0
	s_add_u32 s33, s33, 0x100
	s_addc_u32 s85, s85, 0
	s_cmp_ge_i32 s86, s67
	s_mov_b32 s56, s86
	s_cbranch_scc0 .LBB0_1034

; #define PG8_STAGE(bufoff, gbase, voff) do { _Pragma("unroll") for (int _i = 0; _i < 2; ++_i) \
;         __builtin_amdgcn_global_load_lds((const unsigned*)((const char*)(gbase) + (voff)[_i]), (PG8_LAS unsigned*)(lds + (bufoff) + ldsw + _i * 8192), 16, 0, 0); } while (0)
; #define PG8_LDA(dst, b, h) do { _Pragma("unroll") for (int m = 0; m < 4; ++m) _Pragma("unroll") for (int k = 0; k < 2; ++k) dst[m][k] = *(const PG8_LAS bf16x8*)(lds + PG8_SA(b, h) + aoff + m * 2048 + k * 1024); } while (0)
; #define PG8_LDB(dst, b, h) do { _Pragma("unroll") for (int n = 0; n < 2; ++n) _Pragma("unroll") for (int k = 0; k < 2; ++k) dst[n][k] = *(const PG8_LAS bf16x8*)(lds + PG8_SB(b, h) + boff + n * 2048 + k * 1024); } while (0)
; #define PG8_MMA(ai, bj, At, Bt) do { __builtin_amdgcn_s_setprio(1); _Pragma("unroll") for (int m = 0; m < 4; ++m) _Pragma("unroll") for (int n = 0; n < 2; ++n) _Pragma("unroll") for (int k = 0; k < 2; ++k) \
;         acc[ai][bj][m][n] = __builtin_amdgcn_mfma_f32_16x16x32_bf16(Bt[n][k], At[m][k], acc[ai][bj][m][n], 0, 0, 0); __builtin_amdgcn_s_setprio(0); } while (0)
; #define PG8_WAIT_V(n) asm volatile("s_waitcnt vmcnt(" #n ")" ::: "memory")
; #define PG8_BAR __builtin_amdgcn_s_barrier()
; template <class Epi, class Sched, bool ALIGN_EPI = false, bool SP2 = false>
; __device__ __forceinline__ void gemm_phase(PG8_LAS unsigned char* lds, const Gemm g, const Sched& S, const Epi& E) {
;     ...
;         for (int t = 0; t < nt; t += 2) {
;             const bool last = (t == nt - 2);
;             const char* a1 = cA + (size_t)(t + 1) * kstep;
;             const char* a2 = last ? nA : cA + (size_t)(t + 2) * kstep; const char* b2 = last ? nB : cB + (size_t)(t + 2) * kstep;
;             const char* a3 = a2 + kstep; const char* b3 = b2 + kstep;
;             if (last && has_next) S.a_ready(nxt);
;             if constexpr (SP2) {
;             PG8_LDB(B0, 0, 0); PG8_LDB(B1, 0, 1); PG8_SCHED; PG8_LDA(At, 0, 0); PG8_STAGE(PG8_SA(1, 1), a1 + hstep, voffA);
;             PG8_WAIT_V(8); PG8_WAIT_L(0); PG8_BAR; PG8_MMA(0, 0, At, B0); PG8_MMA(0, 1, At, B1); PG8_BAR; PG8_SCHED;
;             PG8_LDA(At, 0, 1); PG8_STAGE(PG8_SB(0, 0), b2, voffB); PG8_STAGE(PG8_SB(0, 1), b2 + hstep, voffB); PG8_STAGE(PG8_SA(0, 0), a2, voffA);
;             PG8_WAIT_V(8); PG8_WAIT_L(0); PG8_BAR; PG8_MMA(1, 0, At, B0); PG8_MMA(1, 1, At, B1); PG8_BAR; PG8_SCHED;
.LBB0_1118:
	ds_read_b128 v[142:145], v247
	ds_read_b128 v[146:149], v247 offset:1024
	ds_read_b128 v[150:153], v247 offset:2048
	ds_read_b128 v[154:157], v247 offset:3072
	ds_read_b128 v[158:161], v248
	ds_read_b128 v[162:165], v248 offset:1024
	ds_read_b128 v[166:169], v248 offset:2048
	ds_read_b128 v[170:173], v248 offset:3072
	s_add_i32 s72, s33, 2
	s_add_u32 s54, s42, 0x80
	s_addc_u32 s55, s43, 0
	s_cmp_eq_u32 s62, s33
	s_cselect_b32 s55, s9, s55
	s_cselect_b32 s54, s8, s54
	s_cselect_b32 s75, s41, s5
	s_cselect_b32 s74, s40, s4
	v_lshl_add_u64 v[190:191], s[42:43], 0, v[136:137]
	s_add_i32 m0, s48, 0xc000
	ds_read_b128 v[174:177], v249
	ds_read_b128 v[178:181], v249 offset:1024
	ds_read_b128 v[182:185], v249 offset:2048
	ds_read_b128 v[186:189], v249 offset:3072
	ds_read_b128 v[194:197], v249 offset:4096
	ds_read_b128 v[198:201], v249 offset:5120
	ds_read_b128 v[202:205], v249 offset:6144
	ds_read_b128 v[206:209], v249 offset:7168
	global_load_lds_dwordx4 v[190:191], off
	v_lshl_add_u64 v[190:191], s[42:43], 0, v[138:139]
	s_add_i32 m0, s48, 0xe000
	s_nop 0
	global_load_lds_dwordx4 v[190:191], off
	s_waitcnt vmcnt(8)
	s_waitcnt lgkmcnt(0)
	s_barrier
	s_waitcnt lgkmcnt(0)
	v_mfma_f32_16x16x32_bf16 v[124:127], v[142:145], v[174:177], v[124:127]
	v_mfma_f32_16x16x32_bf16 v[120:123], v[150:153], v[174:177], v[120:123]
	v_mfma_f32_16x16x32_bf16 v[116:119], v[142:145], v[182:185], v[116:119]
	v_mfma_f32_16x16x32_bf16 v[112:115], v[150:153], v[182:185], v[112:115]
	v_mfma_f32_16x16x32_bf16 v[104:107], v[142:145], v[194:197], v[104:107]
	v_mfma_f32_16x16x32_bf16 v[96:99], v[150:153], v[194:197], v[96:99]
	v_mfma_f32_16x16x32_bf16 v[88:91], v[142:145], v[202:205], v[88:91]
	v_mfma_f32_16x16x32_bf16 v[80:83], v[150:153], v[202:205], v[80:83]
	v_mfma_f32_16x16x32_bf16 v[124:127], v[146:149], v[178:181], v[124:127]
	v_mfma_f32_16x16x32_bf16 v[120:123], v[154:157], v[178:181], v[120:123]
	v_mfma_f32_16x16x32_bf16 v[116:119], v[146:149], v[186:189], v[116:119]
	v_mfma_f32_16x16x32_bf16 v[112:115], v[154:157], v[186:189], v[112:115]
	v_mfma_f32_16x16x32_bf16 v[104:107], v[146:149], v[198:201], v[104:107]
	v_mfma_f32_16x16x32_bf16 v[96:99], v[154:157], v[198:201], v[96:99]
	v_mfma_f32_16x16x32_bf16 v[88:91], v[146:149], v[206:209], v[88:91]
	v_mfma_f32_16x16x32_bf16 v[80:83], v[154:157], v[206:209], v[80:83]
	v_mfma_f32_16x16x32_bf16 v[108:111], v[158:161], v[174:177], v[108:111]
	v_mfma_f32_16x16x32_bf16 v[100:103], v[166:169], v[174:177], v[100:103]
	v_mfma_f32_16x16x32_bf16 v[92:95], v[158:161], v[182:185], v[92:95]
	v_mfma_f32_16x16x32_bf16 v[84:87], v[166:169], v[182:185], v[84:87]
	v_mfma_f32_16x16x32_bf16 v[76:79], v[158:161], v[194:197], v[76:79]
	v_mfma_f32_16x16x32_bf16 v[72:75], v[166:169], v[194:197], v[72:75]
	v_mfma_f32_16x16x32_bf16 v[68:71], v[158:161], v[202:205], v[68:71]
	v_mfma_f32_16x16x32_bf16 v[64:67], v[166:169], v[202:205], v[64:67]
	v_mfma_f32_16x16x32_bf16 v[108:111], v[162:165], v[178:181], v[108:111]
	v_mfma_f32_16x16x32_bf16 v[100:103], v[170:173], v[178:181], v[100:103]
	v_mfma_f32_16x16x32_bf16 v[92:95], v[162:165], v[186:189], v[92:95]
	v_mfma_f32_16x16x32_bf16 v[84:87], v[170:173], v[186:189], v[84:87]
	v_mfma_f32_16x16x32_bf16 v[76:79], v[162:165], v[198:201], v[76:79]
	v_mfma_f32_16x16x32_bf16 v[72:75], v[170:173], v[198:201], v[72:75]
	v_mfma_f32_16x16x32_bf16 v[68:71], v[162:165], v[206:209], v[68:71]
	v_mfma_f32_16x16x32_bf16 v[64:67], v[170:173], v[206:209], v[64:67]
	s_barrier
	s_add_i32 s33, s66, s3
	v_lshl_add_u64 v[190:191], s[74:75], 0, v[130:131]
	s_mov_b32 m0, s33
	ds_read_b128 v[174:177], v249 offset:16384
	ds_read_b128 v[178:181], v249 offset:17408
	ds_read_b128 v[182:185], v249 offset:18432
	ds_read_b128 v[186:189], v249 offset:19456
	ds_read_b128 v[194:197], v249 offset:20480
	ds_read_b128 v[198:201], v249 offset:21504
	ds_read_b128 v[202:205], v249 offset:22528
	ds_read_b128 v[206:209], v249 offset:23552
	global_load_lds_dwordx4 v[190:191], off
	s_add_i32 m0, s33, 0x2000
	v_lshl_add_u64 v[210:211], s[74:75], 0, v[134:135]
	s_add_u32 s74, s74, s14
	s_addc_u32 s75, s75, s15
	s_add_i32 s33, s67, s3
	global_load_lds_dwordx4 v[210:211], off
	v_lshl_add_u64 v[212:213], s[74:75], 0, v[130:131]
	s_mov_b32 m0, s33
	v_lshl_add_u64 v[214:215], s[74:75], 0, v[134:135]
	global_load_lds_dwordx4 v[212:213], off
	s_add_i32 m0, s33, 0x2000
	v_lshl_add_u64 v[216:217], s[54:55], 0, v[128:129]
	global_load_lds_dwordx4 v[214:215], off
	s_mov_b32 m0, s48
	v_lshl_add_u64 v[218:219], s[54:55], 0, v[132:133]
	global_load_lds_dwordx4 v[216:217], off
	s_mov_b32 m0, s49
	s_nop 0
	global_load_lds_dwordx4 v[218:219], off
	s_waitcnt vmcnt(8)
	s_waitcnt lgkmcnt(0)
	s_barrier
; #define PG8_STAGE(bufoff, gbase, voff) do { _Pragma("unroll") for (int _i = 0; _i < 2; ++_i) \
;         __builtin_amdgcn_global_load_lds((const unsigned*)((const char*)(gbase) + (voff)[_i]), (PG8_LAS unsigned*)(lds + (bufoff) + ldsw + _i * 8192), 16, 0, 0); } while (0)
; #define PG8_LDA(dst, b, h) do { _Pragma("unroll") for (int m = 0; m < 4; ++m) _Pragma("unroll") for (int k = 0; k < 2; ++k) dst[m][k] = *(const PG8_LAS bf16x8*)(lds + PG8_SA(b, h) + aoff + m * 2048 + k * 1024); } while (0)
; #define PG8_LDB(dst, b, h) do { _Pragma("unroll") for (int n = 0; n < 2; ++n) _Pragma("unroll") for (int k = 0; k < 2; ++k) dst[n][k] = *(const PG8_LAS bf16x8*)(lds + PG8_SB(b, h) + boff + n * 2048 + k * 1024); } while (0)
; #define PG8_MMA(ai, bj, At, Bt) do { __builtin_amdgcn_s_setprio(1); _Pragma("unroll") for (int m = 0; m < 4; ++m) _Pragma("unroll") for (int n = 0; n < 2; ++n) _Pragma("unroll") for (int k = 0; k < 2; ++k) \
;         acc[ai][bj][m][n] = __builtin_amdgcn_mfma_f32_16x16x32_bf16(Bt[n][k], At[m][k], acc[ai][bj][m][n], 0, 0, 0); __builtin_amdgcn_s_setprio(0); } while (0)
; #define PG8_WAIT_V(n) asm volatile("s_waitcnt vmcnt(" #n ")" ::: "memory")
; #define PG8_WAIT_L(n) asm volatile("s_waitcnt lgkmcnt(" #n ")" ::: "memory")
; #define PG8_BAR __builtin_amdgcn_s_barrier()
; #define PG8_SCHED __builtin_amdgcn_sched_barrier(0)
; template <class Epi, class Sched, bool ALIGN_EPI = false, bool SP2 = false>
; __device__ __forceinline__ void gemm_phase(PG8_LAS unsigned char* lds, const Gemm g, const Sched& S, const Epi& E) {
;     ...
;             PG8_WAIT_V(8); PG8_WAIT_L(0); PG8_BAR; PG8_MMA(1, 0, At, B0); PG8_MMA(1, 1, At, B1); PG8_BAR; PG8_SCHED;
;             PG8_LDB(B0, 1, 0); PG8_LDB(B1, 1, 1); PG8_SCHED; PG8_LDA(At, 1, 0); PG8_STAGE(PG8_SA(0, 1), a2 + hstep, voffA);
;             PG8_WAIT_V(8); PG8_WAIT_L(0); PG8_BAR; PG8_MMA(0, 0, At, B0); PG8_MMA(0, 1, At, B1); PG8_BAR; PG8_SCHED;
	s_waitcnt lgkmcnt(0)
	v_mfma_f32_16x16x32_bf16 v[60:63], v[142:145], v[174:177], v[60:63]
	v_mfma_f32_16x16x32_bf16 v[56:59], v[150:153], v[174:177], v[56:59]
	v_mfma_f32_16x16x32_bf16 v[52:55], v[142:145], v[182:185], v[52:55]
	v_mfma_f32_16x16x32_bf16 v[48:51], v[150:153], v[182:185], v[48:51]
	v_mfma_f32_16x16x32_bf16 v[40:43], v[142:145], v[194:197], v[40:43]
	v_mfma_f32_16x16x32_bf16 v[32:35], v[150:153], v[194:197], v[32:35]
	v_mfma_f32_16x16x32_bf16 v[24:27], v[142:145], v[202:205], v[24:27]
	v_mfma_f32_16x16x32_bf16 v[16:19], v[150:153], v[202:205], v[16:19]
	v_mfma_f32_16x16x32_bf16 v[60:63], v[146:149], v[178:181], v[60:63]
	v_mfma_f32_16x16x32_bf16 v[56:59], v[154:157], v[178:181], v[56:59]
	v_mfma_f32_16x16x32_bf16 v[52:55], v[146:149], v[186:189], v[52:55]
	v_mfma_f32_16x16x32_bf16 v[48:51], v[154:157], v[186:189], v[48:51]
	v_mfma_f32_16x16x32_bf16 v[40:43], v[146:149], v[198:201], v[40:43]
	v_mfma_f32_16x16x32_bf16 v[32:35], v[154:157], v[198:201], v[32:35]
	v_mfma_f32_16x16x32_bf16 v[24:27], v[146:149], v[206:209], v[24:27]
	v_mfma_f32_16x16x32_bf16 v[16:19], v[154:157], v[206:209], v[16:19]
	v_mfma_f32_16x16x32_bf16 v[44:47], v[158:161], v[174:177], v[44:47]
	v_mfma_f32_16x16x32_bf16 v[36:39], v[166:169], v[174:177], v[36:39]
	v_mfma_f32_16x16x32_bf16 v[28:31], v[158:161], v[182:185], v[28:31]
	v_mfma_f32_16x16x32_bf16 v[20:23], v[166:169], v[182:185], v[20:23]
	v_mfma_f32_16x16x32_bf16 v[12:15], v[158:161], v[194:197], v[12:15]
	v_mfma_f32_16x16x32_bf16 v[8:11], v[166:169], v[194:197], v[8:11]
	v_mfma_f32_16x16x32_bf16 v[4:7], v[158:161], v[202:205], v[4:7]
	v_mfma_f32_16x16x32_bf16 v[0:3], v[166:169], v[202:205], v[0:3]
	v_mfma_f32_16x16x32_bf16 v[44:47], v[162:165], v[178:181], v[44:47]
	v_mfma_f32_16x16x32_bf16 v[36:39], v[170:173], v[178:181], v[36:39]
	v_mfma_f32_16x16x32_bf16 v[28:31], v[162:165], v[186:189], v[28:31]
	v_mfma_f32_16x16x32_bf16 v[20:23], v[170:173], v[186:189], v[20:23]
	v_mfma_f32_16x16x32_bf16 v[12:15], v[162:165], v[198:201], v[12:15]
	v_mfma_f32_16x16x32_bf16 v[8:11], v[170:173], v[198:201], v[8:11]
	v_mfma_f32_16x16x32_bf16 v[4:7], v[162:165], v[206:209], v[4:7]
	v_mfma_f32_16x16x32_bf16 v[0:3], v[170:173], v[206:209], v[0:3]
	s_barrier
	s_add_i32 s33, 0, 0x18000
	s_add_i32 s73, 0, 0x1c000
	v_add_u32_e32 v154, s33, v244
	v_add_u32_e32 v170, s73, v244
	ds_read_b128 v[142:145], v154
	ds_read_b128 v[146:149], v154 offset:1024
	ds_read_b128 v[150:153], v154 offset:2048
	ds_read_b128 v[154:157], v154 offset:3072
	ds_read_b128 v[158:161], v170
	ds_read_b128 v[162:165], v170 offset:1024
	ds_read_b128 v[166:169], v170 offset:2048
	ds_read_b128 v[170:173], v170 offset:3072
	s_add_u32 s54, s54, s14
	s_addc_u32 s55, s55, s15
	s_mov_b32 m0, s56
	v_lshl_add_u64 v[220:221], s[54:55], 0, v[128:129]
	ds_read_b128 v[174:177], v249 offset:32768
	ds_read_b128 v[178:181], v249 offset:33792
	ds_read_b128 v[182:185], v249 offset:34816
	ds_read_b128 v[186:189], v249 offset:35840
	ds_read_b128 v[194:197], v249 offset:36864
	ds_read_b128 v[198:201], v249 offset:37888
	ds_read_b128 v[202:205], v249 offset:38912
	ds_read_b128 v[206:209], v249 offset:39936
	global_load_lds_dwordx4 v[220:221], off
	v_lshl_add_u64 v[220:221], s[54:55], 0, v[132:133]
	s_mov_b32 m0, s57
	s_nop 0
	global_load_lds_dwordx4 v[220:221], off
	s_waitcnt vmcnt(8)
	s_waitcnt lgkmcnt(0)
	s_barrier
	s_waitcnt lgkmcnt(0)
	v_mfma_f32_16x16x32_bf16 v[124:127], v[142:145], v[174:177], v[124:127]
	v_mfma_f32_16x16x32_bf16 v[120:123], v[150:153], v[174:177], v[120:123]
	v_mfma_f32_16x16x32_bf16 v[116:119], v[142:145], v[182:185], v[116:119]
	v_mfma_f32_16x16x32_bf16 v[112:115], v[150:153], v[182:185], v[112:115]
	v_mfma_f32_16x16x32_bf16 v[104:107], v[142:145], v[194:197], v[104:107]
	v_mfma_f32_16x16x32_bf16 v[96:99], v[150:153], v[194:197], v[96:99]
	v_mfma_f32_16x16x32_bf16 v[88:91], v[142:145], v[202:205], v[88:91]
	v_mfma_f32_16x16x32_bf16 v[80:83], v[150:153], v[202:205], v[80:83]
	v_mfma_f32_16x16x32_bf16 v[124:127], v[146:149], v[178:181], v[124:127]
	v_mfma_f32_16x16x32_bf16 v[120:123], v[154:157], v[178:181], v[120:123]
	v_mfma_f32_16x16x32_bf16 v[116:119], v[146:149], v[186:189], v[116:119]
	v_mfma_f32_16x16x32_bf16 v[112:115], v[154:157], v[186:189], v[112:115]
	v_mfma_f32_16x16x32_bf16 v[104:107], v[146:149], v[198:201], v[104:107]
	v_mfma_f32_16x16x32_bf16 v[96:99], v[154:157], v[198:201], v[96:99]
	v_mfma_f32_16x16x32_bf16 v[88:91], v[146:149], v[206:209], v[88:91]
	v_mfma_f32_16x16x32_bf16 v[80:83], v[154:157], v[206:209], v[80:83]
	v_mfma_f32_16x16x32_bf16 v[108:111], v[158:161], v[174:177], v[108:111]
	v_mfma_f32_16x16x32_bf16 v[100:103], v[166:169], v[174:177], v[100:103]
	v_mfma_f32_16x16x32_bf16 v[92:95], v[158:161], v[182:185], v[92:95]
	v_mfma_f32_16x16x32_bf16 v[84:87], v[166:169], v[182:185], v[84:87]
	v_mfma_f32_16x16x32_bf16 v[76:79], v[158:161], v[194:197], v[76:79]
	v_mfma_f32_16x16x32_bf16 v[72:75], v[166:169], v[194:197], v[72:75]
	v_mfma_f32_16x16x32_bf16 v[68:71], v[158:161], v[202:205], v[68:71]
	v_mfma_f32_16x16x32_bf16 v[64:67], v[166:169], v[202:205], v[64:67]
	v_mfma_f32_16x16x32_bf16 v[108:111], v[162:165], v[178:181], v[108:111]
	v_mfma_f32_16x16x32_bf16 v[100:103], v[170:173], v[178:181], v[100:103]
	v_mfma_f32_16x16x32_bf16 v[92:95], v[162:165], v[186:189], v[92:95]
	v_mfma_f32_16x16x32_bf16 v[84:87], v[170:173], v[186:189], v[84:87]
	v_mfma_f32_16x16x32_bf16 v[76:79], v[162:165], v[198:201], v[76:79]
	v_mfma_f32_16x16x32_bf16 v[72:75], v[170:173], v[198:201], v[72:75]
	v_mfma_f32_16x16x32_bf16 v[68:71], v[162:165], v[206:209], v[68:71]
	v_mfma_f32_16x16x32_bf16 v[64:67], v[170:173], v[206:209], v[64:67]
	s_barrier
; #define PG8_STAGE(bufoff, gbase, voff) do { _Pragma("unroll") for (int _i = 0; _i < 2; ++_i) \
;         __builtin_amdgcn_global_load_lds((const unsigned*)((const char*)(gbase) + (voff)[_i]), (PG8_LAS unsigned*)(lds + (bufoff) + ldsw + _i * 8192), 16, 0, 0); } while (0)
; #define PG8_LDA(dst, b, h) do { _Pragma("unroll") for (int m = 0; m < 4; ++m) _Pragma("unroll") for (int k = 0; k < 2; ++k) dst[m][k] = *(const PG8_LAS bf16x8*)(lds + PG8_SA(b, h) + aoff + m * 2048 + k * 1024); } while (0)
; #define PG8_LDB(dst, b, h) do { _Pragma("unroll") for (int n = 0; n < 2; ++n) _Pragma("unroll") for (int k = 0; k < 2; ++k) dst[n][k] = *(const PG8_LAS bf16x8*)(lds + PG8_SB(b, h) + boff + n * 2048 + k * 1024); } while (0)
; #define PG8_MMA(ai, bj, At, Bt) do { __builtin_amdgcn_s_setprio(1); _Pragma("unroll") for (int m = 0; m < 4; ++m) _Pragma("unroll") for (int n = 0; n < 2; ++n) _Pragma("unroll") for (int k = 0; k < 2; ++k) \
;         acc[ai][bj][m][n] = __builtin_amdgcn_mfma_f32_16x16x32_bf16(Bt[n][k], At[m][k], acc[ai][bj][m][n], 0, 0, 0); __builtin_amdgcn_s_setprio(0); } while (0)
; #define PG8_WAIT_V(n) asm volatile("s_waitcnt vmcnt(" #n ")" ::: "memory")
; #define PG8_WAIT_L(n) asm volatile("s_waitcnt lgkmcnt(" #n ")" ::: "memory")
; template <class Epi, class Sched, bool ALIGN_EPI = false, bool SP2 = false>
; __device__ __forceinline__ void gemm_phase(PG8_LAS unsigned char* lds, const Gemm g, const Sched& S, const Epi& E) {
;     ...
;         for (int t = 0; t < nt; t += 2) {
;             const bool last = (t == nt - 2);
;             const char* a1 = cA + (size_t)(t + 1) * kstep;
;             const char* a2 = last ? nA : cA + (size_t)(t + 2) * kstep; const char* b2 = last ? nB : cB + (size_t)(t + 2) * kstep;
;             const char* a3 = a2 + kstep; const char* b3 = b2 + kstep;
;             if (last && has_next) S.a_ready(nxt);
;     ...
;             PG8_LDB(B0, 1, 0); PG8_LDB(B1, 1, 1); PG8_SCHED; PG8_LDA(At, 1, 0); PG8_STAGE(PG8_SA(0, 1), a2 + hstep, voffA);
;             PG8_WAIT_V(8); PG8_WAIT_L(0); PG8_BAR; PG8_MMA(0, 0, At, B0); PG8_MMA(0, 1, At, B1); PG8_BAR; PG8_SCHED;
;             PG8_LDA(At, 1, 1); PG8_STAGE(PG8_SB(1, 0), b3, voffB); PG8_STAGE(PG8_SB(1, 1), b3 + hstep, voffB); PG8_STAGE(PG8_SA(1, 0), a3, voffA);
;             PG8_WAIT_V(8); PG8_WAIT_L(0); PG8_BAR; PG8_MMA(1, 0, At, B0); PG8_MMA(1, 1, At, B1); PG8_BAR; PG8_SCHED;
	s_add_i32 s33, s33, s3
	v_lshl_add_u64 v[190:191], v[190:191], 0, s[22:23]
	s_mov_b32 m0, s33
	ds_read_b128 v[174:177], v249 offset:49152
	ds_read_b128 v[178:181], v249 offset:50176
	ds_read_b128 v[182:185], v249 offset:51200
	ds_read_b128 v[186:189], v249 offset:52224
	ds_read_b128 v[194:197], v249 offset:53248
	ds_read_b128 v[198:201], v249 offset:54272
	ds_read_b128 v[202:205], v249 offset:55296
	ds_read_b128 v[206:209], v249 offset:56320
	global_load_lds_dwordx4 v[190:191], off
	v_lshl_add_u64 v[190:191], v[210:211], 0, s[22:23]
	s_add_i32 m0, s33, 0x2000
	s_add_i32 s33, s73, s3
	global_load_lds_dwordx4 v[190:191], off
	v_lshl_add_u64 v[190:191], v[212:213], 0, s[22:23]
	s_mov_b32 m0, s33
	s_nop 0
	global_load_lds_dwordx4 v[190:191], off
	v_lshl_add_u64 v[190:191], v[214:215], 0, s[22:23]
	s_add_i32 m0, s33, 0x2000
	s_nop 0
	global_load_lds_dwordx4 v[190:191], off
	v_lshl_add_u64 v[190:191], v[216:217], 0, s[22:23]
	s_mov_b32 m0, s58
	s_nop 0
	global_load_lds_dwordx4 v[190:191], off
	v_lshl_add_u64 v[190:191], v[218:219], 0, s[22:23]
	s_mov_b32 m0, s59
	s_nop 0
	global_load_lds_dwordx4 v[190:191], off
	s_waitcnt vmcnt(8)
	s_waitcnt lgkmcnt(0)
	s_barrier
	s_waitcnt lgkmcnt(0)
	v_mfma_f32_16x16x32_bf16 v[60:63], v[142:145], v[174:177], v[60:63]
	v_mfma_f32_16x16x32_bf16 v[56:59], v[150:153], v[174:177], v[56:59]
	v_mfma_f32_16x16x32_bf16 v[52:55], v[142:145], v[182:185], v[52:55]
	v_mfma_f32_16x16x32_bf16 v[48:51], v[150:153], v[182:185], v[48:51]
	v_mfma_f32_16x16x32_bf16 v[40:43], v[142:145], v[194:197], v[40:43]
	v_mfma_f32_16x16x32_bf16 v[32:35], v[150:153], v[194:197], v[32:35]
	v_mfma_f32_16x16x32_bf16 v[24:27], v[142:145], v[202:205], v[24:27]
	v_mfma_f32_16x16x32_bf16 v[16:19], v[150:153], v[202:205], v[16:19]
	v_mfma_f32_16x16x32_bf16 v[60:63], v[146:149], v[178:181], v[60:63]
	v_mfma_f32_16x16x32_bf16 v[56:59], v[154:157], v[178:181], v[56:59]
	v_mfma_f32_16x16x32_bf16 v[52:55], v[146:149], v[186:189], v[52:55]
	v_mfma_f32_16x16x32_bf16 v[48:51], v[154:157], v[186:189], v[48:51]
	v_mfma_f32_16x16x32_bf16 v[40:43], v[146:149], v[198:201], v[40:43]
	v_mfma_f32_16x16x32_bf16 v[32:35], v[154:157], v[198:201], v[32:35]
	v_mfma_f32_16x16x32_bf16 v[24:27], v[146:149], v[206:209], v[24:27]
	v_mfma_f32_16x16x32_bf16 v[16:19], v[154:157], v[206:209], v[16:19]
	v_mfma_f32_16x16x32_bf16 v[44:47], v[158:161], v[174:177], v[44:47]
	v_mfma_f32_16x16x32_bf16 v[36:39], v[166:169], v[174:177], v[36:39]
	v_mfma_f32_16x16x32_bf16 v[28:31], v[158:161], v[182:185], v[28:31]
	v_mfma_f32_16x16x32_bf16 v[20:23], v[166:169], v[182:185], v[20:23]
	v_mfma_f32_16x16x32_bf16 v[12:15], v[158:161], v[194:197], v[12:15]
	v_mfma_f32_16x16x32_bf16 v[8:11], v[166:169], v[194:197], v[8:11]
	v_mfma_f32_16x16x32_bf16 v[4:7], v[158:161], v[202:205], v[4:7]
	v_mfma_f32_16x16x32_bf16 v[0:3], v[166:169], v[202:205], v[0:3]
	v_mfma_f32_16x16x32_bf16 v[44:47], v[162:165], v[178:181], v[44:47]
	v_mfma_f32_16x16x32_bf16 v[36:39], v[170:173], v[178:181], v[36:39]
	v_mfma_f32_16x16x32_bf16 v[28:31], v[162:165], v[186:189], v[28:31]
	v_mfma_f32_16x16x32_bf16 v[20:23], v[170:173], v[186:189], v[20:23]
	v_mfma_f32_16x16x32_bf16 v[12:15], v[162:165], v[198:201], v[12:15]
	v_mfma_f32_16x16x32_bf16 v[8:11], v[170:173], v[198:201], v[8:11]
	v_mfma_f32_16x16x32_bf16 v[4:7], v[162:165], v[206:209], v[4:7]
	v_mfma_f32_16x16x32_bf16 v[0:3], v[170:173], v[206:209], v[0:3]
	s_barrier
	s_add_u32 s42, s42, 0x100
	s_addc_u32 s43, s43, 0
	s_add_u32 s4, s4, 0x100
	s_addc_u32 s5, s5, 0
	s_cmp_ge_i32 s72, s61
	s_mov_b32 s33, s72
	s_cbranch_scc0 .LBB0_1118
;     __device__ __forceinline__ void operator()(const f32x4 (&acc)[2][2][4][2], const Unit& u, int wr, int wc, int fr, int fq) const {
;     ...
;                     v0 += acc[ai][bj][m][0] * alpha; v1 += acc[ai][bj][m][1] * alpha;
	v_pk_mul_f32 v[220:221], v[126:127], 0.5 op_sel_hi:[1,0]
	v_pk_mul_f32 v[222:223], v[124:125], 0.5 op_sel_hi:[1,0]
	v_pk_mul_f32 v[224:225], v[122:123], 0.5 op_sel_hi:[1,0]
	v_pk_mul_f32 v[226:227], v[120:121], 0.5 op_sel_hi:[1,0]
	v_pk_mul_f32 v[214:215], v[110:111], 0.5 op_sel_hi:[1,0]
	v_pk_mul_f32 v[212:213], v[108:109], 0.5 op_sel_hi:[1,0]
	v_pk_mul_f32 v[210:211], v[102:103], 0.5 op_sel_hi:[1,0]
	v_pk_mul_f32 v[206:207], v[100:101], 0.5 op_sel_hi:[1,0]
	v_pk_mul_f32 v[198:199], v[118:119], 0.5 op_sel_hi:[1,0]
	v_pk_mul_f32 v[196:197], v[116:117], 0.5 op_sel_hi:[1,0]
	v_pk_mul_f32 v[194:195], v[114:115], 0.5 op_sel_hi:[1,0]
	v_pk_mul_f32 v[190:191], v[112:113], 0.5 op_sel_hi:[1,0]
	v_pk_mul_f32 v[188:189], v[94:95], 0.5 op_sel_hi:[1,0]
	v_pk_mul_f32 v[186:187], v[92:93], 0.5 op_sel_hi:[1,0]
	v_pk_mul_f32 v[184:185], v[86:87], 0.5 op_sel_hi:[1,0]
	v_pk_mul_f32 v[182:183], v[84:85], 0.5 op_sel_hi:[1,0]
	v_pk_mul_f32 v[176:177], v[106:107], 0.5 op_sel_hi:[1,0]
	v_pk_mul_f32 v[174:175], v[104:105], 0.5 op_sel_hi:[1,0]
	v_pk_mul_f32 v[172:173], v[98:99], 0.5 op_sel_hi:[1,0]
	v_pk_mul_f32 v[170:171], v[96:97], 0.5 op_sel_hi:[1,0]
	v_pk_mul_f32 v[168:169], v[78:79], 0.5 op_sel_hi:[1,0]
	v_pk_mul_f32 v[166:167], v[76:77], 0.5 op_sel_hi:[1,0]
	v_pk_mul_f32 v[164:165], v[74:75], 0.5 op_sel_hi:[1,0]
	v_pk_mul_f32 v[162:163], v[72:73], 0.5 op_sel_hi:[1,0]
	v_pk_mul_f32 v[158:159], v[90:91], 0.5 op_sel_hi:[1,0]
	v_pk_mul_f32 v[156:157], v[88:89], 0.5 op_sel_hi:[1,0]
	v_pk_mul_f32 v[154:155], v[82:83], 0.5 op_sel_hi:[1,0]
	v_pk_mul_f32 v[152:153], v[80:81], 0.5 op_sel_hi:[1,0]
	v_pk_mul_f32 v[148:149], v[70:71], 0.5 op_sel_hi:[1,0]
	v_pk_mul_f32 v[146:147], v[68:69], 0.5 op_sel_hi:[1,0]
	v_pk_mul_f32 v[144:145], v[66:67], 0.5 op_sel_hi:[1,0]
	v_pk_mul_f32 v[142:143], v[64:65], 0.5 op_sel_hi:[1,0]
	v_pk_mul_f32 v[126:127], v[62:63], 0.5 op_sel_hi:[1,0]
	v_pk_mul_f32 v[124:125], v[60:61], 0.5 op_sel_hi:[1,0]
	v_pk_mul_f32 v[122:123], v[58:59], 0.5 op_sel_hi:[1,0]
	v_pk_mul_f32 v[120:121], v[56:57], 0.5 op_sel_hi:[1,0]
	v_pk_mul_f32 v[118:119], v[46:47], 0.5 op_sel_hi:[1,0]
	v_pk_mul_f32 v[116:117], v[44:45], 0.5 op_sel_hi:[1,0]
	v_pk_mul_f32 v[114:115], v[38:39], 0.5 op_sel_hi:[1,0]
	v_pk_mul_f32 v[112:113], v[36:37], 0.5 op_sel_hi:[1,0]
	v_pk_mul_f32 v[110:111], v[54:55], 0.5 op_sel_hi:[1,0]
	v_pk_mul_f32 v[108:109], v[52:53], 0.5 op_sel_hi:[1,0]
	v_pk_mul_f32 v[106:107], v[50:51], 0.5 op_sel_hi:[1,0]
	v_pk_mul_f32 v[104:105], v[48:49], 0.5 op_sel_hi:[1,0]
	v_pk_mul_f32 v[102:103], v[30:31], 0.5 op_sel_hi:[1,0]
	v_pk_mul_f32 v[100:101], v[28:29], 0.5 op_sel_hi:[1,0]
	v_pk_mul_f32 v[98:99], v[22:23], 0.5 op_sel_hi:[1,0]
	v_pk_mul_f32 v[96:97], v[20:21], 0.5 op_sel_hi:[1,0]
	v_pk_mul_f32 v[94:95], v[42:43], 0.5 op_sel_hi:[1,0]
	v_pk_mul_f32 v[92:93], v[40:41], 0.5 op_sel_hi:[1,0]
	v_pk_mul_f32 v[90:91], v[34:35], 0.5 op_sel_hi:[1,0]
	v_pk_mul_f32 v[88:89], v[32:33], 0.5 op_sel_hi:[1,0]
	v_pk_mul_f32 v[86:87], v[14:15], 0.5 op_sel_hi:[1,0]
	v_pk_mul_f32 v[84:85], v[12:13], 0.5 op_sel_hi:[1,0]
	v_pk_mul_f32 v[82:83], v[10:11], 0.5 op_sel_hi:[1,0]
	v_pk_mul_f32 v[80:81], v[8:9], 0.5 op_sel_hi:[1,0]
	v_pk_mul_f32 v[78:79], v[26:27], 0.5 op_sel_hi:[1,0]
	v_pk_mul_f32 v[76:77], v[24:25], 0.5 op_sel_hi:[1,0]
	v_pk_mul_f32 v[74:75], v[18:19], 0.5 op_sel_hi:[1,0]
	v_pk_mul_f32 v[72:73], v[16:17], 0.5 op_sel_hi:[1,0]
	v_pk_mul_f32 v[70:71], v[6:7], 0.5 op_sel_hi:[1,0]
	v_pk_mul_f32 v[68:69], v[4:5], 0.5 op_sel_hi:[1,0]
	v_pk_mul_f32 v[66:67], v[2:3], 0.5 op_sel_hi:[1,0]
	v_pk_mul_f32 v[64:65], v[0:1], 0.5 op_sel_hi:[1,0]

; #define PG8_STAGE(bufoff, gbase, voff) do { _Pragma("unroll") for (int _i = 0; _i < 2; ++_i) \
;         __builtin_amdgcn_global_load_lds((const unsigned*)((const char*)(gbase) + (voff)[_i]), (PG8_LAS unsigned*)(lds + (bufoff) + ldsw + _i * 8192), 16, 0, 0); } while (0)
; #define PG8_LDA(dst, b, h) do { _Pragma("unroll") for (int m = 0; m < 4; ++m) _Pragma("unroll") for (int k = 0; k < 2; ++k) dst[m][k] = *(const PG8_LAS bf16x8*)(lds + PG8_SA(b, h) + aoff + m * 2048 + k * 1024); } while (0)
; #define PG8_LDB(dst, b, h) do { _Pragma("unroll") for (int n = 0; n < 2; ++n) _Pragma("unroll") for (int k = 0; k < 2; ++k) dst[n][k] = *(const PG8_LAS bf16x8*)(lds + PG8_SB(b, h) + boff + n * 2048 + k * 1024); } while (0)
; #define PG8_MMA(ai, bj, At, Bt) do { __builtin_amdgcn_s_setprio(1); _Pragma("unroll") for (int m = 0; m < 4; ++m) _Pragma("unroll") for (int n = 0; n < 2; ++n) _Pragma("unroll") for (int k = 0; k < 2; ++k) \
;         acc[ai][bj][m][n] = __builtin_amdgcn_mfma_f32_16x16x32_bf16(Bt[n][k], At[m][k], acc[ai][bj][m][n], 0, 0, 0); __builtin_amdgcn_s_setprio(0); } while (0)
; #define PG8_WAIT_V(n) asm volatile("s_waitcnt vmcnt(" #n ")" ::: "memory")
; #define PG8_BAR __builtin_amdgcn_s_barrier()
; template <class Epi, class Sched, bool ALIGN_EPI = false, bool SP2 = false>
; __device__ __forceinline__ void gemm_phase(PG8_LAS unsigned char* lds, const Gemm g, const Sched& S, const Epi& E) {
;     ...
;         for (int t = 0; t < nt; t += 2) {
;             const bool last = (t == nt - 2);
;             const char* a1 = cA + (size_t)(t + 1) * kstep;
;             const char* a2 = last ? nA : cA + (size_t)(t + 2) * kstep; const char* b2 = last ? nB : cB + (size_t)(t + 2) * kstep;
;             const char* a3 = a2 + kstep; const char* b3 = b2 + kstep;
;             if (last && has_next) S.a_ready(nxt);
;             if constexpr (SP2) {
;             PG8_LDB(B0, 0, 0); PG8_LDB(B1, 0, 1); PG8_SCHED; PG8_LDA(At, 0, 0); PG8_STAGE(PG8_SA(1, 1), a1 + hstep, voffA);
;             PG8_WAIT_V(8); PG8_WAIT_L(0); PG8_BAR; PG8_MMA(0, 0, At, B0); PG8_MMA(0, 1, At, B1); PG8_BAR; PG8_SCHED;
;             PG8_LDA(At, 0, 1); PG8_STAGE(PG8_SB(0, 0), b2, voffB); PG8_STAGE(PG8_SB(0, 1), b2 + hstep, voffB); PG8_STAGE(PG8_SA(0, 0), a2, voffA);
;             PG8_WAIT_V(8); PG8_WAIT_L(0); PG8_BAR; PG8_MMA(1, 0, At, B0); PG8_MMA(1, 1, At, B1); PG8_BAR; PG8_SCHED;
.LBB0_1221:
	ds_read_b128 v[150:153], v147
	ds_read_b128 v[154:157], v147 offset:1024
	ds_read_b128 v[158:161], v147 offset:2048
	ds_read_b128 v[162:165], v147 offset:3072
	ds_read_b128 v[166:169], v148
	ds_read_b128 v[170:173], v148 offset:1024
	ds_read_b128 v[174:177], v148 offset:2048
	ds_read_b128 v[178:181], v148 offset:3072
	s_add_i32 s70, s48, 2
	s_add_u32 s71, s42, 0x80
	s_addc_u32 s49, s43, 0
	s_cmp_eq_u32 s57, s48
	s_cselect_b32 s48, s4, s71
	s_cselect_b32 s49, s5, s49
	s_cselect_b32 s73, s41, s69
	s_cselect_b32 s72, s40, s68
	v_lshl_add_u64 v[190:191], s[42:43], 0, v[136:137]
	s_add_i32 m0, s33, 0xc000
	ds_read_b128 v[182:185], v149
	ds_read_b128 v[186:189], v149 offset:1024
	ds_read_b128 v[194:197], v149 offset:2048
	ds_read_b128 v[198:201], v149 offset:3072
	ds_read_b128 v[202:205], v149 offset:4096
	ds_read_b128 v[206:209], v149 offset:5120
	ds_read_b128 v[210:213], v149 offset:6144
	ds_read_b128 v[214:217], v149 offset:7168
	global_load_lds_dwordx4 v[190:191], off
	v_lshl_add_u64 v[190:191], s[42:43], 0, v[138:139]
	s_add_i32 m0, s33, 0xe000
	s_nop 0
	global_load_lds_dwordx4 v[190:191], off
	s_waitcnt vmcnt(8)
	s_waitcnt lgkmcnt(0)
	s_barrier
	s_waitcnt lgkmcnt(0)
	v_mfma_f32_16x16x32_bf16 v[120:123], v[150:153], v[182:185], v[120:123]
	v_mfma_f32_16x16x32_bf16 v[124:127], v[158:161], v[182:185], v[124:127]
	v_mfma_f32_16x16x32_bf16 v[108:111], v[150:153], v[194:197], v[108:111]
	v_mfma_f32_16x16x32_bf16 v[104:107], v[158:161], v[194:197], v[104:107]
	v_mfma_f32_16x16x32_bf16 v[92:95], v[150:153], v[202:205], v[92:95]
	v_mfma_f32_16x16x32_bf16 v[88:91], v[158:161], v[202:205], v[88:91]
	v_mfma_f32_16x16x32_bf16 v[76:79], v[150:153], v[210:213], v[76:79]
	v_mfma_f32_16x16x32_bf16 v[72:75], v[158:161], v[210:213], v[72:75]
	v_mfma_f32_16x16x32_bf16 v[120:123], v[154:157], v[186:189], v[120:123]
	v_mfma_f32_16x16x32_bf16 v[124:127], v[162:165], v[186:189], v[124:127]
	v_mfma_f32_16x16x32_bf16 v[108:111], v[154:157], v[198:201], v[108:111]
	v_mfma_f32_16x16x32_bf16 v[104:107], v[162:165], v[198:201], v[104:107]
	v_mfma_f32_16x16x32_bf16 v[92:95], v[154:157], v[206:209], v[92:95]
	v_mfma_f32_16x16x32_bf16 v[88:91], v[162:165], v[206:209], v[88:91]
	v_mfma_f32_16x16x32_bf16 v[76:79], v[154:157], v[214:217], v[76:79]
	v_mfma_f32_16x16x32_bf16 v[72:75], v[162:165], v[214:217], v[72:75]
	v_mfma_f32_16x16x32_bf16 v[116:119], v[166:169], v[182:185], v[116:119]
	v_mfma_f32_16x16x32_bf16 v[112:115], v[174:177], v[182:185], v[112:115]
	v_mfma_f32_16x16x32_bf16 v[100:103], v[166:169], v[194:197], v[100:103]
	v_mfma_f32_16x16x32_bf16 v[96:99], v[174:177], v[194:197], v[96:99]
	v_mfma_f32_16x16x32_bf16 v[84:87], v[166:169], v[202:205], v[84:87]
	v_mfma_f32_16x16x32_bf16 v[80:83], v[174:177], v[202:205], v[80:83]
	v_mfma_f32_16x16x32_bf16 v[68:71], v[166:169], v[210:213], v[68:71]
	v_mfma_f32_16x16x32_bf16 v[64:67], v[174:177], v[210:213], v[64:67]
	v_mfma_f32_16x16x32_bf16 v[116:119], v[170:173], v[186:189], v[116:119]
	v_mfma_f32_16x16x32_bf16 v[112:115], v[178:181], v[186:189], v[112:115]
	v_mfma_f32_16x16x32_bf16 v[100:103], v[170:173], v[198:201], v[100:103]
	v_mfma_f32_16x16x32_bf16 v[96:99], v[178:181], v[198:201], v[96:99]
	v_mfma_f32_16x16x32_bf16 v[84:87], v[170:173], v[206:209], v[84:87]
	v_mfma_f32_16x16x32_bf16 v[80:83], v[178:181], v[206:209], v[80:83]
	v_mfma_f32_16x16x32_bf16 v[68:71], v[170:173], v[214:217], v[68:71]
	v_mfma_f32_16x16x32_bf16 v[64:67], v[178:181], v[214:217], v[64:67]
	s_barrier
	s_add_i32 s71, s59, s31
	v_lshl_add_u64 v[190:191], s[72:73], 0, v[130:131]
	s_mov_b32 m0, s71
	ds_read_b128 v[182:185], v149 offset:16384
	ds_read_b128 v[186:189], v149 offset:17408
	ds_read_b128 v[194:197], v149 offset:18432
	ds_read_b128 v[198:201], v149 offset:19456
	ds_read_b128 v[202:205], v149 offset:20480
	ds_read_b128 v[206:209], v149 offset:21504
	ds_read_b128 v[210:213], v149 offset:22528
	ds_read_b128 v[214:217], v149 offset:23552
	global_load_lds_dwordx4 v[190:191], off
	s_add_i32 m0, s71, 0x2000
	v_lshl_add_u64 v[218:219], s[72:73], 0, v[134:135]
	s_add_u32 s72, s72, s10
	s_addc_u32 s73, s73, s11
	s_add_i32 s71, s60, s31
	global_load_lds_dwordx4 v[218:219], off
	v_lshl_add_u64 v[220:221], s[72:73], 0, v[130:131]
	s_mov_b32 m0, s71
	v_lshl_add_u64 v[222:223], s[72:73], 0, v[134:135]
	global_load_lds_dwordx4 v[220:221], off
	s_add_i32 m0, s71, 0x2000
	v_lshl_add_u64 v[224:225], s[48:49], 0, v[128:129]
	global_load_lds_dwordx4 v[222:223], off
	s_mov_b32 m0, s33
	v_lshl_add_u64 v[226:227], s[48:49], 0, v[132:133]
	global_load_lds_dwordx4 v[224:225], off
	s_mov_b32 m0, s50
	s_nop 0
	global_load_lds_dwordx4 v[226:227], off
	s_waitcnt vmcnt(8)
	s_waitcnt lgkmcnt(0)
	s_barrier
; #define PG8_STAGE(bufoff, gbase, voff) do { _Pragma("unroll") for (int _i = 0; _i < 2; ++_i) \
;         __builtin_amdgcn_global_load_lds((const unsigned*)((const char*)(gbase) + (voff)[_i]), (PG8_LAS unsigned*)(lds + (bufoff) + ldsw + _i * 8192), 16, 0, 0); } while (0)
; #define PG8_LDA(dst, b, h) do { _Pragma("unroll") for (int m = 0; m < 4; ++m) _Pragma("unroll") for (int k = 0; k < 2; ++k) dst[m][k] = *(const PG8_LAS bf16x8*)(lds + PG8_SA(b, h) + aoff + m * 2048 + k * 1024); } while (0)
; #define PG8_LDB(dst, b, h) do { _Pragma("unroll") for (int n = 0; n < 2; ++n) _Pragma("unroll") for (int k = 0; k < 2; ++k) dst[n][k] = *(const PG8_LAS bf16x8*)(lds + PG8_SB(b, h) + boff + n * 2048 + k * 1024); } while (0)
; #define PG8_MMA(ai, bj, At, Bt) do { __builtin_amdgcn_s_setprio(1); _Pragma("unroll") for (int m = 0; m < 4; ++m) _Pragma("unroll") for (int n = 0; n < 2; ++n) _Pragma("unroll") for (int k = 0; k < 2; ++k) \
;         acc[ai][bj][m][n] = __builtin_amdgcn_mfma_f32_16x16x32_bf16(Bt[n][k], At[m][k], acc[ai][bj][m][n], 0, 0, 0); __builtin_amdgcn_s_setprio(0); } while (0)
; #define PG8_WAIT_V(n) asm volatile("s_waitcnt vmcnt(" #n ")" ::: "memory")
; #define PG8_WAIT_L(n) asm volatile("s_waitcnt lgkmcnt(" #n ")" ::: "memory")
; #define PG8_BAR __builtin_amdgcn_s_barrier()
; #define PG8_SCHED __builtin_amdgcn_sched_barrier(0)
; template <class Epi, class Sched, bool ALIGN_EPI = false, bool SP2 = false>
; __device__ __forceinline__ void gemm_phase(PG8_LAS unsigned char* lds, const Gemm g, const Sched& S, const Epi& E) {
;     ...
;             PG8_WAIT_V(8); PG8_WAIT_L(0); PG8_BAR; PG8_MMA(1, 0, At, B0); PG8_MMA(1, 1, At, B1); PG8_BAR; PG8_SCHED;
;             PG8_LDB(B0, 1, 0); PG8_LDB(B1, 1, 1); PG8_SCHED; PG8_LDA(At, 1, 0); PG8_STAGE(PG8_SA(0, 1), a2 + hstep, voffA);
;             PG8_WAIT_V(8); PG8_WAIT_L(0); PG8_BAR; PG8_MMA(0, 0, At, B0); PG8_MMA(0, 1, At, B1); PG8_BAR; PG8_SCHED;
	s_waitcnt lgkmcnt(0)
	v_mfma_f32_16x16x32_bf16 v[60:63], v[150:153], v[182:185], v[60:63]
	v_mfma_f32_16x16x32_bf16 v[56:59], v[158:161], v[182:185], v[56:59]
	v_mfma_f32_16x16x32_bf16 v[44:47], v[150:153], v[194:197], v[44:47]
	v_mfma_f32_16x16x32_bf16 v[40:43], v[158:161], v[194:197], v[40:43]
	v_mfma_f32_16x16x32_bf16 v[28:31], v[150:153], v[202:205], v[28:31]
	v_mfma_f32_16x16x32_bf16 v[24:27], v[158:161], v[202:205], v[24:27]
	v_mfma_f32_16x16x32_bf16 v[12:15], v[150:153], v[210:213], v[12:15]
	v_mfma_f32_16x16x32_bf16 v[8:11], v[158:161], v[210:213], v[8:11]
	v_mfma_f32_16x16x32_bf16 v[60:63], v[154:157], v[186:189], v[60:63]
	v_mfma_f32_16x16x32_bf16 v[56:59], v[162:165], v[186:189], v[56:59]
	v_mfma_f32_16x16x32_bf16 v[44:47], v[154:157], v[198:201], v[44:47]
	v_mfma_f32_16x16x32_bf16 v[40:43], v[162:165], v[198:201], v[40:43]
	v_mfma_f32_16x16x32_bf16 v[28:31], v[154:157], v[206:209], v[28:31]
	v_mfma_f32_16x16x32_bf16 v[24:27], v[162:165], v[206:209], v[24:27]
	v_mfma_f32_16x16x32_bf16 v[12:15], v[154:157], v[214:217], v[12:15]
	v_mfma_f32_16x16x32_bf16 v[8:11], v[162:165], v[214:217], v[8:11]
	v_mfma_f32_16x16x32_bf16 v[52:55], v[166:169], v[182:185], v[52:55]
	v_mfma_f32_16x16x32_bf16 v[48:51], v[174:177], v[182:185], v[48:51]
	v_mfma_f32_16x16x32_bf16 v[36:39], v[166:169], v[194:197], v[36:39]
	v_mfma_f32_16x16x32_bf16 v[32:35], v[174:177], v[194:197], v[32:35]
	v_mfma_f32_16x16x32_bf16 v[20:23], v[166:169], v[202:205], v[20:23]
	v_mfma_f32_16x16x32_bf16 v[16:19], v[174:177], v[202:205], v[16:19]
	v_mfma_f32_16x16x32_bf16 v[4:7], v[166:169], v[210:213], v[4:7]
	v_mfma_f32_16x16x32_bf16 v[0:3], v[174:177], v[210:213], v[0:3]
	v_mfma_f32_16x16x32_bf16 v[52:55], v[170:173], v[186:189], v[52:55]
	v_mfma_f32_16x16x32_bf16 v[48:51], v[178:181], v[186:189], v[48:51]
	v_mfma_f32_16x16x32_bf16 v[36:39], v[170:173], v[198:201], v[36:39]
	v_mfma_f32_16x16x32_bf16 v[32:35], v[178:181], v[198:201], v[32:35]
	v_mfma_f32_16x16x32_bf16 v[20:23], v[170:173], v[206:209], v[20:23]
	v_mfma_f32_16x16x32_bf16 v[16:19], v[178:181], v[206:209], v[16:19]
	v_mfma_f32_16x16x32_bf16 v[4:7], v[170:173], v[214:217], v[4:7]
	v_mfma_f32_16x16x32_bf16 v[0:3], v[178:181], v[214:217], v[0:3]
	s_barrier
	s_add_i32 s71, 0, 0x18000
	s_add_i32 s72, 0, 0x1c000
	v_add_u32_e32 v162, s71, v145
	v_add_u32_e32 v178, s72, v145
	ds_read_b128 v[150:153], v162
	ds_read_b128 v[154:157], v162 offset:1024
	ds_read_b128 v[158:161], v162 offset:2048
	ds_read_b128 v[162:165], v162 offset:3072
	ds_read_b128 v[166:169], v178
	ds_read_b128 v[170:173], v178 offset:1024
	ds_read_b128 v[174:177], v178 offset:2048
	ds_read_b128 v[178:181], v178 offset:3072
	s_add_u32 s48, s48, s10
	s_addc_u32 s49, s49, s11
	s_mov_b32 m0, s51
	v_lshl_add_u64 v[228:229], s[48:49], 0, v[128:129]
	ds_read_b128 v[182:185], v149 offset:32768
	ds_read_b128 v[186:189], v149 offset:33792
	ds_read_b128 v[194:197], v149 offset:34816
	ds_read_b128 v[198:201], v149 offset:35840
	ds_read_b128 v[202:205], v149 offset:36864
	ds_read_b128 v[206:209], v149 offset:37888
	ds_read_b128 v[210:213], v149 offset:38912
	ds_read_b128 v[214:217], v149 offset:39936
	global_load_lds_dwordx4 v[228:229], off
	v_lshl_add_u64 v[228:229], s[48:49], 0, v[132:133]
	s_mov_b32 m0, s52
	s_nop 0
	global_load_lds_dwordx4 v[228:229], off
	s_waitcnt vmcnt(8)
	s_waitcnt lgkmcnt(0)
	s_barrier
	s_waitcnt lgkmcnt(0)
	v_mfma_f32_16x16x32_bf16 v[120:123], v[150:153], v[182:185], v[120:123]
	v_mfma_f32_16x16x32_bf16 v[124:127], v[158:161], v[182:185], v[124:127]
	v_mfma_f32_16x16x32_bf16 v[108:111], v[150:153], v[194:197], v[108:111]
	v_mfma_f32_16x16x32_bf16 v[104:107], v[158:161], v[194:197], v[104:107]
	v_mfma_f32_16x16x32_bf16 v[92:95], v[150:153], v[202:205], v[92:95]
	v_mfma_f32_16x16x32_bf16 v[88:91], v[158:161], v[202:205], v[88:91]
	v_mfma_f32_16x16x32_bf16 v[76:79], v[150:153], v[210:213], v[76:79]
	v_mfma_f32_16x16x32_bf16 v[72:75], v[158:161], v[210:213], v[72:75]
	v_mfma_f32_16x16x32_bf16 v[120:123], v[154:157], v[186:189], v[120:123]
	v_mfma_f32_16x16x32_bf16 v[124:127], v[162:165], v[186:189], v[124:127]
	v_mfma_f32_16x16x32_bf16 v[108:111], v[154:157], v[198:201], v[108:111]
	v_mfma_f32_16x16x32_bf16 v[104:107], v[162:165], v[198:201], v[104:107]
	v_mfma_f32_16x16x32_bf16 v[92:95], v[154:157], v[206:209], v[92:95]
	v_mfma_f32_16x16x32_bf16 v[88:91], v[162:165], v[206:209], v[88:91]
	v_mfma_f32_16x16x32_bf16 v[76:79], v[154:157], v[214:217], v[76:79]
	v_mfma_f32_16x16x32_bf16 v[72:75], v[162:165], v[214:217], v[72:75]
	v_mfma_f32_16x16x32_bf16 v[116:119], v[166:169], v[182:185], v[116:119]
	v_mfma_f32_16x16x32_bf16 v[112:115], v[174:177], v[182:185], v[112:115]
	v_mfma_f32_16x16x32_bf16 v[100:103], v[166:169], v[194:197], v[100:103]
	v_mfma_f32_16x16x32_bf16 v[96:99], v[174:177], v[194:197], v[96:99]
	v_mfma_f32_16x16x32_bf16 v[84:87], v[166:169], v[202:205], v[84:87]
	v_mfma_f32_16x16x32_bf16 v[80:83], v[174:177], v[202:205], v[80:83]
	v_mfma_f32_16x16x32_bf16 v[68:71], v[166:169], v[210:213], v[68:71]
	v_mfma_f32_16x16x32_bf16 v[64:67], v[174:177], v[210:213], v[64:67]
	v_mfma_f32_16x16x32_bf16 v[116:119], v[170:173], v[186:189], v[116:119]
	v_mfma_f32_16x16x32_bf16 v[112:115], v[178:181], v[186:189], v[112:115]
	v_mfma_f32_16x16x32_bf16 v[100:103], v[170:173], v[198:201], v[100:103]
	v_mfma_f32_16x16x32_bf16 v[96:99], v[178:181], v[198:201], v[96:99]
	v_mfma_f32_16x16x32_bf16 v[84:87], v[170:173], v[206:209], v[84:87]
	v_mfma_f32_16x16x32_bf16 v[80:83], v[178:181], v[206:209], v[80:83]
	v_mfma_f32_16x16x32_bf16 v[68:71], v[170:173], v[214:217], v[68:71]
	v_mfma_f32_16x16x32_bf16 v[64:67], v[178:181], v[214:217], v[64:67]
	s_barrier
; #define PG8_STAGE(bufoff, gbase, voff) do { _Pragma("unroll") for (int _i = 0; _i < 2; ++_i) \
;         __builtin_amdgcn_global_load_lds((const unsigned*)((const char*)(gbase) + (voff)[_i]), (PG8_LAS unsigned*)(lds + (bufoff) + ldsw + _i * 8192), 16, 0, 0); } while (0)
; #define PG8_LDA(dst, b, h) do { _Pragma("unroll") for (int m = 0; m < 4; ++m) _Pragma("unroll") for (int k = 0; k < 2; ++k) dst[m][k] = *(const PG8_LAS bf16x8*)(lds + PG8_SA(b, h) + aoff + m * 2048 + k * 1024); } while (0)
; #define PG8_LDB(dst, b, h) do { _Pragma("unroll") for (int n = 0; n < 2; ++n) _Pragma("unroll") for (int k = 0; k < 2; ++k) dst[n][k] = *(const PG8_LAS bf16x8*)(lds + PG8_SB(b, h) + boff + n * 2048 + k * 1024); } while (0)
; #define PG8_MMA(ai, bj, At, Bt) do { __builtin_amdgcn_s_setprio(1); _Pragma("unroll") for (int m = 0; m < 4; ++m) _Pragma("unroll") for (int n = 0; n < 2; ++n) _Pragma("unroll") for (int k = 0; k < 2; ++k) \
;         acc[ai][bj][m][n] = __builtin_amdgcn_mfma_f32_16x16x32_bf16(Bt[n][k], At[m][k], acc[ai][bj][m][n], 0, 0, 0); __builtin_amdgcn_s_setprio(0); } while (0)
; #define PG8_WAIT_V(n) asm volatile("s_waitcnt vmcnt(" #n ")" ::: "memory")
; #define PG8_WAIT_L(n) asm volatile("s_waitcnt lgkmcnt(" #n ")" ::: "memory")
; template <class Epi, class Sched, bool ALIGN_EPI = false, bool SP2 = false>
; __device__ __forceinline__ void gemm_phase(PG8_LAS unsigned char* lds, const Gemm g, const Sched& S, const Epi& E) {
;     ...
;         for (int t = 0; t < nt; t += 2) {
;             const bool last = (t == nt - 2);
;             const char* a1 = cA + (size_t)(t + 1) * kstep;
;             const char* a2 = last ? nA : cA + (size_t)(t + 2) * kstep; const char* b2 = last ? nB : cB + (size_t)(t + 2) * kstep;
;             const char* a3 = a2 + kstep; const char* b3 = b2 + kstep;
;             if (last && has_next) S.a_ready(nxt);
;     ...
;             PG8_LDB(B0, 1, 0); PG8_LDB(B1, 1, 1); PG8_SCHED; PG8_LDA(At, 1, 0); PG8_STAGE(PG8_SA(0, 1), a2 + hstep, voffA);
;             PG8_WAIT_V(8); PG8_WAIT_L(0); PG8_BAR; PG8_MMA(0, 0, At, B0); PG8_MMA(0, 1, At, B1); PG8_BAR; PG8_SCHED;
;             PG8_LDA(At, 1, 1); PG8_STAGE(PG8_SB(1, 0), b3, voffB); PG8_STAGE(PG8_SB(1, 1), b3 + hstep, voffB); PG8_STAGE(PG8_SA(1, 0), a3, voffA);
;             PG8_WAIT_V(8); PG8_WAIT_L(0); PG8_BAR; PG8_MMA(1, 0, At, B0); PG8_MMA(1, 1, At, B1); PG8_BAR; PG8_SCHED;
	s_add_i32 s48, s71, s31
	v_lshl_add_u64 v[190:191], v[190:191], 0, s[16:17]
	s_mov_b32 m0, s48
	ds_read_b128 v[182:185], v149 offset:49152
	ds_read_b128 v[186:189], v149 offset:50176
	ds_read_b128 v[194:197], v149 offset:51200
	ds_read_b128 v[198:201], v149 offset:52224
	ds_read_b128 v[202:205], v149 offset:53248
	ds_read_b128 v[206:209], v149 offset:54272
	ds_read_b128 v[210:213], v149 offset:55296
	ds_read_b128 v[214:217], v149 offset:56320
	global_load_lds_dwordx4 v[190:191], off
	v_lshl_add_u64 v[190:191], v[218:219], 0, s[16:17]
	s_add_i32 m0, s48, 0x2000
	s_add_i32 s48, s72, s31
	global_load_lds_dwordx4 v[190:191], off
	v_lshl_add_u64 v[190:191], v[220:221], 0, s[16:17]
	s_mov_b32 m0, s48
	s_nop 0
	global_load_lds_dwordx4 v[190:191], off
	v_lshl_add_u64 v[190:191], v[222:223], 0, s[16:17]
	s_add_i32 m0, s48, 0x2000
	s_nop 0
	global_load_lds_dwordx4 v[190:191], off
	v_lshl_add_u64 v[190:191], v[224:225], 0, s[16:17]
	s_mov_b32 m0, s54
	s_nop 0
	global_load_lds_dwordx4 v[190:191], off
	v_lshl_add_u64 v[190:191], v[226:227], 0, s[16:17]
	s_mov_b32 m0, s55
	s_nop 0
	global_load_lds_dwordx4 v[190:191], off
	s_waitcnt vmcnt(8)
	s_waitcnt lgkmcnt(0)
	s_barrier
	s_waitcnt lgkmcnt(0)
	v_mfma_f32_16x16x32_bf16 v[60:63], v[150:153], v[182:185], v[60:63]
	v_mfma_f32_16x16x32_bf16 v[56:59], v[158:161], v[182:185], v[56:59]
	v_mfma_f32_16x16x32_bf16 v[44:47], v[150:153], v[194:197], v[44:47]
	v_mfma_f32_16x16x32_bf16 v[40:43], v[158:161], v[194:197], v[40:43]
	v_mfma_f32_16x16x32_bf16 v[28:31], v[150:153], v[202:205], v[28:31]
	v_mfma_f32_16x16x32_bf16 v[24:27], v[158:161], v[202:205], v[24:27]
	v_mfma_f32_16x16x32_bf16 v[12:15], v[150:153], v[210:213], v[12:15]
	v_mfma_f32_16x16x32_bf16 v[8:11], v[158:161], v[210:213], v[8:11]
	v_mfma_f32_16x16x32_bf16 v[60:63], v[154:157], v[186:189], v[60:63]
	v_mfma_f32_16x16x32_bf16 v[56:59], v[162:165], v[186:189], v[56:59]
	v_mfma_f32_16x16x32_bf16 v[44:47], v[154:157], v[198:201], v[44:47]
	v_mfma_f32_16x16x32_bf16 v[40:43], v[162:165], v[198:201], v[40:43]
	v_mfma_f32_16x16x32_bf16 v[28:31], v[154:157], v[206:209], v[28:31]
	v_mfma_f32_16x16x32_bf16 v[24:27], v[162:165], v[206:209], v[24:27]
	v_mfma_f32_16x16x32_bf16 v[12:15], v[154:157], v[214:217], v[12:15]
	v_mfma_f32_16x16x32_bf16 v[8:11], v[162:165], v[214:217], v[8:11]
	v_mfma_f32_16x16x32_bf16 v[52:55], v[166:169], v[182:185], v[52:55]
	v_mfma_f32_16x16x32_bf16 v[48:51], v[174:177], v[182:185], v[48:51]
	v_mfma_f32_16x16x32_bf16 v[36:39], v[166:169], v[194:197], v[36:39]
	v_mfma_f32_16x16x32_bf16 v[32:35], v[174:177], v[194:197], v[32:35]
	v_mfma_f32_16x16x32_bf16 v[20:23], v[166:169], v[202:205], v[20:23]
	v_mfma_f32_16x16x32_bf16 v[16:19], v[174:177], v[202:205], v[16:19]
	v_mfma_f32_16x16x32_bf16 v[4:7], v[166:169], v[210:213], v[4:7]
	v_mfma_f32_16x16x32_bf16 v[0:3], v[174:177], v[210:213], v[0:3]
	v_mfma_f32_16x16x32_bf16 v[52:55], v[170:173], v[186:189], v[52:55]
	v_mfma_f32_16x16x32_bf16 v[48:51], v[178:181], v[186:189], v[48:51]
	v_mfma_f32_16x16x32_bf16 v[36:39], v[170:173], v[198:201], v[36:39]
	v_mfma_f32_16x16x32_bf16 v[32:35], v[178:181], v[198:201], v[32:35]
	v_mfma_f32_16x16x32_bf16 v[20:23], v[170:173], v[206:209], v[20:23]
	v_mfma_f32_16x16x32_bf16 v[16:19], v[178:181], v[206:209], v[16:19]
	v_mfma_f32_16x16x32_bf16 v[4:7], v[170:173], v[214:217], v[4:7]
	v_mfma_f32_16x16x32_bf16 v[0:3], v[178:181], v[214:217], v[0:3]
	s_barrier
	s_add_u32 s42, s42, 0x100
	s_addc_u32 s43, s43, 0
	s_add_u32 s68, s68, 0x100
	s_addc_u32 s69, s69, 0
	s_cmp_ge_i32 s70, s56
	s_mov_b32 s48, s70
	s_cbranch_scc0 .LBB0_1221

; #define PG8_STAGE(bufoff, gbase, voff) do { _Pragma("unroll") for (int _i = 0; _i < 2; ++_i) \
;         __builtin_amdgcn_global_load_lds((const unsigned*)((const char*)(gbase) + (voff)[_i]), (PG8_LAS unsigned*)(lds + (bufoff) + ldsw + _i * 8192), 16, 0, 0); } while (0)
; #define PG8_LDA(dst, b, h) do { _Pragma("unroll") for (int m = 0; m < 4; ++m) _Pragma("unroll") for (int k = 0; k < 2; ++k) dst[m][k] = *(const PG8_LAS bf16x8*)(lds + PG8_SA(b, h) + aoff + m * 2048 + k * 1024); } while (0)
; #define PG8_LDB(dst, b, h) do { _Pragma("unroll") for (int n = 0; n < 2; ++n) _Pragma("unroll") for (int k = 0; k < 2; ++k) dst[n][k] = *(const PG8_LAS bf16x8*)(lds + PG8_SB(b, h) + boff + n * 2048 + k * 1024); } while (0)
; #define PG8_MMA(ai, bj, At, Bt) do { __builtin_amdgcn_s_setprio(1); _Pragma("unroll") for (int m = 0; m < 4; ++m) _Pragma("unroll") for (int n = 0; n < 2; ++n) _Pragma("unroll") for (int k = 0; k < 2; ++k) \
;         acc[ai][bj][m][n] = __builtin_amdgcn_mfma_f32_16x16x32_bf16(Bt[n][k], At[m][k], acc[ai][bj][m][n], 0, 0, 0); __builtin_amdgcn_s_setprio(0); } while (0)
; #define PG8_WAIT_V(n) asm volatile("s_waitcnt vmcnt(" #n ")" ::: "memory")
; #define PG8_BAR __builtin_amdgcn_s_barrier()
; template <class Epi, class Sched, bool ALIGN_EPI = false, bool SP2 = false>
; __device__ __forceinline__ void gemm_phase(PG8_LAS unsigned char* lds, const Gemm g, const Sched& S, const Epi& E) {
;     ...
;         for (int t = 0; t < nt; t += 2) {
;             const bool last = (t == nt - 2);
;             const char* a1 = cA + (size_t)(t + 1) * kstep;
;             const char* a2 = last ? nA : cA + (size_t)(t + 2) * kstep; const char* b2 = last ? nB : cB + (size_t)(t + 2) * kstep;
;             const char* a3 = a2 + kstep; const char* b3 = b2 + kstep;
;             if (last && has_next) S.a_ready(nxt);
;             if constexpr (SP2) {
;             PG8_LDB(B0, 0, 0); PG8_LDB(B1, 0, 1); PG8_SCHED; PG8_LDA(At, 0, 0); PG8_STAGE(PG8_SA(1, 1), a1 + hstep, voffA);
;             PG8_WAIT_V(8); PG8_WAIT_L(0); PG8_BAR; PG8_MMA(0, 0, At, B0); PG8_MMA(0, 1, At, B1); PG8_BAR; PG8_SCHED;
;             PG8_LDA(At, 0, 1); PG8_STAGE(PG8_SB(0, 0), b2, voffB); PG8_STAGE(PG8_SB(0, 1), b2 + hstep, voffB); PG8_STAGE(PG8_SA(0, 0), a2, voffA);
;             PG8_WAIT_V(8); PG8_WAIT_L(0); PG8_BAR; PG8_MMA(1, 0, At, B0); PG8_MMA(1, 1, At, B1); PG8_BAR; PG8_SCHED;
.LBB0_1253:
	ds_read_b128 v[124:127], v214
	ds_read_b128 v[132:135], v214 offset:1024
	ds_read_b128 v[136:139], v214 offset:2048
	ds_read_b128 v[140:143], v214 offset:3072
	ds_read_b128 v[144:147], v215
	ds_read_b128 v[148:151], v215 offset:1024
	ds_read_b128 v[152:155], v215 offset:2048
	ds_read_b128 v[156:159], v215 offset:3072
	s_add_i32 s55, s26, 2
	s_add_u32 s56, s22, 0x80
	s_addc_u32 s27, s23, 0
	s_cmp_eq_u32 s41, s26
	s_cselect_b32 s26, s4, s56
	s_cselect_b32 s27, s5, s27
	s_cselect_b32 s57, s21, s54
	s_cselect_b32 s56, s20, s53
	v_lshl_add_u64 v[220:221], s[22:23], 0, v[186:187]
	s_add_i32 m0, s29, 0xc000
	ds_read_b128 v[160:163], v216
	ds_read_b128 v[164:167], v216 offset:1024
	ds_read_b128 v[168:171], v216 offset:2048
	ds_read_b128 v[172:175], v216 offset:3072
	ds_read_b128 v[196:199], v216 offset:4096
	ds_read_b128 v[200:203], v216 offset:5120
	ds_read_b128 v[204:207], v216 offset:6144
	ds_read_b128 v[208:211], v216 offset:7168
	global_load_lds_dwordx4 v[220:221], off
	v_lshl_add_u64 v[220:221], s[22:23], 0, v[188:189]
	s_add_i32 m0, s29, 0xe000
	s_nop 0
	global_load_lds_dwordx4 v[220:221], off
	s_waitcnt vmcnt(8)
	s_waitcnt lgkmcnt(0)
	s_barrier
	s_waitcnt lgkmcnt(0)
	v_mfma_f32_16x16x32_bf16 v[128:131], v[124:127], v[160:163], v[128:131]
	v_mfma_f32_16x16x32_bf16 v[120:123], v[136:139], v[160:163], v[120:123]
	v_mfma_f32_16x16x32_bf16 v[108:111], v[124:127], v[168:171], v[108:111]
	v_mfma_f32_16x16x32_bf16 v[104:107], v[136:139], v[168:171], v[104:107]
	v_mfma_f32_16x16x32_bf16 v[92:95], v[124:127], v[196:199], v[92:95]
	v_mfma_f32_16x16x32_bf16 v[88:91], v[136:139], v[196:199], v[88:91]
	v_mfma_f32_16x16x32_bf16 v[76:79], v[124:127], v[204:207], v[76:79]
	v_mfma_f32_16x16x32_bf16 v[72:75], v[136:139], v[204:207], v[72:75]
	v_mfma_f32_16x16x32_bf16 v[128:131], v[132:135], v[164:167], v[128:131]
	v_mfma_f32_16x16x32_bf16 v[120:123], v[140:143], v[164:167], v[120:123]
	v_mfma_f32_16x16x32_bf16 v[108:111], v[132:135], v[172:175], v[108:111]
	v_mfma_f32_16x16x32_bf16 v[104:107], v[140:143], v[172:175], v[104:107]
	v_mfma_f32_16x16x32_bf16 v[92:95], v[132:135], v[200:203], v[92:95]
	v_mfma_f32_16x16x32_bf16 v[88:91], v[140:143], v[200:203], v[88:91]
	v_mfma_f32_16x16x32_bf16 v[76:79], v[132:135], v[208:211], v[76:79]
	v_mfma_f32_16x16x32_bf16 v[72:75], v[140:143], v[208:211], v[72:75]
	v_mfma_f32_16x16x32_bf16 v[116:119], v[144:147], v[160:163], v[116:119]
	v_mfma_f32_16x16x32_bf16 v[112:115], v[152:155], v[160:163], v[112:115]
	v_mfma_f32_16x16x32_bf16 v[100:103], v[144:147], v[168:171], v[100:103]
	v_mfma_f32_16x16x32_bf16 v[96:99], v[152:155], v[168:171], v[96:99]
	v_mfma_f32_16x16x32_bf16 v[84:87], v[144:147], v[196:199], v[84:87]
	v_mfma_f32_16x16x32_bf16 v[80:83], v[152:155], v[196:199], v[80:83]
	v_mfma_f32_16x16x32_bf16 v[68:71], v[144:147], v[204:207], v[68:71]
	v_mfma_f32_16x16x32_bf16 v[64:67], v[152:155], v[204:207], v[64:67]
	v_mfma_f32_16x16x32_bf16 v[116:119], v[148:151], v[164:167], v[116:119]
	v_mfma_f32_16x16x32_bf16 v[112:115], v[156:159], v[164:167], v[112:115]
	v_mfma_f32_16x16x32_bf16 v[100:103], v[148:151], v[172:175], v[100:103]
	v_mfma_f32_16x16x32_bf16 v[96:99], v[156:159], v[172:175], v[96:99]
	v_mfma_f32_16x16x32_bf16 v[84:87], v[148:151], v[200:203], v[84:87]
	v_mfma_f32_16x16x32_bf16 v[80:83], v[156:159], v[200:203], v[80:83]
	v_mfma_f32_16x16x32_bf16 v[68:71], v[148:151], v[208:211], v[68:71]
	v_mfma_f32_16x16x32_bf16 v[64:67], v[156:159], v[208:211], v[64:67]
	s_barrier
	s_add_i32 s58, s43, s28
	v_lshl_add_u64 v[220:221], s[56:57], 0, v[178:179]
	s_mov_b32 m0, s58
	ds_read_b128 v[160:163], v216 offset:16384
	ds_read_b128 v[164:167], v216 offset:17408
	ds_read_b128 v[168:171], v216 offset:18432
	ds_read_b128 v[172:175], v216 offset:19456
	ds_read_b128 v[196:199], v216 offset:20480
	ds_read_b128 v[200:203], v216 offset:21504
	ds_read_b128 v[204:207], v216 offset:22528
	ds_read_b128 v[208:211], v216 offset:23552
	global_load_lds_dwordx4 v[220:221], off
	s_add_i32 m0, s58, 0x2000
	v_lshl_add_u64 v[222:223], s[56:57], 0, v[182:183]
	s_add_u32 s56, s56, s8
	s_addc_u32 s57, s57, s9
	s_add_i32 s58, s48, s28
	global_load_lds_dwordx4 v[222:223], off
	v_lshl_add_u64 v[224:225], s[56:57], 0, v[178:179]
	s_mov_b32 m0, s58
	v_lshl_add_u64 v[226:227], s[56:57], 0, v[182:183]
	global_load_lds_dwordx4 v[224:225], off
	s_add_i32 m0, s58, 0x2000
	v_lshl_add_u64 v[228:229], s[26:27], 0, v[176:177]
	global_load_lds_dwordx4 v[226:227], off
	s_mov_b32 m0, s29
	v_lshl_add_u64 v[230:231], s[26:27], 0, v[180:181]
	global_load_lds_dwordx4 v[228:229], off
	s_mov_b32 m0, s31
	s_nop 0
	global_load_lds_dwordx4 v[230:231], off
	s_waitcnt vmcnt(8)
	s_waitcnt lgkmcnt(0)
	s_barrier
; #define PG8_STAGE(bufoff, gbase, voff) do { _Pragma("unroll") for (int _i = 0; _i < 2; ++_i) \
;         __builtin_amdgcn_global_load_lds((const unsigned*)((const char*)(gbase) + (voff)[_i]), (PG8_LAS unsigned*)(lds + (bufoff) + ldsw + _i * 8192), 16, 0, 0); } while (0)
; #define PG8_LDA(dst, b, h) do { _Pragma("unroll") for (int m = 0; m < 4; ++m) _Pragma("unroll") for (int k = 0; k < 2; ++k) dst[m][k] = *(const PG8_LAS bf16x8*)(lds + PG8_SA(b, h) + aoff + m * 2048 + k * 1024); } while (0)
; #define PG8_LDB(dst, b, h) do { _Pragma("unroll") for (int n = 0; n < 2; ++n) _Pragma("unroll") for (int k = 0; k < 2; ++k) dst[n][k] = *(const PG8_LAS bf16x8*)(lds + PG8_SB(b, h) + boff + n * 2048 + k * 1024); } while (0)
; #define PG8_MMA(ai, bj, At, Bt) do { __builtin_amdgcn_s_setprio(1); _Pragma("unroll") for (int m = 0; m < 4; ++m) _Pragma("unroll") for (int n = 0; n < 2; ++n) _Pragma("unroll") for (int k = 0; k < 2; ++k) \
;         acc[ai][bj][m][n] = __builtin_amdgcn_mfma_f32_16x16x32_bf16(Bt[n][k], At[m][k], acc[ai][bj][m][n], 0, 0, 0); __builtin_amdgcn_s_setprio(0); } while (0)
; #define PG8_WAIT_V(n) asm volatile("s_waitcnt vmcnt(" #n ")" ::: "memory")
; #define PG8_WAIT_L(n) asm volatile("s_waitcnt lgkmcnt(" #n ")" ::: "memory")
; #define PG8_BAR __builtin_amdgcn_s_barrier()
; #define PG8_SCHED __builtin_amdgcn_sched_barrier(0)
; template <class Epi, class Sched, bool ALIGN_EPI = false, bool SP2 = false>
; __device__ __forceinline__ void gemm_phase(PG8_LAS unsigned char* lds, const Gemm g, const Sched& S, const Epi& E) {
;     ...
;             PG8_WAIT_V(8); PG8_WAIT_L(0); PG8_BAR; PG8_MMA(1, 0, At, B0); PG8_MMA(1, 1, At, B1); PG8_BAR; PG8_SCHED;
;             PG8_LDB(B0, 1, 0); PG8_LDB(B1, 1, 1); PG8_SCHED; PG8_LDA(At, 1, 0); PG8_STAGE(PG8_SA(0, 1), a2 + hstep, voffA);
;             PG8_WAIT_V(8); PG8_WAIT_L(0); PG8_BAR; PG8_MMA(0, 0, At, B0); PG8_MMA(0, 1, At, B1); PG8_BAR; PG8_SCHED;
	s_waitcnt lgkmcnt(0)
	v_mfma_f32_16x16x32_bf16 v[60:63], v[124:127], v[160:163], v[60:63]
	v_mfma_f32_16x16x32_bf16 v[56:59], v[136:139], v[160:163], v[56:59]
	v_mfma_f32_16x16x32_bf16 v[44:47], v[124:127], v[168:171], v[44:47]
	v_mfma_f32_16x16x32_bf16 v[40:43], v[136:139], v[168:171], v[40:43]
	v_mfma_f32_16x16x32_bf16 v[28:31], v[124:127], v[196:199], v[28:31]
	v_mfma_f32_16x16x32_bf16 v[24:27], v[136:139], v[196:199], v[24:27]
	v_mfma_f32_16x16x32_bf16 v[12:15], v[124:127], v[204:207], v[12:15]
	v_mfma_f32_16x16x32_bf16 v[8:11], v[136:139], v[204:207], v[8:11]
	v_mfma_f32_16x16x32_bf16 v[60:63], v[132:135], v[164:167], v[60:63]
	v_mfma_f32_16x16x32_bf16 v[56:59], v[140:143], v[164:167], v[56:59]
	v_mfma_f32_16x16x32_bf16 v[44:47], v[132:135], v[172:175], v[44:47]
	v_mfma_f32_16x16x32_bf16 v[40:43], v[140:143], v[172:175], v[40:43]
	v_mfma_f32_16x16x32_bf16 v[28:31], v[132:135], v[200:203], v[28:31]
	v_mfma_f32_16x16x32_bf16 v[24:27], v[140:143], v[200:203], v[24:27]
	v_mfma_f32_16x16x32_bf16 v[12:15], v[132:135], v[208:211], v[12:15]
	v_mfma_f32_16x16x32_bf16 v[8:11], v[140:143], v[208:211], v[8:11]
	v_mfma_f32_16x16x32_bf16 v[52:55], v[144:147], v[160:163], v[52:55]
	v_mfma_f32_16x16x32_bf16 v[48:51], v[152:155], v[160:163], v[48:51]
	v_mfma_f32_16x16x32_bf16 v[36:39], v[144:147], v[168:171], v[36:39]
	v_mfma_f32_16x16x32_bf16 v[32:35], v[152:155], v[168:171], v[32:35]
	v_mfma_f32_16x16x32_bf16 v[20:23], v[144:147], v[196:199], v[20:23]
	v_mfma_f32_16x16x32_bf16 v[16:19], v[152:155], v[196:199], v[16:19]
	v_mfma_f32_16x16x32_bf16 v[4:7], v[144:147], v[204:207], v[4:7]
	v_mfma_f32_16x16x32_bf16 v[0:3], v[152:155], v[204:207], v[0:3]
	v_mfma_f32_16x16x32_bf16 v[52:55], v[148:151], v[164:167], v[52:55]
	v_mfma_f32_16x16x32_bf16 v[48:51], v[156:159], v[164:167], v[48:51]
	v_mfma_f32_16x16x32_bf16 v[36:39], v[148:151], v[172:175], v[36:39]
	v_mfma_f32_16x16x32_bf16 v[32:35], v[156:159], v[172:175], v[32:35]
	v_mfma_f32_16x16x32_bf16 v[20:23], v[148:151], v[200:203], v[20:23]
	v_mfma_f32_16x16x32_bf16 v[16:19], v[156:159], v[200:203], v[16:19]
	v_mfma_f32_16x16x32_bf16 v[4:7], v[148:151], v[208:211], v[4:7]
	v_mfma_f32_16x16x32_bf16 v[0:3], v[156:159], v[208:211], v[0:3]
	s_barrier
	s_add_i32 s56, 0, 0x18000
	s_add_i32 s57, 0, 0x1c000
	v_add_u32_e32 v140, s56, v212
	v_add_u32_e32 v156, s57, v212
	ds_read_b128 v[124:127], v140
	ds_read_b128 v[132:135], v140 offset:1024
	ds_read_b128 v[136:139], v140 offset:2048
	ds_read_b128 v[140:143], v140 offset:3072
	ds_read_b128 v[144:147], v156
	ds_read_b128 v[148:151], v156 offset:1024
	ds_read_b128 v[152:155], v156 offset:2048
	ds_read_b128 v[156:159], v156 offset:3072
	s_add_u32 s26, s26, s8
	s_addc_u32 s27, s27, s9
	s_mov_b32 m0, s33
	v_lshl_add_u64 v[232:233], s[26:27], 0, v[176:177]
	ds_read_b128 v[160:163], v216 offset:32768
	ds_read_b128 v[164:167], v216 offset:33792
	ds_read_b128 v[168:171], v216 offset:34816
	ds_read_b128 v[172:175], v216 offset:35840
	ds_read_b128 v[196:199], v216 offset:36864
	ds_read_b128 v[200:203], v216 offset:37888
	ds_read_b128 v[204:207], v216 offset:38912
	ds_read_b128 v[208:211], v216 offset:39936
	global_load_lds_dwordx4 v[232:233], off
	v_lshl_add_u64 v[232:233], s[26:27], 0, v[180:181]
	s_mov_b32 m0, s36
	s_nop 0
	global_load_lds_dwordx4 v[232:233], off
	s_waitcnt vmcnt(8)
	s_waitcnt lgkmcnt(0)
	s_barrier
	s_waitcnt lgkmcnt(0)
	v_mfma_f32_16x16x32_bf16 v[128:131], v[124:127], v[160:163], v[128:131]
	v_mfma_f32_16x16x32_bf16 v[120:123], v[136:139], v[160:163], v[120:123]
	v_mfma_f32_16x16x32_bf16 v[108:111], v[124:127], v[168:171], v[108:111]
	v_mfma_f32_16x16x32_bf16 v[104:107], v[136:139], v[168:171], v[104:107]
	v_mfma_f32_16x16x32_bf16 v[92:95], v[124:127], v[196:199], v[92:95]
	v_mfma_f32_16x16x32_bf16 v[88:91], v[136:139], v[196:199], v[88:91]
	v_mfma_f32_16x16x32_bf16 v[76:79], v[124:127], v[204:207], v[76:79]
	v_mfma_f32_16x16x32_bf16 v[72:75], v[136:139], v[204:207], v[72:75]
	v_mfma_f32_16x16x32_bf16 v[128:131], v[132:135], v[164:167], v[128:131]
	v_mfma_f32_16x16x32_bf16 v[120:123], v[140:143], v[164:167], v[120:123]
	v_mfma_f32_16x16x32_bf16 v[108:111], v[132:135], v[172:175], v[108:111]
	v_mfma_f32_16x16x32_bf16 v[104:107], v[140:143], v[172:175], v[104:107]
	v_mfma_f32_16x16x32_bf16 v[92:95], v[132:135], v[200:203], v[92:95]
	v_mfma_f32_16x16x32_bf16 v[88:91], v[140:143], v[200:203], v[88:91]
	v_mfma_f32_16x16x32_bf16 v[76:79], v[132:135], v[208:211], v[76:79]
	v_mfma_f32_16x16x32_bf16 v[72:75], v[140:143], v[208:211], v[72:75]
	v_mfma_f32_16x16x32_bf16 v[116:119], v[144:147], v[160:163], v[116:119]
	v_mfma_f32_16x16x32_bf16 v[112:115], v[152:155], v[160:163], v[112:115]
	v_mfma_f32_16x16x32_bf16 v[100:103], v[144:147], v[168:171], v[100:103]
	v_mfma_f32_16x16x32_bf16 v[96:99], v[152:155], v[168:171], v[96:99]
	v_mfma_f32_16x16x32_bf16 v[84:87], v[144:147], v[196:199], v[84:87]
	v_mfma_f32_16x16x32_bf16 v[80:83], v[152:155], v[196:199], v[80:83]
	v_mfma_f32_16x16x32_bf16 v[68:71], v[144:147], v[204:207], v[68:71]
	v_mfma_f32_16x16x32_bf16 v[64:67], v[152:155], v[204:207], v[64:67]
	v_mfma_f32_16x16x32_bf16 v[116:119], v[148:151], v[164:167], v[116:119]
	v_mfma_f32_16x16x32_bf16 v[112:115], v[156:159], v[164:167], v[112:115]
	v_mfma_f32_16x16x32_bf16 v[100:103], v[148:151], v[172:175], v[100:103]
	v_mfma_f32_16x16x32_bf16 v[96:99], v[156:159], v[172:175], v[96:99]
	v_mfma_f32_16x16x32_bf16 v[84:87], v[148:151], v[200:203], v[84:87]
	v_mfma_f32_16x16x32_bf16 v[80:83], v[156:159], v[200:203], v[80:83]
	v_mfma_f32_16x16x32_bf16 v[68:71], v[148:151], v[208:211], v[68:71]
	v_mfma_f32_16x16x32_bf16 v[64:67], v[156:159], v[208:211], v[64:67]
	s_barrier
; #define PG8_STAGE(bufoff, gbase, voff) do { _Pragma("unroll") for (int _i = 0; _i < 2; ++_i) \
;         __builtin_amdgcn_global_load_lds((const unsigned*)((const char*)(gbase) + (voff)[_i]), (PG8_LAS unsigned*)(lds + (bufoff) + ldsw + _i * 8192), 16, 0, 0); } while (0)
; #define PG8_LDA(dst, b, h) do { _Pragma("unroll") for (int m = 0; m < 4; ++m) _Pragma("unroll") for (int k = 0; k < 2; ++k) dst[m][k] = *(const PG8_LAS bf16x8*)(lds + PG8_SA(b, h) + aoff + m * 2048 + k * 1024); } while (0)
; #define PG8_LDB(dst, b, h) do { _Pragma("unroll") for (int n = 0; n < 2; ++n) _Pragma("unroll") for (int k = 0; k < 2; ++k) dst[n][k] = *(const PG8_LAS bf16x8*)(lds + PG8_SB(b, h) + boff + n * 2048 + k * 1024); } while (0)
; #define PG8_MMA(ai, bj, At, Bt) do { __builtin_amdgcn_s_setprio(1); _Pragma("unroll") for (int m = 0; m < 4; ++m) _Pragma("unroll") for (int n = 0; n < 2; ++n) _Pragma("unroll") for (int k = 0; k < 2; ++k) \
;         acc[ai][bj][m][n] = __builtin_amdgcn_mfma_f32_16x16x32_bf16(Bt[n][k], At[m][k], acc[ai][bj][m][n], 0, 0, 0); __builtin_amdgcn_s_setprio(0); } while (0)
; #define PG8_WAIT_V(n) asm volatile("s_waitcnt vmcnt(" #n ")" ::: "memory")
; #define PG8_WAIT_L(n) asm volatile("s_waitcnt lgkmcnt(" #n ")" ::: "memory")
; template <class Epi, class Sched, bool ALIGN_EPI = false, bool SP2 = false>
; __device__ __forceinline__ void gemm_phase(PG8_LAS unsigned char* lds, const Gemm g, const Sched& S, const Epi& E) {
;     ...
;         for (int t = 0; t < nt; t += 2) {
;             const bool last = (t == nt - 2);
;             const char* a1 = cA + (size_t)(t + 1) * kstep;
;             const char* a2 = last ? nA : cA + (size_t)(t + 2) * kstep; const char* b2 = last ? nB : cB + (size_t)(t + 2) * kstep;
;             const char* a3 = a2 + kstep; const char* b3 = b2 + kstep;
;             if (last && has_next) S.a_ready(nxt);
;     ...
;             PG8_LDB(B0, 1, 0); PG8_LDB(B1, 1, 1); PG8_SCHED; PG8_LDA(At, 1, 0); PG8_STAGE(PG8_SA(0, 1), a2 + hstep, voffA);
;             PG8_WAIT_V(8); PG8_WAIT_L(0); PG8_BAR; PG8_MMA(0, 0, At, B0); PG8_MMA(0, 1, At, B1); PG8_BAR; PG8_SCHED;
;             PG8_LDA(At, 1, 1); PG8_STAGE(PG8_SB(1, 0), b3, voffB); PG8_STAGE(PG8_SB(1, 1), b3 + hstep, voffB); PG8_STAGE(PG8_SA(1, 0), a3, voffA);
;             PG8_WAIT_V(8); PG8_WAIT_L(0); PG8_BAR; PG8_MMA(1, 0, At, B0); PG8_MMA(1, 1, At, B1); PG8_BAR; PG8_SCHED;
	s_add_i32 s26, s56, s28
	v_lshl_add_u64 v[220:221], v[220:221], 0, s[14:15]
	s_mov_b32 m0, s26
	ds_read_b128 v[160:163], v216 offset:49152
	ds_read_b128 v[164:167], v216 offset:50176
	ds_read_b128 v[168:171], v216 offset:51200
	ds_read_b128 v[172:175], v216 offset:52224
	ds_read_b128 v[196:199], v216 offset:53248
	ds_read_b128 v[200:203], v216 offset:54272
	ds_read_b128 v[204:207], v216 offset:55296
	ds_read_b128 v[208:211], v216 offset:56320
	global_load_lds_dwordx4 v[220:221], off
	v_lshl_add_u64 v[220:221], v[222:223], 0, s[14:15]
	s_add_i32 m0, s26, 0x2000
	s_add_i32 s26, s57, s28
	global_load_lds_dwordx4 v[220:221], off
	v_lshl_add_u64 v[220:221], v[224:225], 0, s[14:15]
	s_mov_b32 m0, s26
	s_nop 0
	global_load_lds_dwordx4 v[220:221], off
	v_lshl_add_u64 v[220:221], v[226:227], 0, s[14:15]
	s_add_i32 m0, s26, 0x2000
	s_nop 0
	global_load_lds_dwordx4 v[220:221], off
	v_lshl_add_u64 v[220:221], v[228:229], 0, s[14:15]
	s_mov_b32 m0, s38
	s_nop 0
	global_load_lds_dwordx4 v[220:221], off
	v_lshl_add_u64 v[220:221], v[230:231], 0, s[14:15]
	s_mov_b32 m0, s39
	s_nop 0
	global_load_lds_dwordx4 v[220:221], off
	s_waitcnt vmcnt(8)
	s_waitcnt lgkmcnt(0)
	s_barrier
	s_waitcnt lgkmcnt(0)
	v_mfma_f32_16x16x32_bf16 v[60:63], v[124:127], v[160:163], v[60:63]
	v_mfma_f32_16x16x32_bf16 v[56:59], v[136:139], v[160:163], v[56:59]
	v_mfma_f32_16x16x32_bf16 v[44:47], v[124:127], v[168:171], v[44:47]
	v_mfma_f32_16x16x32_bf16 v[40:43], v[136:139], v[168:171], v[40:43]
	v_mfma_f32_16x16x32_bf16 v[28:31], v[124:127], v[196:199], v[28:31]
	v_mfma_f32_16x16x32_bf16 v[24:27], v[136:139], v[196:199], v[24:27]
	v_mfma_f32_16x16x32_bf16 v[12:15], v[124:127], v[204:207], v[12:15]
	v_mfma_f32_16x16x32_bf16 v[8:11], v[136:139], v[204:207], v[8:11]
	v_mfma_f32_16x16x32_bf16 v[60:63], v[132:135], v[164:167], v[60:63]
	v_mfma_f32_16x16x32_bf16 v[56:59], v[140:143], v[164:167], v[56:59]
	v_mfma_f32_16x16x32_bf16 v[44:47], v[132:135], v[172:175], v[44:47]
	v_mfma_f32_16x16x32_bf16 v[40:43], v[140:143], v[172:175], v[40:43]
	v_mfma_f32_16x16x32_bf16 v[28:31], v[132:135], v[200:203], v[28:31]
	v_mfma_f32_16x16x32_bf16 v[24:27], v[140:143], v[200:203], v[24:27]
	v_mfma_f32_16x16x32_bf16 v[12:15], v[132:135], v[208:211], v[12:15]
	v_mfma_f32_16x16x32_bf16 v[8:11], v[140:143], v[208:211], v[8:11]
	v_mfma_f32_16x16x32_bf16 v[52:55], v[144:147], v[160:163], v[52:55]
	v_mfma_f32_16x16x32_bf16 v[48:51], v[152:155], v[160:163], v[48:51]
	v_mfma_f32_16x16x32_bf16 v[36:39], v[144:147], v[168:171], v[36:39]
	v_mfma_f32_16x16x32_bf16 v[32:35], v[152:155], v[168:171], v[32:35]
	v_mfma_f32_16x16x32_bf16 v[20:23], v[144:147], v[196:199], v[20:23]
	v_mfma_f32_16x16x32_bf16 v[16:19], v[152:155], v[196:199], v[16:19]
	v_mfma_f32_16x16x32_bf16 v[4:7], v[144:147], v[204:207], v[4:7]
	v_mfma_f32_16x16x32_bf16 v[0:3], v[152:155], v[204:207], v[0:3]
	v_mfma_f32_16x16x32_bf16 v[52:55], v[148:151], v[164:167], v[52:55]
	v_mfma_f32_16x16x32_bf16 v[48:51], v[156:159], v[164:167], v[48:51]
	v_mfma_f32_16x16x32_bf16 v[36:39], v[148:151], v[172:175], v[36:39]
	v_mfma_f32_16x16x32_bf16 v[32:35], v[156:159], v[172:175], v[32:35]
	v_mfma_f32_16x16x32_bf16 v[20:23], v[148:151], v[200:203], v[20:23]
	v_mfma_f32_16x16x32_bf16 v[16:19], v[156:159], v[200:203], v[16:19]
	v_mfma_f32_16x16x32_bf16 v[4:7], v[148:151], v[208:211], v[4:7]
	v_mfma_f32_16x16x32_bf16 v[0:3], v[156:159], v[208:211], v[0:3]
	s_barrier
	s_add_u32 s22, s22, 0x100
	s_addc_u32 s23, s23, 0
	s_add_u32 s53, s53, 0x100
	s_addc_u32 s54, s54, 0
	s_cmp_ge_i32 s55, s40
	s_mov_b32 s26, s55
	s_cbranch_scc0 .LBB0_1253
